# all five GEMM phases: per-block s_setprio flips removed, one static s_setprio 1 for the trailing half-workgroup per phase, reset to 0 before every grid barrier
# baseline (speedup 1.0000x reference)
.LBB0_2:
	s_mov_b64 s[4:5], s[0:1]
	s_and_b64 vcc, exec, s[6:7]
	s_waitcnt lgkmcnt(0)
	s_barrier
	s_cbranch_vccz .LBB0_4
	s_setprio 0
	s_getreg_b32 s6, hwreg(HW_REG_XCC_ID, 0, 4)
	v_mbcnt_hi_u32_b32 v220, -1, v2
	s_cbranch_execz .LBB0_5
	s_branch .LBB0_9
.LBB0_4:
.LBB0_5:
	v_mbcnt_hi_u32_b32 v220, -1, v2
	v_mov_b32_e32 v2, v220
	s_setprio 0
	s_getreg_b32 s14, hwreg(HW_REG_XCC_ID, 0, 4)
	v_cmp_eq_u32_e32 vcc, 0, v2
	s_and_saveexec_b64 s[6:7], vcc
	s_cbranch_execz .LBB0_8
	s_mov_b64 s[12:13], exec
	v_mbcnt_lo_u32_b32 v2, s12, 0
	v_mbcnt_hi_u32_b32 v2, s13, v2
	v_cmp_eq_u32_e32 vcc, 0, v2
	s_and_b64 s[16:17], exec, vcc
	s_mov_b64 exec, s[16:17]
	s_cbranch_execz .LBB0_8
	s_load_dwordx2 s[4:5], s[4:5], 0x80
	s_lshl_b32 s14, s14, 8
	s_and_b32 s14, s14, 0xf00
	v_mov_b32_e32 v2, 0x4000
	s_waitcnt lgkmcnt(0)
	s_add_u32 s4, s4, s14
	s_addc_u32 s5, s5, 0
	s_bcnt1_i32_b64 s12, s[12:13]
	v_mov_b32_e32 v3, s12
	global_atomic_add v2, v3, s[4:5] offset:1024

.LBB0_94:
	s_mov_b64 s[4:5], s[0:1]
	s_load_dwordx2 s[6:7], s[4:5], 0x80
	v_readlane_b32 s4, v245, 0
	v_readlane_b32 s5, v245, 1
	s_andn2_b64 vcc, exec, s[4:5]
	s_setprio 0
	s_getreg_b32 s10, hwreg(HW_REG_XCC_ID, 0, 4)
	v_cndmask_b32_e64 v0, 0, 1, s[4:5]
	v_cmp_ne_u32_e64 s[76:77], 1, v0
	s_cbranch_vccnz .LBB0_96
	v_mov_b32_e32 v0, v220
	s_nop 0
	v_cmp_eq_u32_e32 vcc, 0, v0
	s_and_b64 s[12:13], vcc, exec

.LBB0_157:
	s_mov_b64 s[2:3], s[0:1]
	s_load_dwordx2 s[2:3], s[2:3], 0x80
	v_writelane_b32 v244, s4, 27
	s_mul_i32 s33, s46, 0x1800000
	s_waitcnt vmcnt(4)
	v_mov_b32_e32 v11, v220
	v_writelane_b32 v244, s5, 28
	s_mov_b64 s[4:5], s[0:1]
	s_load_dwordx2 s[4:5], s[4:5], 0x80
	s_waitcnt lgkmcnt(0)
	s_add_u32 s6, s2, s33
	s_addc_u32 s7, s3, 0
	s_add_u32 s12, s6, 0x200000
	s_addc_u32 s7, s7, 0
	s_add_u32 s56, s4, 0x7200000
	s_addc_u32 s57, s5, 0
	s_mov_b64 s[4:5], s[0:1]
	s_load_dwordx2 s[8:9], s[4:5], 0x80
	s_mov_b64 s[4:5], s[0:1]
	v_readlane_b32 s10, v245, 2
	s_load_dwordx2 s[4:5], s[4:5], 0x80
	s_lshl_b32 s58, s10, 10
	s_waitcnt vmcnt(3)
	v_lshlrev_b32_e32 v14, 4, v11
	v_add_u32_e32 v2, s58, v14
	v_ashrrev_i32_e32 v0, 31, v2
	v_lshrrev_b32_e32 v0, 22, v0
	v_add_u32_e32 v0, v2, v0
	v_ashrrev_i32_e32 v10, 10, v0
	v_mul_i32_i24_e32 v0, 0x400, v10
	v_sub_u32_e32 v0, v2, v0
	v_lshrrev_b32_e32 v3, 4, v0
	v_bitop3_b32 v0, v3, v0, 32 bitop3:0x6c
	v_ashrrev_i32_e32 v4, 31, v0
	v_lshrrev_b32_e32 v4, 26, v4
	v_add_u32_e32 v4, v0, v4
	v_lshlrev_b32_e32 v3, 3, v10
	v_ashrrev_i32_e32 v12, 6, v4
	v_and_b32_e32 v4, 0xc0, v4
	v_and_b32_e32 v3, -16, v3
	v_sub_u32_e32 v0, v0, v4
	v_add_u32_e32 v3, v12, v3
	v_ashrrev_i16_sdwa v0, v230, sext(v0) dst_sel:DWORD dst_unused:UNUSED_PAD src0_sel:DWORD src1_sel:BYTE_0
	v_lshlrev_b32_e32 v5, 5, v10
	v_bfe_i32 v13, v0, 0, 16
	v_lshlrev_b32_e32 v0, 1, v3
	v_lshrrev_b32_e32 v4, 2, v3
	v_and_b32_e32 v6, 3, v12
	s_mov_b32 s6, 0x1fffe0
	v_and_b32_e32 v5, 32, v5
	v_and_b32_e32 v0, 24, v0
	v_and_b32_e32 v4, 4, v4
	v_and_or_b32 v6, v3, s6, v6
	v_or3_b32 v0, v6, v4, v0
	v_add_lshl_u32 v4, v5, v13, 1
	v_add_u32_e32 v2, 0x2000, v2
	v_lshl_add_u32 v130, v3, 11, v4
	v_ashrrev_i32_e32 v3, 31, v2
	v_lshrrev_b32_e32 v3, 22, v3
	v_add_u32_e32 v3, v2, v3
	v_ashrrev_i32_e32 v15, 10, v3
	v_mul_i32_i24_e32 v3, 0x400, v15
	v_sub_u32_e32 v2, v2, v3
	v_lshrrev_b32_e32 v3, 4, v2
	v_bitop3_b32 v2, v3, v2, 32 bitop3:0x6c
	v_lshl_add_u32 v0, v0, 11, v4
	v_ashrrev_i32_e32 v4, 31, v2
	v_lshrrev_b32_e32 v4, 26, v4
	v_add_u32_e32 v4, v2, v4
	v_ashrrev_i32_e32 v16, 6, v4
	v_and_b32_e32 v4, 0xffc0, v4
	v_lshlrev_b32_e32 v3, 3, v15
	v_sub_u32_e32 v2, v2, v4
	v_and_b32_e32 v3, -16, v3
	v_lshrrev_b16_e32 v4, 7, v2
	v_add_u32_e32 v3, v16, v3
	v_and_b32_e32 v4, 1, v4
	v_and_b32_e32 v6, 3, v16
	s_ashr_i32 s11, s10, 2
	v_add_u16_e32 v2, v2, v4
	v_and_or_b32 v6, v3, s6, v6
	v_readlane_b32 s6, v245, 48
	v_ashrrev_i16_sdwa v2, v230, sext(v2) dst_sel:DWORD dst_unused:UNUSED_PAD src0_sel:DWORD src1_sel:BYTE_0
	s_add_u32 s84, s12, s6
	v_lshlrev_b32_e32 v5, 5, v15
	v_bfe_i32 v17, v2, 0, 16
	v_lshlrev_b32_e32 v2, 1, v3
	v_lshrrev_b32_e32 v4, 2, v3
	s_addc_u32 s85, s7, 0
	s_add_i32 s59, s58, 0
	v_and_b32_e32 v5, 32, v5
	v_and_b32_e32 v2, 24, v2
	v_and_b32_e32 v4, 4, v4
	s_add_i32 m0, s59, 0x10000
	v_or3_b32 v2, v6, v4, v2
	v_add_lshl_u32 v4, v5, v17, 1
	global_load_lds_dwordx4 v0, s[84:85]
	s_add_i32 m0, s59, 0x12000
	v_lshl_add_u32 v134, v2, 11, v4
	v_writelane_b32 v244, s12, 29
	s_add_u32 s6, s84, 0x40000
	v_writelane_b32 v244, s7, 30
	global_load_lds_dwordx4 v134, s[84:85]
	s_addc_u32 s7, s85, 0
	s_add_i32 m0, s59, 0x14000
	v_lshl_add_u32 v132, v3, 11, v4
	global_load_lds_dwordx4 v0, s[6:7]
	s_add_i32 m0, s59, 0x16000
	v_mov_b32_e32 v135, v1
	global_load_lds_dwordx4 v134, s[6:7]
	v_readlane_b32 s6, v245, 46
	s_add_u32 s6, s56, s6
	s_addc_u32 s7, s57, 0
	s_add_i32 s60, s59, 0x2000
	s_mov_b32 m0, s59
	s_add_u32 s12, s6, 0x40000
	global_load_lds_dwordx4 v130, s[6:7]
	s_mov_b32 m0, s60
	s_addc_u32 s13, s7, 0
	s_add_i32 s61, s59, 0x4000
	global_load_lds_dwordx4 v132, s[6:7]
	s_mov_b32 m0, s61
	s_add_i32 s68, s59, 0x6000
	global_load_lds_dwordx4 v130, s[12:13]
	s_mov_b32 m0, s68
	v_mov_b32_e32 v131, v1
	global_load_lds_dwordx4 v132, s[12:13]
	v_mov_b32_e32 v133, v1
	s_cmp_eq_u32 s11, 1
	v_lshl_add_u64 v[8:9], s[84:85], 0, v[0:1]
	v_lshl_add_u64 v[6:7], s[84:85], 0, v[134:135]
	v_lshl_add_u64 v[2:3], s[6:7], 0, v[130:131]
	s_cselect_b64 s[70:71], -1, 0
	s_cmp_lg_u32 s11, 1
	v_lshl_add_u64 v[4:5], s[6:7], 0, v[132:133]
	s_cbranch_scc1 .LBB0_159
	s_setprio 1
	s_barrier

.LBB0_164:
	s_ashr_i32 s77, s76, 31
	s_lshl_b64 s[10:11], s[76:77], 19
	s_add_u32 s80, s56, s10
	s_addc_u32 s81, s57, s11
	s_and_b64 s[10:11], s[12:13], exec
	s_cselect_b32 s46, s81, s7
	s_cselect_b32 s77, s80, s6
	s_ashr_i32 s79, s78, 31
	s_lshl_b64 s[10:11], s[78:79], 19
	v_readlane_b32 s55, v244, 29
	s_add_u32 s82, s55, s10
	v_readlane_b32 s10, v244, 30
	s_addc_u32 s83, s10, s11
	s_and_b64 s[10:11], s[12:13], exec
	s_cselect_b32 s12, s83, s85
	s_cselect_b32 s13, s82, s84
	s_add_u32 s6, s6, 0x40080
	s_addc_u32 s7, s7, 0
	s_add_u32 s79, s84, 0x100
	s_addc_u32 s96, s85, 0
	s_mov_b32 s97, -2
	s_add_u32 s10, s6, 0xfffc0080
	s_addc_u32 s11, s7, -1
	s_cmp_eq_u32 s97, 12
	s_cselect_b32 s87, s46, s11
	s_cselect_b32 s86, s77, s10
	s_cselect_b32 s85, s12, s96
	s_cselect_b32 s84, s13, s79
	s_add_i32 s10, 0, 0x14000
	v_add_u32_e32 v144, s10, v147
	ds_read_b128 v[140:143], v150
	ds_read_b128 v[152:155], v150 offset:1024
	ds_read_b128 v[156:159], v150 offset:2048
	ds_read_b128 v[160:163], v150 offset:3072
	ds_read_b128 v[164:167], v144
	ds_read_b128 v[168:171], v144 offset:1024
	ds_read_b128 v[172:175], v144 offset:2048
	ds_read_b128 v[176:179], v144 offset:3072
	v_lshl_add_u64 v[144:145], s[6:7], 0, v[136:137]
	s_add_i32 m0, s59, 0xc000
	ds_read_b128 v[180:183], v149
	ds_read_b128 v[184:187], v149 offset:1024
	ds_read_b128 v[192:195], v149 offset:2048
	ds_read_b128 v[196:199], v149 offset:3072
	ds_read_b128 v[200:203], v149 offset:4096
	ds_read_b128 v[204:207], v149 offset:5120
	ds_read_b128 v[208:211], v149 offset:6144
	ds_read_b128 v[212:215], v149 offset:7168
	global_load_lds_dwordx4 v[144:145], off
	v_lshl_add_u64 v[144:145], s[6:7], 0, v[138:139]
	s_add_i32 m0, s59, 0xe000
	s_nop 0
	global_load_lds_dwordx4 v[144:145], off
	s_waitcnt vmcnt(8)
	s_waitcnt lgkmcnt(0)
	s_barrier
	s_waitcnt lgkmcnt(0)
	v_mfma_f32_16x16x32_bf16 v[126:129], v[140:143], v[180:183], 0
	v_mfma_f32_16x16x32_bf16 v[122:125], v[156:159], v[180:183], 0
	v_mfma_f32_16x16x32_bf16 v[110:113], v[140:143], v[192:195], 0
	v_mfma_f32_16x16x32_bf16 v[106:109], v[156:159], v[192:195], 0
	v_mfma_f32_16x16x32_bf16 v[94:97], v[140:143], v[200:203], 0
	v_mfma_f32_16x16x32_bf16 v[90:93], v[156:159], v[200:203], 0
	v_mfma_f32_16x16x32_bf16 v[78:81], v[140:143], v[208:211], 0
	v_mfma_f32_16x16x32_bf16 v[74:77], v[156:159], v[208:211], 0
	v_mfma_f32_16x16x32_bf16 v[126:129], v[152:155], v[184:187], v[126:129]
	v_mfma_f32_16x16x32_bf16 v[122:125], v[160:163], v[184:187], v[122:125]
	v_mfma_f32_16x16x32_bf16 v[110:113], v[152:155], v[196:199], v[110:113]
	v_mfma_f32_16x16x32_bf16 v[106:109], v[160:163], v[196:199], v[106:109]
	v_mfma_f32_16x16x32_bf16 v[94:97], v[152:155], v[204:207], v[94:97]
	v_mfma_f32_16x16x32_bf16 v[90:93], v[160:163], v[204:207], v[90:93]
	v_mfma_f32_16x16x32_bf16 v[78:81], v[152:155], v[212:215], v[78:81]
	v_mfma_f32_16x16x32_bf16 v[74:77], v[160:163], v[212:215], v[74:77]
	v_mfma_f32_16x16x32_bf16 v[118:121], v[164:167], v[180:183], 0
	v_mfma_f32_16x16x32_bf16 v[114:117], v[172:175], v[180:183], 0
	v_mfma_f32_16x16x32_bf16 v[102:105], v[164:167], v[192:195], 0
	v_mfma_f32_16x16x32_bf16 v[98:101], v[172:175], v[192:195], 0
	v_mfma_f32_16x16x32_bf16 v[86:89], v[164:167], v[200:203], 0
	v_mfma_f32_16x16x32_bf16 v[82:85], v[172:175], v[200:203], 0
	v_mfma_f32_16x16x32_bf16 v[70:73], v[164:167], v[208:211], 0
	v_mfma_f32_16x16x32_bf16 v[66:69], v[172:175], v[208:211], 0
	v_mfma_f32_16x16x32_bf16 v[118:121], v[168:171], v[184:187], v[118:121]
	v_mfma_f32_16x16x32_bf16 v[114:117], v[176:179], v[184:187], v[114:117]
	v_mfma_f32_16x16x32_bf16 v[102:105], v[168:171], v[196:199], v[102:105]
	v_mfma_f32_16x16x32_bf16 v[98:101], v[176:179], v[196:199], v[98:101]
	v_mfma_f32_16x16x32_bf16 v[86:89], v[168:171], v[204:207], v[86:89]
	v_mfma_f32_16x16x32_bf16 v[82:85], v[176:179], v[204:207], v[82:85]
	v_mfma_f32_16x16x32_bf16 v[70:73], v[168:171], v[212:215], v[70:73]
	v_mfma_f32_16x16x32_bf16 v[66:69], v[176:179], v[212:215], v[66:69]
	s_barrier
	s_add_i32 s11, s63, s58
	v_lshl_add_u64 v[144:145], s[84:85], 0, v[0:1]
	s_mov_b32 m0, s11
	ds_read_b128 v[180:183], v149 offset:16384
	ds_read_b128 v[184:187], v149 offset:17408
	ds_read_b128 v[192:195], v149 offset:18432
	ds_read_b128 v[196:199], v149 offset:19456
	ds_read_b128 v[200:203], v149 offset:20480
	ds_read_b128 v[204:207], v149 offset:21504
	ds_read_b128 v[208:211], v149 offset:22528
	ds_read_b128 v[212:215], v149 offset:23552
	global_load_lds_dwordx4 v[144:145], off
	s_add_i32 m0, s11, 0x2000
	s_add_u32 vcc_lo, s84, 0x40000
	v_lshl_add_u64 v[188:189], s[84:85], 0, v[134:135]
	s_addc_u32 vcc_hi, s85, 0
	s_add_i32 s11, s10, s58
	global_load_lds_dwordx4 v[188:189], off
	v_lshl_add_u64 v[216:217], vcc, 0, v[0:1]
	s_mov_b32 m0, s11
	v_lshl_add_u64 v[218:219], s[86:87], 0, v[132:133]
	global_load_lds_dwordx4 v[216:217], off
	v_lshl_add_u64 v[216:217], vcc, 0, v[134:135]
	s_add_i32 m0, s11, 0x2000
	s_nop 0
	global_load_lds_dwordx4 v[216:217], off
	v_lshl_add_u64 v[216:217], s[86:87], 0, v[130:131]
	s_mov_b32 m0, s59
	s_nop 0
	global_load_lds_dwordx4 v[216:217], off
	s_mov_b32 m0, s60
	s_nop 0
	global_load_lds_dwordx4 v[218:219], off
	s_waitcnt vmcnt(8)
	s_waitcnt lgkmcnt(0)
	s_barrier
	s_waitcnt lgkmcnt(0)
	v_mfma_f32_16x16x32_bf16 v[62:65], v[140:143], v[180:183], 0
	v_mfma_f32_16x16x32_bf16 v[58:61], v[156:159], v[180:183], 0
	v_mfma_f32_16x16x32_bf16 v[46:49], v[140:143], v[192:195], 0
	v_mfma_f32_16x16x32_bf16 v[42:45], v[156:159], v[192:195], 0
	v_mfma_f32_16x16x32_bf16 v[30:33], v[140:143], v[200:203], 0
	v_mfma_f32_16x16x32_bf16 v[26:29], v[156:159], v[200:203], 0
	v_mfma_f32_16x16x32_bf16 v[14:17], v[140:143], v[208:211], 0
	v_mfma_f32_16x16x32_bf16 v[10:13], v[156:159], v[208:211], 0
	v_mfma_f32_16x16x32_bf16 v[62:65], v[152:155], v[184:187], v[62:65]
	v_mfma_f32_16x16x32_bf16 v[58:61], v[160:163], v[184:187], v[58:61]
	v_mfma_f32_16x16x32_bf16 v[46:49], v[152:155], v[196:199], v[46:49]
	v_mfma_f32_16x16x32_bf16 v[42:45], v[160:163], v[196:199], v[42:45]
	v_mfma_f32_16x16x32_bf16 v[30:33], v[152:155], v[204:207], v[30:33]
	v_mfma_f32_16x16x32_bf16 v[26:29], v[160:163], v[204:207], v[26:29]
	v_mfma_f32_16x16x32_bf16 v[14:17], v[152:155], v[212:215], v[14:17]
	v_mfma_f32_16x16x32_bf16 v[10:13], v[160:163], v[212:215], v[10:13]
	v_mfma_f32_16x16x32_bf16 v[54:57], v[164:167], v[180:183], 0
	v_mfma_f32_16x16x32_bf16 v[50:53], v[172:175], v[180:183], 0
	v_mfma_f32_16x16x32_bf16 v[38:41], v[164:167], v[192:195], 0
	v_mfma_f32_16x16x32_bf16 v[34:37], v[172:175], v[192:195], 0
	v_mfma_f32_16x16x32_bf16 v[22:25], v[164:167], v[200:203], 0
	v_mfma_f32_16x16x32_bf16 v[18:21], v[172:175], v[200:203], 0
	v_mfma_f32_16x16x32_bf16 v[6:9], v[164:167], v[208:211], 0
	v_mfma_f32_16x16x32_bf16 v[2:5], v[172:175], v[208:211], 0
	v_mfma_f32_16x16x32_bf16 v[54:57], v[168:171], v[184:187], v[54:57]
	v_mfma_f32_16x16x32_bf16 v[50:53], v[176:179], v[184:187], v[50:53]
	v_mfma_f32_16x16x32_bf16 v[38:41], v[168:171], v[196:199], v[38:41]
	v_mfma_f32_16x16x32_bf16 v[34:37], v[176:179], v[196:199], v[34:37]
	v_mfma_f32_16x16x32_bf16 v[22:25], v[168:171], v[204:207], v[22:25]
	v_mfma_f32_16x16x32_bf16 v[18:21], v[176:179], v[204:207], v[18:21]
	v_mfma_f32_16x16x32_bf16 v[6:9], v[168:171], v[212:215], v[6:9]
	v_mfma_f32_16x16x32_bf16 v[2:5], v[176:179], v[212:215], v[2:5]
	s_barrier
	s_add_i32 s11, 0, 0x18000
	v_add_u32_e32 v151, s11, v147
	s_add_i32 s67, 0, 0x1c000
	ds_read_b128 v[140:143], v151
	ds_read_b128 v[152:155], v151 offset:1024
	ds_read_b128 v[156:159], v151 offset:2048
	ds_read_b128 v[160:163], v151 offset:3072
	v_add_u32_e32 v151, s67, v147
	ds_read_b128 v[164:167], v151
	ds_read_b128 v[168:171], v151 offset:1024
	ds_read_b128 v[172:175], v151 offset:2048
	ds_read_b128 v[176:179], v151 offset:3072
	s_add_u32 s86, s86, 0x40000
	s_addc_u32 s87, s87, 0
	s_mov_b32 m0, s61
	v_lshl_add_u64 v[240:241], s[86:87], 0, v[130:131]
	ds_read_b128 v[180:183], v149 offset:32768
	ds_read_b128 v[184:187], v149 offset:33792
	ds_read_b128 v[192:195], v149 offset:34816
	ds_read_b128 v[196:199], v149 offset:35840
	ds_read_b128 v[200:203], v149 offset:36864
	ds_read_b128 v[204:207], v149 offset:37888
	ds_read_b128 v[208:211], v149 offset:38912
	ds_read_b128 v[212:215], v149 offset:39936
	global_load_lds_dwordx4 v[240:241], off
	v_lshl_add_u64 v[240:241], s[86:87], 0, v[132:133]
	s_mov_b32 m0, s68
	s_nop 0
	global_load_lds_dwordx4 v[240:241], off
	s_waitcnt vmcnt(8)
	s_waitcnt lgkmcnt(0)
	s_barrier
	s_waitcnt lgkmcnt(0)
	v_mfma_f32_16x16x32_bf16 v[126:129], v[140:143], v[180:183], v[126:129]
	v_mfma_f32_16x16x32_bf16 v[122:125], v[156:159], v[180:183], v[122:125]
	v_mfma_f32_16x16x32_bf16 v[110:113], v[140:143], v[192:195], v[110:113]
	v_mfma_f32_16x16x32_bf16 v[106:109], v[156:159], v[192:195], v[106:109]
	v_mfma_f32_16x16x32_bf16 v[94:97], v[140:143], v[200:203], v[94:97]
	v_mfma_f32_16x16x32_bf16 v[90:93], v[156:159], v[200:203], v[90:93]
	v_mfma_f32_16x16x32_bf16 v[78:81], v[140:143], v[208:211], v[78:81]
	v_mfma_f32_16x16x32_bf16 v[74:77], v[156:159], v[208:211], v[74:77]
	v_mfma_f32_16x16x32_bf16 v[126:129], v[152:155], v[184:187], v[126:129]
	v_mfma_f32_16x16x32_bf16 v[122:125], v[160:163], v[184:187], v[122:125]
	v_mfma_f32_16x16x32_bf16 v[110:113], v[152:155], v[196:199], v[110:113]
	v_mfma_f32_16x16x32_bf16 v[106:109], v[160:163], v[196:199], v[106:109]
	v_mfma_f32_16x16x32_bf16 v[94:97], v[152:155], v[204:207], v[94:97]
	v_mfma_f32_16x16x32_bf16 v[90:93], v[160:163], v[204:207], v[90:93]
	v_mfma_f32_16x16x32_bf16 v[78:81], v[152:155], v[212:215], v[78:81]
	v_mfma_f32_16x16x32_bf16 v[74:77], v[160:163], v[212:215], v[74:77]
	v_mfma_f32_16x16x32_bf16 v[118:121], v[164:167], v[180:183], v[118:121]
	v_mfma_f32_16x16x32_bf16 v[114:117], v[172:175], v[180:183], v[114:117]
	v_mfma_f32_16x16x32_bf16 v[102:105], v[164:167], v[192:195], v[102:105]
	v_mfma_f32_16x16x32_bf16 v[98:101], v[172:175], v[192:195], v[98:101]
	v_mfma_f32_16x16x32_bf16 v[86:89], v[164:167], v[200:203], v[86:89]
	v_mfma_f32_16x16x32_bf16 v[82:85], v[172:175], v[200:203], v[82:85]
	v_mfma_f32_16x16x32_bf16 v[70:73], v[164:167], v[208:211], v[70:73]
	v_mfma_f32_16x16x32_bf16 v[66:69], v[172:175], v[208:211], v[66:69]
	v_mfma_f32_16x16x32_bf16 v[118:121], v[168:171], v[184:187], v[118:121]
	v_mfma_f32_16x16x32_bf16 v[114:117], v[176:179], v[184:187], v[114:117]
	v_mfma_f32_16x16x32_bf16 v[102:105], v[168:171], v[196:199], v[102:105]
	v_mfma_f32_16x16x32_bf16 v[98:101], v[176:179], v[196:199], v[98:101]
	v_mfma_f32_16x16x32_bf16 v[86:89], v[168:171], v[204:207], v[86:89]
	v_mfma_f32_16x16x32_bf16 v[82:85], v[176:179], v[204:207], v[82:85]
	v_mfma_f32_16x16x32_bf16 v[70:73], v[168:171], v[212:215], v[70:73]
	v_mfma_f32_16x16x32_bf16 v[66:69], v[176:179], v[212:215], v[66:69]
	s_barrier
	s_add_i32 s55, s11, s58
	v_lshl_add_u64 v[144:145], v[144:145], 0, s[50:51]
	s_mov_b32 m0, s55
	ds_read_b128 v[180:183], v149 offset:49152
	ds_read_b128 v[184:187], v149 offset:50176
	ds_read_b128 v[192:195], v149 offset:51200
	ds_read_b128 v[196:199], v149 offset:52224
	ds_read_b128 v[200:203], v149 offset:53248
	ds_read_b128 v[204:207], v149 offset:54272
	ds_read_b128 v[208:211], v149 offset:55296
	ds_read_b128 v[212:215], v149 offset:56320
	global_load_lds_dwordx4 v[144:145], off
	s_add_i32 m0, s55, 0x2000
	s_add_u32 s84, s84, 0x40080
	v_lshl_add_u64 v[144:145], v[188:189], 0, s[50:51]
	s_addc_u32 s85, s85, 0
	s_add_i32 s55, s67, s58
	global_load_lds_dwordx4 v[144:145], off
	v_lshl_add_u64 v[144:145], s[84:85], 0, v[0:1]
	s_mov_b32 m0, s55
	s_nop 0
	global_load_lds_dwordx4 v[144:145], off
	v_lshl_add_u64 v[144:145], s[84:85], 0, v[134:135]
	s_add_i32 m0, s55, 0x2000
	s_nop 0
	global_load_lds_dwordx4 v[144:145], off
	v_lshl_add_u64 v[144:145], v[216:217], 0, s[50:51]
	s_mov_b32 m0, s89
	s_nop 0
	global_load_lds_dwordx4 v[144:145], off
	v_lshl_add_u64 v[144:145], v[218:219], 0, s[50:51]
	s_mov_b32 m0, s90
	s_nop 0
	global_load_lds_dwordx4 v[144:145], off
	s_waitcnt vmcnt(8)
	s_waitcnt lgkmcnt(0)
	s_barrier
	s_waitcnt lgkmcnt(0)
	v_mfma_f32_16x16x32_bf16 v[62:65], v[140:143], v[180:183], v[62:65]
	v_mfma_f32_16x16x32_bf16 v[58:61], v[156:159], v[180:183], v[58:61]
	v_mfma_f32_16x16x32_bf16 v[46:49], v[140:143], v[192:195], v[46:49]
	v_mfma_f32_16x16x32_bf16 v[42:45], v[156:159], v[192:195], v[42:45]
	v_mfma_f32_16x16x32_bf16 v[30:33], v[140:143], v[200:203], v[30:33]
	v_mfma_f32_16x16x32_bf16 v[26:29], v[156:159], v[200:203], v[26:29]
	v_mfma_f32_16x16x32_bf16 v[14:17], v[140:143], v[208:211], v[14:17]
	v_mfma_f32_16x16x32_bf16 v[10:13], v[156:159], v[208:211], v[10:13]
	v_mfma_f32_16x16x32_bf16 v[62:65], v[152:155], v[184:187], v[62:65]
	v_mfma_f32_16x16x32_bf16 v[58:61], v[160:163], v[184:187], v[58:61]
	v_mfma_f32_16x16x32_bf16 v[46:49], v[152:155], v[196:199], v[46:49]
	v_mfma_f32_16x16x32_bf16 v[42:45], v[160:163], v[196:199], v[42:45]
	v_mfma_f32_16x16x32_bf16 v[30:33], v[152:155], v[204:207], v[30:33]
	v_mfma_f32_16x16x32_bf16 v[26:29], v[160:163], v[204:207], v[26:29]
	v_mfma_f32_16x16x32_bf16 v[14:17], v[152:155], v[212:215], v[14:17]
	v_mfma_f32_16x16x32_bf16 v[10:13], v[160:163], v[212:215], v[10:13]
	v_mfma_f32_16x16x32_bf16 v[54:57], v[164:167], v[180:183], v[54:57]
	v_mfma_f32_16x16x32_bf16 v[50:53], v[172:175], v[180:183], v[50:53]
	v_mfma_f32_16x16x32_bf16 v[38:41], v[164:167], v[192:195], v[38:41]
	v_mfma_f32_16x16x32_bf16 v[34:37], v[172:175], v[192:195], v[34:37]
	v_mfma_f32_16x16x32_bf16 v[22:25], v[164:167], v[200:203], v[22:25]
	v_mfma_f32_16x16x32_bf16 v[18:21], v[172:175], v[200:203], v[18:21]
	v_mfma_f32_16x16x32_bf16 v[6:9], v[164:167], v[208:211], v[6:9]
	v_mfma_f32_16x16x32_bf16 v[2:5], v[172:175], v[208:211], v[2:5]
	v_mfma_f32_16x16x32_bf16 v[54:57], v[168:171], v[184:187], v[54:57]
	v_mfma_f32_16x16x32_bf16 v[50:53], v[176:179], v[184:187], v[50:53]
	v_mfma_f32_16x16x32_bf16 v[38:41], v[168:171], v[196:199], v[38:41]
	v_mfma_f32_16x16x32_bf16 v[34:37], v[176:179], v[196:199], v[34:37]
	v_mfma_f32_16x16x32_bf16 v[22:25], v[168:171], v[204:207], v[22:25]
	v_mfma_f32_16x16x32_bf16 v[18:21], v[176:179], v[204:207], v[18:21]
	v_mfma_f32_16x16x32_bf16 v[6:9], v[168:171], v[212:215], v[6:9]
	v_mfma_f32_16x16x32_bf16 v[2:5], v[176:179], v[212:215], v[2:5]
	s_barrier
	s_add_i32 s97, s97, 2
	s_add_u32 s6, s6, 0x100
	s_addc_u32 s7, s7, 0
	s_add_u32 s79, s79, 0x100
	s_addc_u32 s96, s96, 0
.LBB0_165:
	s_add_u32 s10, s6, 0xfffc0080
	s_addc_u32 s11, s7, -1
	s_cmp_eq_u32 s97, 12
	s_cselect_b32 s87, s46, s11
	s_cselect_b32 s86, s77, s10
	s_cselect_b32 s85, s12, s96
	s_cselect_b32 s84, s13, s79
	s_add_i32 s10, 0, 0x14000
	v_add_u32_e32 v144, s10, v147
	ds_read_b128 v[140:143], v150
	ds_read_b128 v[152:155], v150 offset:1024
	ds_read_b128 v[156:159], v150 offset:2048
	ds_read_b128 v[160:163], v150 offset:3072
	ds_read_b128 v[164:167], v144
	ds_read_b128 v[168:171], v144 offset:1024
	ds_read_b128 v[172:175], v144 offset:2048
	ds_read_b128 v[176:179], v144 offset:3072
	v_lshl_add_u64 v[144:145], s[6:7], 0, v[136:137]
	s_add_i32 m0, s59, 0xc000
	ds_read_b128 v[180:183], v149
	ds_read_b128 v[184:187], v149 offset:1024
	ds_read_b128 v[192:195], v149 offset:2048
	ds_read_b128 v[196:199], v149 offset:3072
	ds_read_b128 v[200:203], v149 offset:4096
	ds_read_b128 v[204:207], v149 offset:5120
	ds_read_b128 v[208:211], v149 offset:6144
	ds_read_b128 v[212:215], v149 offset:7168
	global_load_lds_dwordx4 v[144:145], off
	v_lshl_add_u64 v[144:145], s[6:7], 0, v[138:139]
	s_add_i32 m0, s59, 0xe000
	s_nop 0
	global_load_lds_dwordx4 v[144:145], off
	s_waitcnt vmcnt(8)
	s_waitcnt lgkmcnt(0)
	s_barrier
	s_waitcnt lgkmcnt(0)
	v_mfma_f32_16x16x32_bf16 v[126:129], v[140:143], v[180:183], v[126:129]
	v_mfma_f32_16x16x32_bf16 v[122:125], v[156:159], v[180:183], v[122:125]
	v_mfma_f32_16x16x32_bf16 v[110:113], v[140:143], v[192:195], v[110:113]
	v_mfma_f32_16x16x32_bf16 v[106:109], v[156:159], v[192:195], v[106:109]
	v_mfma_f32_16x16x32_bf16 v[94:97], v[140:143], v[200:203], v[94:97]
	v_mfma_f32_16x16x32_bf16 v[90:93], v[156:159], v[200:203], v[90:93]
	v_mfma_f32_16x16x32_bf16 v[78:81], v[140:143], v[208:211], v[78:81]
	v_mfma_f32_16x16x32_bf16 v[74:77], v[156:159], v[208:211], v[74:77]
	v_mfma_f32_16x16x32_bf16 v[126:129], v[152:155], v[184:187], v[126:129]
	v_mfma_f32_16x16x32_bf16 v[122:125], v[160:163], v[184:187], v[122:125]
	v_mfma_f32_16x16x32_bf16 v[110:113], v[152:155], v[196:199], v[110:113]
	v_mfma_f32_16x16x32_bf16 v[106:109], v[160:163], v[196:199], v[106:109]
	v_mfma_f32_16x16x32_bf16 v[94:97], v[152:155], v[204:207], v[94:97]
	v_mfma_f32_16x16x32_bf16 v[90:93], v[160:163], v[204:207], v[90:93]
	v_mfma_f32_16x16x32_bf16 v[78:81], v[152:155], v[212:215], v[78:81]
	v_mfma_f32_16x16x32_bf16 v[74:77], v[160:163], v[212:215], v[74:77]
	v_mfma_f32_16x16x32_bf16 v[118:121], v[164:167], v[180:183], v[118:121]
	v_mfma_f32_16x16x32_bf16 v[114:117], v[172:175], v[180:183], v[114:117]
	v_mfma_f32_16x16x32_bf16 v[102:105], v[164:167], v[192:195], v[102:105]
	v_mfma_f32_16x16x32_bf16 v[98:101], v[172:175], v[192:195], v[98:101]
	v_mfma_f32_16x16x32_bf16 v[86:89], v[164:167], v[200:203], v[86:89]
	v_mfma_f32_16x16x32_bf16 v[82:85], v[172:175], v[200:203], v[82:85]
	v_mfma_f32_16x16x32_bf16 v[70:73], v[164:167], v[208:211], v[70:73]
	v_mfma_f32_16x16x32_bf16 v[66:69], v[172:175], v[208:211], v[66:69]
	v_mfma_f32_16x16x32_bf16 v[118:121], v[168:171], v[184:187], v[118:121]
	v_mfma_f32_16x16x32_bf16 v[114:117], v[176:179], v[184:187], v[114:117]
	v_mfma_f32_16x16x32_bf16 v[102:105], v[168:171], v[196:199], v[102:105]
	v_mfma_f32_16x16x32_bf16 v[98:101], v[176:179], v[196:199], v[98:101]
	v_mfma_f32_16x16x32_bf16 v[86:89], v[168:171], v[204:207], v[86:89]
	v_mfma_f32_16x16x32_bf16 v[82:85], v[176:179], v[204:207], v[82:85]
	v_mfma_f32_16x16x32_bf16 v[70:73], v[168:171], v[212:215], v[70:73]
	v_mfma_f32_16x16x32_bf16 v[66:69], v[176:179], v[212:215], v[66:69]
	s_barrier
	s_add_i32 s11, s63, s58
	v_lshl_add_u64 v[144:145], s[84:85], 0, v[0:1]
	s_mov_b32 m0, s11
	ds_read_b128 v[180:183], v149 offset:16384
	ds_read_b128 v[184:187], v149 offset:17408
	ds_read_b128 v[192:195], v149 offset:18432
	ds_read_b128 v[196:199], v149 offset:19456
	ds_read_b128 v[200:203], v149 offset:20480
	ds_read_b128 v[204:207], v149 offset:21504
	ds_read_b128 v[208:211], v149 offset:22528
	ds_read_b128 v[212:215], v149 offset:23552
	global_load_lds_dwordx4 v[144:145], off
	s_add_i32 m0, s11, 0x2000
	s_add_u32 vcc_lo, s84, 0x40000
	v_lshl_add_u64 v[188:189], s[84:85], 0, v[134:135]
	s_addc_u32 vcc_hi, s85, 0
	s_add_i32 s11, s10, s58
	global_load_lds_dwordx4 v[188:189], off
	v_lshl_add_u64 v[216:217], vcc, 0, v[0:1]
	s_mov_b32 m0, s11
	v_lshl_add_u64 v[218:219], s[86:87], 0, v[132:133]
	global_load_lds_dwordx4 v[216:217], off
	v_lshl_add_u64 v[216:217], vcc, 0, v[134:135]
	s_add_i32 m0, s11, 0x2000
	s_nop 0
	global_load_lds_dwordx4 v[216:217], off
	v_lshl_add_u64 v[216:217], s[86:87], 0, v[130:131]
	s_mov_b32 m0, s59
	s_nop 0
	global_load_lds_dwordx4 v[216:217], off
	s_mov_b32 m0, s60
	s_nop 0
	global_load_lds_dwordx4 v[218:219], off
	s_waitcnt vmcnt(8)
	s_waitcnt lgkmcnt(0)
	s_barrier
	s_waitcnt lgkmcnt(0)
	v_mfma_f32_16x16x32_bf16 v[62:65], v[140:143], v[180:183], v[62:65]
	v_mfma_f32_16x16x32_bf16 v[58:61], v[156:159], v[180:183], v[58:61]
	v_mfma_f32_16x16x32_bf16 v[46:49], v[140:143], v[192:195], v[46:49]
	v_mfma_f32_16x16x32_bf16 v[42:45], v[156:159], v[192:195], v[42:45]
	v_mfma_f32_16x16x32_bf16 v[30:33], v[140:143], v[200:203], v[30:33]
	v_mfma_f32_16x16x32_bf16 v[26:29], v[156:159], v[200:203], v[26:29]
	v_mfma_f32_16x16x32_bf16 v[14:17], v[140:143], v[208:211], v[14:17]
	v_mfma_f32_16x16x32_bf16 v[10:13], v[156:159], v[208:211], v[10:13]
	v_mfma_f32_16x16x32_bf16 v[62:65], v[152:155], v[184:187], v[62:65]
	v_mfma_f32_16x16x32_bf16 v[58:61], v[160:163], v[184:187], v[58:61]
	v_mfma_f32_16x16x32_bf16 v[46:49], v[152:155], v[196:199], v[46:49]
	v_mfma_f32_16x16x32_bf16 v[42:45], v[160:163], v[196:199], v[42:45]
	v_mfma_f32_16x16x32_bf16 v[30:33], v[152:155], v[204:207], v[30:33]
	v_mfma_f32_16x16x32_bf16 v[26:29], v[160:163], v[204:207], v[26:29]
	v_mfma_f32_16x16x32_bf16 v[14:17], v[152:155], v[212:215], v[14:17]
	v_mfma_f32_16x16x32_bf16 v[10:13], v[160:163], v[212:215], v[10:13]
	v_mfma_f32_16x16x32_bf16 v[54:57], v[164:167], v[180:183], v[54:57]
	v_mfma_f32_16x16x32_bf16 v[50:53], v[172:175], v[180:183], v[50:53]
	v_mfma_f32_16x16x32_bf16 v[38:41], v[164:167], v[192:195], v[38:41]
	v_mfma_f32_16x16x32_bf16 v[34:37], v[172:175], v[192:195], v[34:37]
	v_mfma_f32_16x16x32_bf16 v[22:25], v[164:167], v[200:203], v[22:25]
	v_mfma_f32_16x16x32_bf16 v[18:21], v[172:175], v[200:203], v[18:21]
	v_mfma_f32_16x16x32_bf16 v[6:9], v[164:167], v[208:211], v[6:9]
	v_mfma_f32_16x16x32_bf16 v[2:5], v[172:175], v[208:211], v[2:5]
	v_mfma_f32_16x16x32_bf16 v[54:57], v[168:171], v[184:187], v[54:57]
	v_mfma_f32_16x16x32_bf16 v[50:53], v[176:179], v[184:187], v[50:53]
	v_mfma_f32_16x16x32_bf16 v[38:41], v[168:171], v[196:199], v[38:41]
	v_mfma_f32_16x16x32_bf16 v[34:37], v[176:179], v[196:199], v[34:37]
	v_mfma_f32_16x16x32_bf16 v[22:25], v[168:171], v[204:207], v[22:25]
	v_mfma_f32_16x16x32_bf16 v[18:21], v[176:179], v[204:207], v[18:21]
	v_mfma_f32_16x16x32_bf16 v[6:9], v[168:171], v[212:215], v[6:9]
	v_mfma_f32_16x16x32_bf16 v[2:5], v[176:179], v[212:215], v[2:5]
	s_barrier
	s_add_i32 s11, 0, 0x18000
	v_add_u32_e32 v151, s11, v147
	s_add_i32 s67, 0, 0x1c000
	ds_read_b128 v[140:143], v151
	ds_read_b128 v[152:155], v151 offset:1024
	ds_read_b128 v[156:159], v151 offset:2048
	ds_read_b128 v[160:163], v151 offset:3072
	v_add_u32_e32 v151, s67, v147
	ds_read_b128 v[164:167], v151
	ds_read_b128 v[168:171], v151 offset:1024
	ds_read_b128 v[172:175], v151 offset:2048
	ds_read_b128 v[176:179], v151 offset:3072
	s_add_u32 s86, s86, 0x40000
	s_addc_u32 s87, s87, 0
	s_mov_b32 m0, s61
	v_lshl_add_u64 v[240:241], s[86:87], 0, v[130:131]
	ds_read_b128 v[180:183], v149 offset:32768
	ds_read_b128 v[184:187], v149 offset:33792
	ds_read_b128 v[192:195], v149 offset:34816
	ds_read_b128 v[196:199], v149 offset:35840
	ds_read_b128 v[200:203], v149 offset:36864
	ds_read_b128 v[204:207], v149 offset:37888
	ds_read_b128 v[208:211], v149 offset:38912
	ds_read_b128 v[212:215], v149 offset:39936
	global_load_lds_dwordx4 v[240:241], off
	v_lshl_add_u64 v[240:241], s[86:87], 0, v[132:133]
	s_mov_b32 m0, s68
	s_nop 0
	global_load_lds_dwordx4 v[240:241], off
	s_waitcnt vmcnt(8)
	s_waitcnt lgkmcnt(0)
	s_barrier
	s_waitcnt lgkmcnt(0)
	v_mfma_f32_16x16x32_bf16 v[126:129], v[140:143], v[180:183], v[126:129]
	v_mfma_f32_16x16x32_bf16 v[122:125], v[156:159], v[180:183], v[122:125]
	v_mfma_f32_16x16x32_bf16 v[110:113], v[140:143], v[192:195], v[110:113]
	v_mfma_f32_16x16x32_bf16 v[106:109], v[156:159], v[192:195], v[106:109]
	v_mfma_f32_16x16x32_bf16 v[94:97], v[140:143], v[200:203], v[94:97]
	v_mfma_f32_16x16x32_bf16 v[90:93], v[156:159], v[200:203], v[90:93]
	v_mfma_f32_16x16x32_bf16 v[78:81], v[140:143], v[208:211], v[78:81]
	v_mfma_f32_16x16x32_bf16 v[74:77], v[156:159], v[208:211], v[74:77]
	v_mfma_f32_16x16x32_bf16 v[126:129], v[152:155], v[184:187], v[126:129]
	v_mfma_f32_16x16x32_bf16 v[122:125], v[160:163], v[184:187], v[122:125]
	v_mfma_f32_16x16x32_bf16 v[110:113], v[152:155], v[196:199], v[110:113]
	v_mfma_f32_16x16x32_bf16 v[106:109], v[160:163], v[196:199], v[106:109]
	v_mfma_f32_16x16x32_bf16 v[94:97], v[152:155], v[204:207], v[94:97]
	v_mfma_f32_16x16x32_bf16 v[90:93], v[160:163], v[204:207], v[90:93]
	v_mfma_f32_16x16x32_bf16 v[78:81], v[152:155], v[212:215], v[78:81]
	v_mfma_f32_16x16x32_bf16 v[74:77], v[160:163], v[212:215], v[74:77]
	v_mfma_f32_16x16x32_bf16 v[118:121], v[164:167], v[180:183], v[118:121]
	v_mfma_f32_16x16x32_bf16 v[114:117], v[172:175], v[180:183], v[114:117]
	v_mfma_f32_16x16x32_bf16 v[102:105], v[164:167], v[192:195], v[102:105]
	v_mfma_f32_16x16x32_bf16 v[98:101], v[172:175], v[192:195], v[98:101]
	v_mfma_f32_16x16x32_bf16 v[86:89], v[164:167], v[200:203], v[86:89]
	v_mfma_f32_16x16x32_bf16 v[82:85], v[172:175], v[200:203], v[82:85]
	v_mfma_f32_16x16x32_bf16 v[70:73], v[164:167], v[208:211], v[70:73]
	v_mfma_f32_16x16x32_bf16 v[66:69], v[172:175], v[208:211], v[66:69]
	v_mfma_f32_16x16x32_bf16 v[118:121], v[168:171], v[184:187], v[118:121]
	v_mfma_f32_16x16x32_bf16 v[114:117], v[176:179], v[184:187], v[114:117]
	v_mfma_f32_16x16x32_bf16 v[102:105], v[168:171], v[196:199], v[102:105]
	v_mfma_f32_16x16x32_bf16 v[98:101], v[176:179], v[196:199], v[98:101]
	v_mfma_f32_16x16x32_bf16 v[86:89], v[168:171], v[204:207], v[86:89]
	v_mfma_f32_16x16x32_bf16 v[82:85], v[176:179], v[204:207], v[82:85]
	v_mfma_f32_16x16x32_bf16 v[70:73], v[168:171], v[212:215], v[70:73]
	v_mfma_f32_16x16x32_bf16 v[66:69], v[176:179], v[212:215], v[66:69]
	s_barrier
	s_add_i32 s55, s11, s58
	v_lshl_add_u64 v[144:145], v[144:145], 0, s[50:51]
	s_mov_b32 m0, s55
	ds_read_b128 v[180:183], v149 offset:49152
	ds_read_b128 v[184:187], v149 offset:50176
	ds_read_b128 v[192:195], v149 offset:51200
	ds_read_b128 v[196:199], v149 offset:52224
	ds_read_b128 v[200:203], v149 offset:53248
	ds_read_b128 v[204:207], v149 offset:54272
	ds_read_b128 v[208:211], v149 offset:55296
	ds_read_b128 v[212:215], v149 offset:56320
	global_load_lds_dwordx4 v[144:145], off
	s_add_i32 m0, s55, 0x2000
	s_add_u32 s84, s84, 0x40080
	v_lshl_add_u64 v[144:145], v[188:189], 0, s[50:51]
	s_addc_u32 s85, s85, 0
	s_add_i32 s55, s67, s58
	global_load_lds_dwordx4 v[144:145], off
	v_lshl_add_u64 v[144:145], s[84:85], 0, v[0:1]
	s_mov_b32 m0, s55
	s_nop 0
	global_load_lds_dwordx4 v[144:145], off
	v_lshl_add_u64 v[144:145], s[84:85], 0, v[134:135]
	s_add_i32 m0, s55, 0x2000
	s_nop 0
	global_load_lds_dwordx4 v[144:145], off
	v_lshl_add_u64 v[144:145], v[216:217], 0, s[50:51]
	s_mov_b32 m0, s89
	s_nop 0
	global_load_lds_dwordx4 v[144:145], off
	v_lshl_add_u64 v[144:145], v[218:219], 0, s[50:51]
	s_mov_b32 m0, s90
	s_nop 0
	global_load_lds_dwordx4 v[144:145], off
	s_waitcnt vmcnt(8)
	s_waitcnt lgkmcnt(0)
	s_barrier
	s_waitcnt lgkmcnt(0)
	v_mfma_f32_16x16x32_bf16 v[62:65], v[140:143], v[180:183], v[62:65]
	v_mfma_f32_16x16x32_bf16 v[58:61], v[156:159], v[180:183], v[58:61]
	v_mfma_f32_16x16x32_bf16 v[46:49], v[140:143], v[192:195], v[46:49]
	v_mfma_f32_16x16x32_bf16 v[42:45], v[156:159], v[192:195], v[42:45]
	v_mfma_f32_16x16x32_bf16 v[30:33], v[140:143], v[200:203], v[30:33]
	v_mfma_f32_16x16x32_bf16 v[26:29], v[156:159], v[200:203], v[26:29]
	v_mfma_f32_16x16x32_bf16 v[14:17], v[140:143], v[208:211], v[14:17]
	v_mfma_f32_16x16x32_bf16 v[10:13], v[156:159], v[208:211], v[10:13]
	v_mfma_f32_16x16x32_bf16 v[62:65], v[152:155], v[184:187], v[62:65]
	v_mfma_f32_16x16x32_bf16 v[58:61], v[160:163], v[184:187], v[58:61]
	v_mfma_f32_16x16x32_bf16 v[46:49], v[152:155], v[196:199], v[46:49]
	v_mfma_f32_16x16x32_bf16 v[42:45], v[160:163], v[196:199], v[42:45]
	v_mfma_f32_16x16x32_bf16 v[30:33], v[152:155], v[204:207], v[30:33]
	v_mfma_f32_16x16x32_bf16 v[26:29], v[160:163], v[204:207], v[26:29]
	v_mfma_f32_16x16x32_bf16 v[14:17], v[152:155], v[212:215], v[14:17]
	v_mfma_f32_16x16x32_bf16 v[10:13], v[160:163], v[212:215], v[10:13]
	v_mfma_f32_16x16x32_bf16 v[54:57], v[164:167], v[180:183], v[54:57]
	v_mfma_f32_16x16x32_bf16 v[50:53], v[172:175], v[180:183], v[50:53]
	v_mfma_f32_16x16x32_bf16 v[38:41], v[164:167], v[192:195], v[38:41]
	v_mfma_f32_16x16x32_bf16 v[34:37], v[172:175], v[192:195], v[34:37]
	v_mfma_f32_16x16x32_bf16 v[22:25], v[164:167], v[200:203], v[22:25]
	v_mfma_f32_16x16x32_bf16 v[18:21], v[172:175], v[200:203], v[18:21]
	v_mfma_f32_16x16x32_bf16 v[6:9], v[164:167], v[208:211], v[6:9]
	v_mfma_f32_16x16x32_bf16 v[2:5], v[172:175], v[208:211], v[2:5]
	v_mfma_f32_16x16x32_bf16 v[54:57], v[168:171], v[184:187], v[54:57]
	v_mfma_f32_16x16x32_bf16 v[50:53], v[176:179], v[184:187], v[50:53]
	v_mfma_f32_16x16x32_bf16 v[38:41], v[168:171], v[196:199], v[38:41]
	v_mfma_f32_16x16x32_bf16 v[34:37], v[176:179], v[196:199], v[34:37]
	v_mfma_f32_16x16x32_bf16 v[22:25], v[168:171], v[204:207], v[22:25]
	v_mfma_f32_16x16x32_bf16 v[18:21], v[176:179], v[204:207], v[18:21]
	v_mfma_f32_16x16x32_bf16 v[6:9], v[168:171], v[212:215], v[6:9]
	v_mfma_f32_16x16x32_bf16 v[2:5], v[176:179], v[212:215], v[2:5]
	s_barrier
	s_add_i32 s97, s97, 2
	s_add_u32 s6, s6, 0x100
	s_addc_u32 s7, s7, 0
	s_add_u32 s79, s79, 0x100
	s_addc_u32 s96, s96, 0
	s_cmp_gt_u32 s97, 13
	s_cbranch_scc0 .LBB0_165
	s_and_b64 vcc, exec, s[74:75]
	s_cbranch_vccz .LBB0_168
	s_barrier

.LBB0_213:
	v_readlane_b32 s4, v244, 6
	v_readlane_b32 s5, v244, 29
	s_add_u32 s6, s5, s4
	v_readlane_b32 s4, v244, 30
	s_addc_u32 s7, s4, 0
	s_add_u32 s4, s6, 0x300000
	s_addc_u32 s5, s7, 0
	s_add_u32 s12, s6, 0x340000
	s_addc_u32 s13, s7, 0
	s_mov_b64 s[6:7], s[0:1]
	s_waitcnt vmcnt(0)
	s_barrier
	s_load_dwordx2 s[72:73], s[6:7], 0x80
	s_mov_b64 s[6:7], s[0:1]
	v_mov_b32_e32 v140, v220
	v_readlane_b32 s46, v245, 2
	s_load_dwordx2 s[6:7], s[6:7], 0x80
	s_lshl_b32 s56, s46, 10
	v_lshl_add_u32 v2, v140, 4, s56
	v_ashrrev_i32_e32 v0, 31, v2
	v_lshrrev_b32_e32 v0, 22, v0
	v_add_u32_e32 v0, v2, v0
	v_ashrrev_i32_e32 v10, 10, v0
	v_mul_i32_i24_e32 v0, 0x400, v10
	v_sub_u32_e32 v0, v2, v0
	v_lshrrev_b32_e32 v3, 4, v0
	v_bitop3_b32 v0, v3, v0, 32 bitop3:0x6c
	v_ashrrev_i32_e32 v4, 31, v0
	v_lshrrev_b32_e32 v4, 26, v4
	v_add_u32_e32 v4, v0, v4
	v_lshlrev_b32_e32 v3, 3, v10
	v_ashrrev_i32_e32 v11, 6, v4
	v_and_b32_e32 v4, 0xc0, v4
	v_and_b32_e32 v3, -16, v3
	v_sub_u32_e32 v0, v0, v4
	v_add_u32_e32 v3, v11, v3
	v_ashrrev_i16_sdwa v0, v230, sext(v0) dst_sel:DWORD dst_unused:UNUSED_PAD src0_sel:DWORD src1_sel:BYTE_0
	v_lshlrev_b32_e32 v5, 5, v10
	v_bfe_i32 v12, v0, 0, 16
	v_lshlrev_b32_e32 v0, 1, v3
	v_lshrrev_b32_e32 v4, 2, v3
	v_and_b32_e32 v6, 3, v11
	s_mov_b32 s55, 0x1fffe0
	v_and_b32_e32 v5, 32, v5
	v_and_b32_e32 v0, 24, v0
	v_and_b32_e32 v4, 4, v4
	v_and_or_b32 v6, v3, s55, v6
	v_or3_b32 v0, v6, v4, v0
	v_add_lshl_u32 v4, v5, v12, 1
	v_add_u32_e32 v2, 0x2000, v2
	v_lshl_add_u32 v130, v3, 11, v4
	v_ashrrev_i32_e32 v3, 31, v2
	v_lshrrev_b32_e32 v3, 22, v3
	v_add_u32_e32 v3, v2, v3
	v_ashrrev_i32_e32 v13, 10, v3
	v_mul_i32_i24_e32 v3, 0x400, v13
	v_sub_u32_e32 v2, v2, v3
	v_lshrrev_b32_e32 v3, 4, v2
	v_bitop3_b32 v2, v3, v2, 32 bitop3:0x6c
	v_lshl_add_u32 v0, v0, 11, v4
	v_ashrrev_i32_e32 v4, 31, v2
	v_lshrrev_b32_e32 v4, 26, v4
	v_lshlrev_b32_e32 v3, 3, v13
	v_add_u32_e32 v4, v2, v4
	v_and_b32_e32 v3, -16, v3
	v_ashrrev_i32_e32 v14, 6, v4
	v_and_b32_e32 v4, 0xffc0, v4
	v_add_u32_e32 v3, v14, v3
	v_sub_u32_e32 v2, v2, v4
	v_and_b32_e32 v6, 3, v14
	s_ashr_i32 s61, s46, 2
	v_lshrrev_b16_e32 v4, 7, v2
	v_and_or_b32 v6, v3, s55, v6
	v_readlane_b32 s55, v245, 6
	v_and_b32_e32 v4, 1, v4
	s_waitcnt lgkmcnt(0)
	s_add_u32 s55, s72, s55
	v_add_u16_e32 v2, v2, v4
	s_addc_u32 s59, s73, 0
	v_ashrrev_i16_sdwa v2, v230, sext(v2) dst_sel:DWORD dst_unused:UNUSED_PAD src0_sel:DWORD src1_sel:BYTE_0
	s_add_u32 s70, s55, 0x7200000
	v_lshlrev_b32_e32 v5, 5, v13
	v_bfe_i32 v15, v2, 0, 16
	v_lshlrev_b32_e32 v2, 1, v3
	v_lshrrev_b32_e32 v4, 2, v3
	s_addc_u32 s71, s59, 0
	s_add_i32 s57, s56, 0
	v_and_b32_e32 v5, 32, v5
	v_and_b32_e32 v2, 24, v2
	v_and_b32_e32 v4, 4, v4
	s_add_i32 m0, s57, 0x10000
	v_or3_b32 v2, v6, v4, v2
	v_add_lshl_u32 v4, v5, v15, 1
	global_load_lds_dwordx4 v0, s[70:71]
	s_add_i32 m0, s57, 0x12000
	v_lshl_add_u32 v134, v2, 11, v4
	s_add_u32 s58, s55, 0x7240000
	global_load_lds_dwordx4 v134, s[70:71]
	s_addc_u32 s59, s59, 0
	s_add_i32 m0, s57, 0x14000
	v_lshl_add_u32 v132, v3, 11, v4
	global_load_lds_dwordx4 v0, s[58:59]
	s_add_i32 m0, s57, 0x16000
	s_add_i32 s60, s57, 0x6000
	global_load_lds_dwordx4 v134, s[58:59]
	s_mov_b32 m0, s57
	s_add_i32 s58, s57, 0x2000
	global_load_lds_dwordx4 v130, s[4:5]
	s_mov_b32 m0, s58
	s_add_i32 s59, s57, 0x4000
	global_load_lds_dwordx4 v132, s[4:5]
	s_mov_b32 m0, s59
	v_mov_b32_e32 v135, v1
	global_load_lds_dwordx4 v130, s[12:13]
	s_mov_b32 m0, s60
	v_mov_b32_e32 v131, v1
	global_load_lds_dwordx4 v132, s[12:13]
	v_mov_b32_e32 v133, v1
	v_readlane_b32 s92, v244, 24
	v_lshl_add_u64 v[8:9], s[70:71], 0, v[0:1]
	v_lshl_add_u64 v[6:7], s[70:71], 0, v[134:135]
	v_lshl_add_u64 v[4:5], s[4:5], 0, v[130:131]
	s_cmp_lg_u32 s61, 1
	v_lshl_add_u64 v[2:3], s[4:5], 0, v[132:133]
	v_readlane_b32 s93, v244, 25
	s_cbranch_scc1 .LBB0_215
	s_setprio 1
	s_barrier
.LBB0_215:
	s_lshl_b32 s12, s46, 5
	v_ashrrev_i32_e32 v17, 6, v140
	s_and_b32 s12, s12, 0x60
	v_and_b32_e32 v16, 15, v140
	v_lshlrev_b32_e32 v19, 10, v17
	s_lshr_b32 s13, s12, 3
	s_add_i32 m0, s57, 0x18000
	v_lshl_add_u64 v[8:9], v[8:9], 0, s[50:51]
	v_lshl_or_b32 v141, s61, 6, v16
	v_lshl_add_u32 v19, s61, 13, v19
	v_add_lshl_u32 v17, s13, v17, 10
	s_waitcnt vmcnt(2)
	s_barrier
	global_load_lds_dwordx4 v[8:9], off
	v_lshl_add_u64 v[6:7], v[6:7], 0, s[50:51]
	s_add_i32 m0, s57, 0x1a000
	s_add_i32 s13, s57, 0x8000
	s_add_i32 s61, s57, 0xa000
	global_load_lds_dwordx4 v[6:7], off
	v_lshl_add_u64 v[4:5], v[4:5], 0, s[50:51]
	s_mov_b32 m0, s13
	s_add_u32 s68, s70, 0x40080
	global_load_lds_dwordx4 v[4:5], off
	v_lshl_add_u64 v[2:3], v[2:3], 0, s[50:51]
	s_mov_b32 m0, s61
	s_addc_u32 s69, s71, 0
	global_load_lds_dwordx4 v[2:3], off
	s_add_i32 m0, s57, 0x1c000
	v_lshl_add_u64 v[2:3], s[68:69], 0, v[0:1]
	global_load_lds_dwordx4 v[2:3], off
	v_lshl_add_u64 v[2:3], s[68:69], 0, v[134:135]
	s_add_i32 m0, s57, 0x1e000
	v_readlane_b32 s55, v244, 6
	global_load_lds_dwordx4 v[2:3], off
	s_add_u32 s55, s2, s55
	s_addc_u32 s69, s3, 0
	s_add_u32 s68, s55, s33
	s_addc_u32 s69, s69, 0
	v_readlane_b32 s55, v244, 2
	v_lshlrev_b32_e32 v2, 14, v10
	s_add_u32 s2, s2, s55
	v_and_b32_e32 v2, 0xffff8000, v2
	s_addc_u32 s3, s3, 0
	v_lshl_add_u32 v2, v11, 11, v2
	v_and_b32_e32 v3, 1, v10
	v_lshl_or_b32 v2, v3, 6, v2
	s_add_u32 s2, s2, s33
	v_lshl_add_u32 v2, v12, 1, v2
	v_mov_b32_e32 v3, v1
	s_addc_u32 s3, s3, 0
	v_lshl_add_u64 v[136:137], s[2:3], 0, v[2:3]
	v_lshlrev_b32_e32 v2, 14, v13
	v_and_b32_e32 v2, 0xffff8000, v2
	v_lshl_add_u32 v2, v14, 11, v2
	v_and_b32_e32 v3, 1, v13
	v_and_b32_e32 v18, 48, v140
	v_lshl_or_b32 v2, v3, 6, v2
	v_lshl_or_b32 v16, v16, 6, v18
	v_lshlrev_b32_e32 v18, 2, v140
	v_lshl_add_u32 v2, v15, 1, v2
	v_mov_b32_e32 v3, v1
	v_and_b32_e32 v18, 32, v18
	s_waitcnt vmcnt(6)
	v_lshl_add_u64 v[138:139], s[2:3], 0, v[2:3]
	v_readlane_b32 s2, v244, 3
	v_bitop3_b32 v19, v16, v19, v18 bitop3:0xde
	s_add_u32 s33, s72, s2
	v_readlane_b32 s2, v244, 4
	v_bitop3_b32 v142, v17, v16, v18 bitop3:0xf6
	s_addc_u32 s76, s73, s2
	s_mov_b32 s77, -2
	s_mov_b64 s[2:3], 0
	v_add_u32_e32 v143, 0, v19
	v_readlane_b32 s91, v245, 4
	v_readlane_b32 s87, v244, 26
	s_movk_i32 s88, 0x600
	v_readlane_b32 s89, v244, 21
	s_mov_b32 s90, 0x46000000
	v_readlane_b32 s94, v244, 31
	s_barrier
	v_add_u32_e32 v156, s63, v142
	v_add_u32_e32 v172, s10, v142
	s_add_u32 s55, s68, s2
	ds_read_b128 v[144:147], v156
	ds_read_b128 v[148:151], v156 offset:1024
	ds_read_b128 v[152:155], v156 offset:2048
	ds_read_b128 v[156:159], v156 offset:3072
	ds_read_b128 v[160:163], v172
	ds_read_b128 v[164:167], v172 offset:1024
	ds_read_b128 v[168:171], v172 offset:2048
	ds_read_b128 v[172:175], v172 offset:3072
	s_addc_u32 s72, s69, s3
	s_add_u32 s55, s55, 0x500100
	s_addc_u32 s72, s72, 0
	s_add_u32 s78, s33, s2
	s_addc_u32 s73, s76, s3
	s_cmpk_eq_i32 s2, 0x700
	s_cselect_b32 s75, s5, s72
	s_cselect_b32 s74, s4, s55
	s_cselect_b32 s73, s71, s73
	s_cselect_b32 s72, s70, s78
	v_lshl_add_u64 v[188:189], v[136:137], 0, s[2:3]
	s_add_i32 m0, s57, 0xc000
	ds_read_b128 v[176:179], v143
	ds_read_b128 v[180:183], v143 offset:1024
	ds_read_b128 v[184:187], v143 offset:2048
	ds_read_b128 v[192:195], v143 offset:3072
	ds_read_b128 v[196:199], v143 offset:4096
	ds_read_b128 v[200:203], v143 offset:5120
	ds_read_b128 v[204:207], v143 offset:6144
	ds_read_b128 v[208:211], v143 offset:7168
	global_load_lds_dwordx4 v[188:189], off
	v_lshl_add_u64 v[188:189], v[138:139], 0, s[2:3]
	s_add_i32 m0, s57, 0xe000
	s_nop 0
	global_load_lds_dwordx4 v[188:189], off
	s_waitcnt vmcnt(8)
	s_waitcnt lgkmcnt(0)
	s_barrier
	s_waitcnt lgkmcnt(0)
	v_mfma_f32_16x16x32_bf16 v[126:129], v[144:147], v[176:179], 0
	v_mfma_f32_16x16x32_bf16 v[122:125], v[152:155], v[176:179], 0
	v_mfma_f32_16x16x32_bf16 v[118:121], v[144:147], v[184:187], 0
	v_mfma_f32_16x16x32_bf16 v[110:113], v[152:155], v[184:187], 0
	v_mfma_f32_16x16x32_bf16 v[102:105], v[144:147], v[196:199], 0
	v_mfma_f32_16x16x32_bf16 v[94:97], v[152:155], v[196:199], 0
	v_mfma_f32_16x16x32_bf16 v[86:89], v[144:147], v[204:207], 0
	v_mfma_f32_16x16x32_bf16 v[78:81], v[152:155], v[204:207], 0
	v_mfma_f32_16x16x32_bf16 v[126:129], v[148:151], v[180:183], v[126:129]
	v_mfma_f32_16x16x32_bf16 v[122:125], v[156:159], v[180:183], v[122:125]
	v_mfma_f32_16x16x32_bf16 v[118:121], v[148:151], v[192:195], v[118:121]
	v_mfma_f32_16x16x32_bf16 v[110:113], v[156:159], v[192:195], v[110:113]
	v_mfma_f32_16x16x32_bf16 v[102:105], v[148:151], v[200:203], v[102:105]
	v_mfma_f32_16x16x32_bf16 v[94:97], v[156:159], v[200:203], v[94:97]
	v_mfma_f32_16x16x32_bf16 v[86:89], v[148:151], v[208:211], v[86:89]
	v_mfma_f32_16x16x32_bf16 v[78:81], v[156:159], v[208:211], v[78:81]
	v_mfma_f32_16x16x32_bf16 v[114:117], v[160:163], v[176:179], 0
	v_mfma_f32_16x16x32_bf16 v[106:109], v[168:171], v[176:179], 0
	v_mfma_f32_16x16x32_bf16 v[98:101], v[160:163], v[184:187], 0
	v_mfma_f32_16x16x32_bf16 v[90:93], v[168:171], v[184:187], 0
	v_mfma_f32_16x16x32_bf16 v[82:85], v[160:163], v[196:199], 0
	v_mfma_f32_16x16x32_bf16 v[74:77], v[168:171], v[196:199], 0
	v_mfma_f32_16x16x32_bf16 v[70:73], v[160:163], v[204:207], 0
	v_mfma_f32_16x16x32_bf16 v[66:69], v[168:171], v[204:207], 0
	v_mfma_f32_16x16x32_bf16 v[114:117], v[164:167], v[180:183], v[114:117]
	v_mfma_f32_16x16x32_bf16 v[106:109], v[172:175], v[180:183], v[106:109]
	v_mfma_f32_16x16x32_bf16 v[98:101], v[164:167], v[192:195], v[98:101]
	v_mfma_f32_16x16x32_bf16 v[90:93], v[172:175], v[192:195], v[90:93]
	v_mfma_f32_16x16x32_bf16 v[82:85], v[164:167], v[200:203], v[82:85]
	v_mfma_f32_16x16x32_bf16 v[74:77], v[172:175], v[200:203], v[74:77]
	v_mfma_f32_16x16x32_bf16 v[70:73], v[164:167], v[208:211], v[70:73]
	v_mfma_f32_16x16x32_bf16 v[66:69], v[172:175], v[208:211], v[66:69]
	s_barrier
	s_add_i32 s55, s63, s56
	v_lshl_add_u64 v[188:189], s[72:73], 0, v[0:1]
	s_mov_b32 m0, s55
	ds_read_b128 v[176:179], v143 offset:16384
	ds_read_b128 v[180:183], v143 offset:17408
	ds_read_b128 v[184:187], v143 offset:18432
	ds_read_b128 v[192:195], v143 offset:19456
	ds_read_b128 v[196:199], v143 offset:20480
	ds_read_b128 v[200:203], v143 offset:21504
	ds_read_b128 v[204:207], v143 offset:22528
	ds_read_b128 v[208:211], v143 offset:23552
	global_load_lds_dwordx4 v[188:189], off
	s_add_i32 m0, s55, 0x2000
	s_add_u32 s78, s72, 0x40000
	v_lshl_add_u64 v[212:213], s[72:73], 0, v[134:135]
	s_addc_u32 s79, s73, 0
	s_add_i32 s55, s10, s56
	global_load_lds_dwordx4 v[212:213], off
	v_lshl_add_u64 v[214:215], s[78:79], 0, v[0:1]
	s_mov_b32 m0, s55
	v_lshl_add_u64 v[216:217], s[74:75], 0, v[132:133]
	global_load_lds_dwordx4 v[214:215], off
	v_lshl_add_u64 v[214:215], s[78:79], 0, v[134:135]
	s_add_i32 m0, s55, 0x2000
	s_nop 0
	global_load_lds_dwordx4 v[214:215], off
	v_lshl_add_u64 v[214:215], s[74:75], 0, v[130:131]
	s_mov_b32 m0, s57
	s_nop 0
	global_load_lds_dwordx4 v[214:215], off
	s_mov_b32 m0, s58
	s_nop 0
	global_load_lds_dwordx4 v[216:217], off
	s_waitcnt vmcnt(8)
	s_waitcnt lgkmcnt(0)
	s_barrier
	s_waitcnt lgkmcnt(0)
	v_mfma_f32_16x16x32_bf16 v[62:65], v[144:147], v[176:179], 0
	v_mfma_f32_16x16x32_bf16 v[58:61], v[152:155], v[176:179], 0
	v_mfma_f32_16x16x32_bf16 v[54:57], v[144:147], v[184:187], 0
	v_mfma_f32_16x16x32_bf16 v[46:49], v[152:155], v[184:187], 0
	v_mfma_f32_16x16x32_bf16 v[38:41], v[144:147], v[196:199], 0
	v_mfma_f32_16x16x32_bf16 v[30:33], v[152:155], v[196:199], 0
	v_mfma_f32_16x16x32_bf16 v[22:25], v[144:147], v[204:207], 0
	v_mfma_f32_16x16x32_bf16 v[14:17], v[152:155], v[204:207], 0
	v_mfma_f32_16x16x32_bf16 v[62:65], v[148:151], v[180:183], v[62:65]
	v_mfma_f32_16x16x32_bf16 v[58:61], v[156:159], v[180:183], v[58:61]
	v_mfma_f32_16x16x32_bf16 v[54:57], v[148:151], v[192:195], v[54:57]
	v_mfma_f32_16x16x32_bf16 v[46:49], v[156:159], v[192:195], v[46:49]
	v_mfma_f32_16x16x32_bf16 v[38:41], v[148:151], v[200:203], v[38:41]
	v_mfma_f32_16x16x32_bf16 v[30:33], v[156:159], v[200:203], v[30:33]
	v_mfma_f32_16x16x32_bf16 v[22:25], v[148:151], v[208:211], v[22:25]
	v_mfma_f32_16x16x32_bf16 v[14:17], v[156:159], v[208:211], v[14:17]
	v_mfma_f32_16x16x32_bf16 v[50:53], v[160:163], v[176:179], 0
	v_mfma_f32_16x16x32_bf16 v[42:45], v[168:171], v[176:179], 0
	v_mfma_f32_16x16x32_bf16 v[34:37], v[160:163], v[184:187], 0
	v_mfma_f32_16x16x32_bf16 v[26:29], v[168:171], v[184:187], 0
	v_mfma_f32_16x16x32_bf16 v[18:21], v[160:163], v[196:199], 0
	v_mfma_f32_16x16x32_bf16 v[10:13], v[168:171], v[196:199], 0
	v_mfma_f32_16x16x32_bf16 v[6:9], v[160:163], v[204:207], 0
	v_mfma_f32_16x16x32_bf16 v[2:5], v[168:171], v[204:207], 0
	v_mfma_f32_16x16x32_bf16 v[50:53], v[164:167], v[180:183], v[50:53]
	v_mfma_f32_16x16x32_bf16 v[42:45], v[172:175], v[180:183], v[42:45]
	v_mfma_f32_16x16x32_bf16 v[34:37], v[164:167], v[192:195], v[34:37]
	v_mfma_f32_16x16x32_bf16 v[26:29], v[172:175], v[192:195], v[26:29]
	v_mfma_f32_16x16x32_bf16 v[18:21], v[164:167], v[200:203], v[18:21]
	v_mfma_f32_16x16x32_bf16 v[10:13], v[172:175], v[200:203], v[10:13]
	v_mfma_f32_16x16x32_bf16 v[6:9], v[164:167], v[208:211], v[6:9]
	v_mfma_f32_16x16x32_bf16 v[2:5], v[172:175], v[208:211], v[2:5]
	s_barrier
	v_add_u32_e32 v156, s11, v142
	v_add_u32_e32 v172, s67, v142
	ds_read_b128 v[144:147], v156
	ds_read_b128 v[148:151], v156 offset:1024
	ds_read_b128 v[152:155], v156 offset:2048
	ds_read_b128 v[156:159], v156 offset:3072
	ds_read_b128 v[160:163], v172
	ds_read_b128 v[164:167], v172 offset:1024
	ds_read_b128 v[168:171], v172 offset:2048
	ds_read_b128 v[172:175], v172 offset:3072
	s_add_u32 s74, s74, 0x40000
	s_addc_u32 s75, s75, 0
	s_mov_b32 m0, s59
	v_lshl_add_u64 v[218:219], s[74:75], 0, v[130:131]
	ds_read_b128 v[176:179], v143 offset:32768
	ds_read_b128 v[180:183], v143 offset:33792
	ds_read_b128 v[184:187], v143 offset:34816
	ds_read_b128 v[192:195], v143 offset:35840
	ds_read_b128 v[196:199], v143 offset:36864
	ds_read_b128 v[200:203], v143 offset:37888
	ds_read_b128 v[204:207], v143 offset:38912
	ds_read_b128 v[208:211], v143 offset:39936
	global_load_lds_dwordx4 v[218:219], off
	v_lshl_add_u64 v[218:219], s[74:75], 0, v[132:133]
	s_mov_b32 m0, s60
	s_nop 0
	global_load_lds_dwordx4 v[218:219], off
	s_waitcnt vmcnt(8)
	s_waitcnt lgkmcnt(0)
	s_barrier
	s_waitcnt lgkmcnt(0)
	v_mfma_f32_16x16x32_bf16 v[126:129], v[144:147], v[176:179], v[126:129]
	v_mfma_f32_16x16x32_bf16 v[122:125], v[152:155], v[176:179], v[122:125]
	v_mfma_f32_16x16x32_bf16 v[118:121], v[144:147], v[184:187], v[118:121]
	v_mfma_f32_16x16x32_bf16 v[110:113], v[152:155], v[184:187], v[110:113]
	v_mfma_f32_16x16x32_bf16 v[102:105], v[144:147], v[196:199], v[102:105]
	v_mfma_f32_16x16x32_bf16 v[94:97], v[152:155], v[196:199], v[94:97]
	v_mfma_f32_16x16x32_bf16 v[86:89], v[144:147], v[204:207], v[86:89]
	v_mfma_f32_16x16x32_bf16 v[78:81], v[152:155], v[204:207], v[78:81]
	v_mfma_f32_16x16x32_bf16 v[126:129], v[148:151], v[180:183], v[126:129]
	v_mfma_f32_16x16x32_bf16 v[122:125], v[156:159], v[180:183], v[122:125]
	v_mfma_f32_16x16x32_bf16 v[118:121], v[148:151], v[192:195], v[118:121]
	v_mfma_f32_16x16x32_bf16 v[110:113], v[156:159], v[192:195], v[110:113]
	v_mfma_f32_16x16x32_bf16 v[102:105], v[148:151], v[200:203], v[102:105]
	v_mfma_f32_16x16x32_bf16 v[94:97], v[156:159], v[200:203], v[94:97]
	v_mfma_f32_16x16x32_bf16 v[86:89], v[148:151], v[208:211], v[86:89]
	v_mfma_f32_16x16x32_bf16 v[78:81], v[156:159], v[208:211], v[78:81]
	v_mfma_f32_16x16x32_bf16 v[114:117], v[160:163], v[176:179], v[114:117]
	v_mfma_f32_16x16x32_bf16 v[106:109], v[168:171], v[176:179], v[106:109]
	v_mfma_f32_16x16x32_bf16 v[98:101], v[160:163], v[184:187], v[98:101]
	v_mfma_f32_16x16x32_bf16 v[90:93], v[168:171], v[184:187], v[90:93]
	v_mfma_f32_16x16x32_bf16 v[82:85], v[160:163], v[196:199], v[82:85]
	v_mfma_f32_16x16x32_bf16 v[74:77], v[168:171], v[196:199], v[74:77]
	v_mfma_f32_16x16x32_bf16 v[70:73], v[160:163], v[204:207], v[70:73]
	v_mfma_f32_16x16x32_bf16 v[66:69], v[168:171], v[204:207], v[66:69]
	v_mfma_f32_16x16x32_bf16 v[114:117], v[164:167], v[180:183], v[114:117]
	v_mfma_f32_16x16x32_bf16 v[106:109], v[172:175], v[180:183], v[106:109]
	v_mfma_f32_16x16x32_bf16 v[98:101], v[164:167], v[192:195], v[98:101]
	v_mfma_f32_16x16x32_bf16 v[90:93], v[172:175], v[192:195], v[90:93]
	v_mfma_f32_16x16x32_bf16 v[82:85], v[164:167], v[200:203], v[82:85]
	v_mfma_f32_16x16x32_bf16 v[74:77], v[172:175], v[200:203], v[74:77]
	v_mfma_f32_16x16x32_bf16 v[70:73], v[164:167], v[208:211], v[70:73]
	v_mfma_f32_16x16x32_bf16 v[66:69], v[172:175], v[208:211], v[66:69]
	s_barrier
	s_add_i32 s55, s11, s56
	v_lshl_add_u64 v[188:189], v[188:189], 0, s[50:51]
	s_mov_b32 m0, s55
	ds_read_b128 v[176:179], v143 offset:49152
	ds_read_b128 v[180:183], v143 offset:50176
	ds_read_b128 v[184:187], v143 offset:51200
	ds_read_b128 v[192:195], v143 offset:52224
	ds_read_b128 v[196:199], v143 offset:53248
	ds_read_b128 v[200:203], v143 offset:54272
	ds_read_b128 v[204:207], v143 offset:55296
	ds_read_b128 v[208:211], v143 offset:56320
	global_load_lds_dwordx4 v[188:189], off
	s_add_i32 m0, s55, 0x2000
	s_add_u32 s72, s72, 0x40080
	v_lshl_add_u64 v[188:189], v[212:213], 0, s[50:51]
	s_addc_u32 s73, s73, 0
	s_add_i32 s55, s67, s56
	global_load_lds_dwordx4 v[188:189], off
	v_lshl_add_u64 v[188:189], s[72:73], 0, v[0:1]
	s_mov_b32 m0, s55
	s_nop 0
	global_load_lds_dwordx4 v[188:189], off
	v_lshl_add_u64 v[188:189], s[72:73], 0, v[134:135]
	s_add_i32 m0, s55, 0x2000
	s_nop 0
	global_load_lds_dwordx4 v[188:189], off
	v_lshl_add_u64 v[188:189], v[214:215], 0, s[50:51]
	s_mov_b32 m0, s13
	s_nop 0
	global_load_lds_dwordx4 v[188:189], off
	v_lshl_add_u64 v[188:189], v[216:217], 0, s[50:51]
	s_mov_b32 m0, s61
	s_nop 0
	global_load_lds_dwordx4 v[188:189], off
	s_waitcnt vmcnt(8)
	s_waitcnt lgkmcnt(0)
	s_barrier
	s_waitcnt lgkmcnt(0)
	v_mfma_f32_16x16x32_bf16 v[62:65], v[144:147], v[176:179], v[62:65]
	v_mfma_f32_16x16x32_bf16 v[58:61], v[152:155], v[176:179], v[58:61]
	v_mfma_f32_16x16x32_bf16 v[54:57], v[144:147], v[184:187], v[54:57]
	v_mfma_f32_16x16x32_bf16 v[46:49], v[152:155], v[184:187], v[46:49]
	v_mfma_f32_16x16x32_bf16 v[38:41], v[144:147], v[196:199], v[38:41]
	v_mfma_f32_16x16x32_bf16 v[30:33], v[152:155], v[196:199], v[30:33]
	v_mfma_f32_16x16x32_bf16 v[22:25], v[144:147], v[204:207], v[22:25]
	v_mfma_f32_16x16x32_bf16 v[14:17], v[152:155], v[204:207], v[14:17]
	v_mfma_f32_16x16x32_bf16 v[62:65], v[148:151], v[180:183], v[62:65]
	v_mfma_f32_16x16x32_bf16 v[58:61], v[156:159], v[180:183], v[58:61]
	v_mfma_f32_16x16x32_bf16 v[54:57], v[148:151], v[192:195], v[54:57]
	v_mfma_f32_16x16x32_bf16 v[46:49], v[156:159], v[192:195], v[46:49]
	v_mfma_f32_16x16x32_bf16 v[38:41], v[148:151], v[200:203], v[38:41]
	v_mfma_f32_16x16x32_bf16 v[30:33], v[156:159], v[200:203], v[30:33]
	v_mfma_f32_16x16x32_bf16 v[22:25], v[148:151], v[208:211], v[22:25]
	v_mfma_f32_16x16x32_bf16 v[14:17], v[156:159], v[208:211], v[14:17]
	v_mfma_f32_16x16x32_bf16 v[50:53], v[160:163], v[176:179], v[50:53]
	v_mfma_f32_16x16x32_bf16 v[42:45], v[168:171], v[176:179], v[42:45]
	v_mfma_f32_16x16x32_bf16 v[34:37], v[160:163], v[184:187], v[34:37]
	v_mfma_f32_16x16x32_bf16 v[26:29], v[168:171], v[184:187], v[26:29]
	v_mfma_f32_16x16x32_bf16 v[18:21], v[160:163], v[196:199], v[18:21]
	v_mfma_f32_16x16x32_bf16 v[10:13], v[168:171], v[196:199], v[10:13]
	v_mfma_f32_16x16x32_bf16 v[6:9], v[160:163], v[204:207], v[6:9]
	v_mfma_f32_16x16x32_bf16 v[2:5], v[168:171], v[204:207], v[2:5]
	v_mfma_f32_16x16x32_bf16 v[50:53], v[164:167], v[180:183], v[50:53]
	v_mfma_f32_16x16x32_bf16 v[42:45], v[172:175], v[180:183], v[42:45]
	v_mfma_f32_16x16x32_bf16 v[34:37], v[164:167], v[192:195], v[34:37]
	v_mfma_f32_16x16x32_bf16 v[26:29], v[172:175], v[192:195], v[26:29]
	v_mfma_f32_16x16x32_bf16 v[18:21], v[164:167], v[200:203], v[18:21]
	v_mfma_f32_16x16x32_bf16 v[10:13], v[172:175], v[200:203], v[10:13]
	v_mfma_f32_16x16x32_bf16 v[6:9], v[164:167], v[208:211], v[6:9]
	v_mfma_f32_16x16x32_bf16 v[2:5], v[172:175], v[208:211], v[2:5]
	s_barrier
	s_add_i32 s77, s77, 2
	s_add_u32 s2, s2, 0x100
	s_addc_u32 s3, s3, 0
.LBB0_216:
	v_add_u32_e32 v156, s63, v142
	v_add_u32_e32 v172, s10, v142
	s_add_u32 s55, s68, s2
	ds_read_b128 v[144:147], v156
	ds_read_b128 v[148:151], v156 offset:1024
	ds_read_b128 v[152:155], v156 offset:2048
	ds_read_b128 v[156:159], v156 offset:3072
	ds_read_b128 v[160:163], v172
	ds_read_b128 v[164:167], v172 offset:1024
	ds_read_b128 v[168:171], v172 offset:2048
	ds_read_b128 v[172:175], v172 offset:3072
	s_addc_u32 s72, s69, s3
	s_add_u32 s55, s55, 0x500100
	s_addc_u32 s72, s72, 0
	s_add_u32 s78, s33, s2
	s_addc_u32 s73, s76, s3
	s_cmpk_eq_i32 s2, 0x700
	s_cselect_b32 s75, s5, s72
	s_cselect_b32 s74, s4, s55
	s_cselect_b32 s73, s71, s73
	s_cselect_b32 s72, s70, s78
	v_lshl_add_u64 v[188:189], v[136:137], 0, s[2:3]
	s_add_i32 m0, s57, 0xc000
	ds_read_b128 v[176:179], v143
	ds_read_b128 v[180:183], v143 offset:1024
	ds_read_b128 v[184:187], v143 offset:2048
	ds_read_b128 v[192:195], v143 offset:3072
	ds_read_b128 v[196:199], v143 offset:4096
	ds_read_b128 v[200:203], v143 offset:5120
	ds_read_b128 v[204:207], v143 offset:6144
	ds_read_b128 v[208:211], v143 offset:7168
	global_load_lds_dwordx4 v[188:189], off
	v_lshl_add_u64 v[188:189], v[138:139], 0, s[2:3]
	s_add_i32 m0, s57, 0xe000
	s_nop 0
	global_load_lds_dwordx4 v[188:189], off
	s_waitcnt vmcnt(8)
	s_waitcnt lgkmcnt(0)
	s_barrier
	s_waitcnt lgkmcnt(0)
	v_mfma_f32_16x16x32_bf16 v[126:129], v[144:147], v[176:179], v[126:129]
	v_mfma_f32_16x16x32_bf16 v[122:125], v[152:155], v[176:179], v[122:125]
	v_mfma_f32_16x16x32_bf16 v[118:121], v[144:147], v[184:187], v[118:121]
	v_mfma_f32_16x16x32_bf16 v[110:113], v[152:155], v[184:187], v[110:113]
	v_mfma_f32_16x16x32_bf16 v[102:105], v[144:147], v[196:199], v[102:105]
	v_mfma_f32_16x16x32_bf16 v[94:97], v[152:155], v[196:199], v[94:97]
	v_mfma_f32_16x16x32_bf16 v[86:89], v[144:147], v[204:207], v[86:89]
	v_mfma_f32_16x16x32_bf16 v[78:81], v[152:155], v[204:207], v[78:81]
	v_mfma_f32_16x16x32_bf16 v[126:129], v[148:151], v[180:183], v[126:129]
	v_mfma_f32_16x16x32_bf16 v[122:125], v[156:159], v[180:183], v[122:125]
	v_mfma_f32_16x16x32_bf16 v[118:121], v[148:151], v[192:195], v[118:121]
	v_mfma_f32_16x16x32_bf16 v[110:113], v[156:159], v[192:195], v[110:113]
	v_mfma_f32_16x16x32_bf16 v[102:105], v[148:151], v[200:203], v[102:105]
	v_mfma_f32_16x16x32_bf16 v[94:97], v[156:159], v[200:203], v[94:97]
	v_mfma_f32_16x16x32_bf16 v[86:89], v[148:151], v[208:211], v[86:89]
	v_mfma_f32_16x16x32_bf16 v[78:81], v[156:159], v[208:211], v[78:81]
	v_mfma_f32_16x16x32_bf16 v[114:117], v[160:163], v[176:179], v[114:117]
	v_mfma_f32_16x16x32_bf16 v[106:109], v[168:171], v[176:179], v[106:109]
	v_mfma_f32_16x16x32_bf16 v[98:101], v[160:163], v[184:187], v[98:101]
	v_mfma_f32_16x16x32_bf16 v[90:93], v[168:171], v[184:187], v[90:93]
	v_mfma_f32_16x16x32_bf16 v[82:85], v[160:163], v[196:199], v[82:85]
	v_mfma_f32_16x16x32_bf16 v[74:77], v[168:171], v[196:199], v[74:77]
	v_mfma_f32_16x16x32_bf16 v[70:73], v[160:163], v[204:207], v[70:73]
	v_mfma_f32_16x16x32_bf16 v[66:69], v[168:171], v[204:207], v[66:69]
	v_mfma_f32_16x16x32_bf16 v[114:117], v[164:167], v[180:183], v[114:117]
	v_mfma_f32_16x16x32_bf16 v[106:109], v[172:175], v[180:183], v[106:109]
	v_mfma_f32_16x16x32_bf16 v[98:101], v[164:167], v[192:195], v[98:101]
	v_mfma_f32_16x16x32_bf16 v[90:93], v[172:175], v[192:195], v[90:93]
	v_mfma_f32_16x16x32_bf16 v[82:85], v[164:167], v[200:203], v[82:85]
	v_mfma_f32_16x16x32_bf16 v[74:77], v[172:175], v[200:203], v[74:77]
	v_mfma_f32_16x16x32_bf16 v[70:73], v[164:167], v[208:211], v[70:73]
	v_mfma_f32_16x16x32_bf16 v[66:69], v[172:175], v[208:211], v[66:69]
	s_barrier
	s_add_i32 s55, s63, s56
	v_lshl_add_u64 v[188:189], s[72:73], 0, v[0:1]
	s_mov_b32 m0, s55
	ds_read_b128 v[176:179], v143 offset:16384
	ds_read_b128 v[180:183], v143 offset:17408
	ds_read_b128 v[184:187], v143 offset:18432
	ds_read_b128 v[192:195], v143 offset:19456
	ds_read_b128 v[196:199], v143 offset:20480
	ds_read_b128 v[200:203], v143 offset:21504
	ds_read_b128 v[204:207], v143 offset:22528
	ds_read_b128 v[208:211], v143 offset:23552
	global_load_lds_dwordx4 v[188:189], off
	s_add_i32 m0, s55, 0x2000
	s_add_u32 s78, s72, 0x40000
	v_lshl_add_u64 v[212:213], s[72:73], 0, v[134:135]
	s_addc_u32 s79, s73, 0
	s_add_i32 s55, s10, s56
	global_load_lds_dwordx4 v[212:213], off
	v_lshl_add_u64 v[214:215], s[78:79], 0, v[0:1]
	s_mov_b32 m0, s55
	v_lshl_add_u64 v[216:217], s[74:75], 0, v[132:133]
	global_load_lds_dwordx4 v[214:215], off
	v_lshl_add_u64 v[214:215], s[78:79], 0, v[134:135]
	s_add_i32 m0, s55, 0x2000
	s_nop 0
	global_load_lds_dwordx4 v[214:215], off
	v_lshl_add_u64 v[214:215], s[74:75], 0, v[130:131]
	s_mov_b32 m0, s57
	s_nop 0
	global_load_lds_dwordx4 v[214:215], off
	s_mov_b32 m0, s58
	s_nop 0
	global_load_lds_dwordx4 v[216:217], off
	s_waitcnt vmcnt(8)
	s_waitcnt lgkmcnt(0)
	s_barrier
	s_waitcnt lgkmcnt(0)
	v_mfma_f32_16x16x32_bf16 v[62:65], v[144:147], v[176:179], v[62:65]
	v_mfma_f32_16x16x32_bf16 v[58:61], v[152:155], v[176:179], v[58:61]
	v_mfma_f32_16x16x32_bf16 v[54:57], v[144:147], v[184:187], v[54:57]
	v_mfma_f32_16x16x32_bf16 v[46:49], v[152:155], v[184:187], v[46:49]
	v_mfma_f32_16x16x32_bf16 v[38:41], v[144:147], v[196:199], v[38:41]
	v_mfma_f32_16x16x32_bf16 v[30:33], v[152:155], v[196:199], v[30:33]
	v_mfma_f32_16x16x32_bf16 v[22:25], v[144:147], v[204:207], v[22:25]
	v_mfma_f32_16x16x32_bf16 v[14:17], v[152:155], v[204:207], v[14:17]
	v_mfma_f32_16x16x32_bf16 v[62:65], v[148:151], v[180:183], v[62:65]
	v_mfma_f32_16x16x32_bf16 v[58:61], v[156:159], v[180:183], v[58:61]
	v_mfma_f32_16x16x32_bf16 v[54:57], v[148:151], v[192:195], v[54:57]
	v_mfma_f32_16x16x32_bf16 v[46:49], v[156:159], v[192:195], v[46:49]
	v_mfma_f32_16x16x32_bf16 v[38:41], v[148:151], v[200:203], v[38:41]
	v_mfma_f32_16x16x32_bf16 v[30:33], v[156:159], v[200:203], v[30:33]
	v_mfma_f32_16x16x32_bf16 v[22:25], v[148:151], v[208:211], v[22:25]
	v_mfma_f32_16x16x32_bf16 v[14:17], v[156:159], v[208:211], v[14:17]
	v_mfma_f32_16x16x32_bf16 v[50:53], v[160:163], v[176:179], v[50:53]
	v_mfma_f32_16x16x32_bf16 v[42:45], v[168:171], v[176:179], v[42:45]
	v_mfma_f32_16x16x32_bf16 v[34:37], v[160:163], v[184:187], v[34:37]
	v_mfma_f32_16x16x32_bf16 v[26:29], v[168:171], v[184:187], v[26:29]
	v_mfma_f32_16x16x32_bf16 v[18:21], v[160:163], v[196:199], v[18:21]
	v_mfma_f32_16x16x32_bf16 v[10:13], v[168:171], v[196:199], v[10:13]
	v_mfma_f32_16x16x32_bf16 v[6:9], v[160:163], v[204:207], v[6:9]
	v_mfma_f32_16x16x32_bf16 v[2:5], v[168:171], v[204:207], v[2:5]
	v_mfma_f32_16x16x32_bf16 v[50:53], v[164:167], v[180:183], v[50:53]
	v_mfma_f32_16x16x32_bf16 v[42:45], v[172:175], v[180:183], v[42:45]
	v_mfma_f32_16x16x32_bf16 v[34:37], v[164:167], v[192:195], v[34:37]
	v_mfma_f32_16x16x32_bf16 v[26:29], v[172:175], v[192:195], v[26:29]
	v_mfma_f32_16x16x32_bf16 v[18:21], v[164:167], v[200:203], v[18:21]
	v_mfma_f32_16x16x32_bf16 v[10:13], v[172:175], v[200:203], v[10:13]
	v_mfma_f32_16x16x32_bf16 v[6:9], v[164:167], v[208:211], v[6:9]
	v_mfma_f32_16x16x32_bf16 v[2:5], v[172:175], v[208:211], v[2:5]
	s_barrier
	v_add_u32_e32 v156, s11, v142
	v_add_u32_e32 v172, s67, v142
	ds_read_b128 v[144:147], v156
	ds_read_b128 v[148:151], v156 offset:1024
	ds_read_b128 v[152:155], v156 offset:2048
	ds_read_b128 v[156:159], v156 offset:3072
	ds_read_b128 v[160:163], v172
	ds_read_b128 v[164:167], v172 offset:1024
	ds_read_b128 v[168:171], v172 offset:2048
	ds_read_b128 v[172:175], v172 offset:3072
	s_add_u32 s74, s74, 0x40000
	s_addc_u32 s75, s75, 0
	s_mov_b32 m0, s59
	v_lshl_add_u64 v[218:219], s[74:75], 0, v[130:131]
	ds_read_b128 v[176:179], v143 offset:32768
	ds_read_b128 v[180:183], v143 offset:33792
	ds_read_b128 v[184:187], v143 offset:34816
	ds_read_b128 v[192:195], v143 offset:35840
	ds_read_b128 v[196:199], v143 offset:36864
	ds_read_b128 v[200:203], v143 offset:37888
	ds_read_b128 v[204:207], v143 offset:38912
	ds_read_b128 v[208:211], v143 offset:39936
	global_load_lds_dwordx4 v[218:219], off
	v_lshl_add_u64 v[218:219], s[74:75], 0, v[132:133]
	s_mov_b32 m0, s60
	s_nop 0
	global_load_lds_dwordx4 v[218:219], off
	s_waitcnt vmcnt(8)
	s_waitcnt lgkmcnt(0)
	s_barrier
	s_waitcnt lgkmcnt(0)
	v_mfma_f32_16x16x32_bf16 v[126:129], v[144:147], v[176:179], v[126:129]
	v_mfma_f32_16x16x32_bf16 v[122:125], v[152:155], v[176:179], v[122:125]
	v_mfma_f32_16x16x32_bf16 v[118:121], v[144:147], v[184:187], v[118:121]
	v_mfma_f32_16x16x32_bf16 v[110:113], v[152:155], v[184:187], v[110:113]
	v_mfma_f32_16x16x32_bf16 v[102:105], v[144:147], v[196:199], v[102:105]
	v_mfma_f32_16x16x32_bf16 v[94:97], v[152:155], v[196:199], v[94:97]
	v_mfma_f32_16x16x32_bf16 v[86:89], v[144:147], v[204:207], v[86:89]
	v_mfma_f32_16x16x32_bf16 v[78:81], v[152:155], v[204:207], v[78:81]
	v_mfma_f32_16x16x32_bf16 v[126:129], v[148:151], v[180:183], v[126:129]
	v_mfma_f32_16x16x32_bf16 v[122:125], v[156:159], v[180:183], v[122:125]
	v_mfma_f32_16x16x32_bf16 v[118:121], v[148:151], v[192:195], v[118:121]
	v_mfma_f32_16x16x32_bf16 v[110:113], v[156:159], v[192:195], v[110:113]
	v_mfma_f32_16x16x32_bf16 v[102:105], v[148:151], v[200:203], v[102:105]
	v_mfma_f32_16x16x32_bf16 v[94:97], v[156:159], v[200:203], v[94:97]
	v_mfma_f32_16x16x32_bf16 v[86:89], v[148:151], v[208:211], v[86:89]
	v_mfma_f32_16x16x32_bf16 v[78:81], v[156:159], v[208:211], v[78:81]
	v_mfma_f32_16x16x32_bf16 v[114:117], v[160:163], v[176:179], v[114:117]
	v_mfma_f32_16x16x32_bf16 v[106:109], v[168:171], v[176:179], v[106:109]
	v_mfma_f32_16x16x32_bf16 v[98:101], v[160:163], v[184:187], v[98:101]
	v_mfma_f32_16x16x32_bf16 v[90:93], v[168:171], v[184:187], v[90:93]
	v_mfma_f32_16x16x32_bf16 v[82:85], v[160:163], v[196:199], v[82:85]
	v_mfma_f32_16x16x32_bf16 v[74:77], v[168:171], v[196:199], v[74:77]
	v_mfma_f32_16x16x32_bf16 v[70:73], v[160:163], v[204:207], v[70:73]
	v_mfma_f32_16x16x32_bf16 v[66:69], v[168:171], v[204:207], v[66:69]
	v_mfma_f32_16x16x32_bf16 v[114:117], v[164:167], v[180:183], v[114:117]
	v_mfma_f32_16x16x32_bf16 v[106:109], v[172:175], v[180:183], v[106:109]
	v_mfma_f32_16x16x32_bf16 v[98:101], v[164:167], v[192:195], v[98:101]
	v_mfma_f32_16x16x32_bf16 v[90:93], v[172:175], v[192:195], v[90:93]
	v_mfma_f32_16x16x32_bf16 v[82:85], v[164:167], v[200:203], v[82:85]
	v_mfma_f32_16x16x32_bf16 v[74:77], v[172:175], v[200:203], v[74:77]
	v_mfma_f32_16x16x32_bf16 v[70:73], v[164:167], v[208:211], v[70:73]
	v_mfma_f32_16x16x32_bf16 v[66:69], v[172:175], v[208:211], v[66:69]
	s_barrier
	s_add_i32 s55, s11, s56
	v_lshl_add_u64 v[188:189], v[188:189], 0, s[50:51]
	s_mov_b32 m0, s55
	ds_read_b128 v[176:179], v143 offset:49152
	ds_read_b128 v[180:183], v143 offset:50176
	ds_read_b128 v[184:187], v143 offset:51200
	ds_read_b128 v[192:195], v143 offset:52224
	ds_read_b128 v[196:199], v143 offset:53248
	ds_read_b128 v[200:203], v143 offset:54272
	ds_read_b128 v[204:207], v143 offset:55296
	ds_read_b128 v[208:211], v143 offset:56320
	global_load_lds_dwordx4 v[188:189], off
	s_add_i32 m0, s55, 0x2000
	s_add_u32 s72, s72, 0x40080
	v_lshl_add_u64 v[188:189], v[212:213], 0, s[50:51]
	s_addc_u32 s73, s73, 0
	s_add_i32 s55, s67, s56
	global_load_lds_dwordx4 v[188:189], off
	v_lshl_add_u64 v[188:189], s[72:73], 0, v[0:1]
	s_mov_b32 m0, s55
	s_nop 0
	global_load_lds_dwordx4 v[188:189], off
	v_lshl_add_u64 v[188:189], s[72:73], 0, v[134:135]
	s_add_i32 m0, s55, 0x2000
	s_nop 0
	global_load_lds_dwordx4 v[188:189], off
	v_lshl_add_u64 v[188:189], v[214:215], 0, s[50:51]
	s_mov_b32 m0, s13
	s_nop 0
	global_load_lds_dwordx4 v[188:189], off
	v_lshl_add_u64 v[188:189], v[216:217], 0, s[50:51]
	s_mov_b32 m0, s61
	s_nop 0
	global_load_lds_dwordx4 v[188:189], off
	s_waitcnt vmcnt(8)
	s_waitcnt lgkmcnt(0)
	s_barrier
	s_waitcnt lgkmcnt(0)
	v_mfma_f32_16x16x32_bf16 v[62:65], v[144:147], v[176:179], v[62:65]
	v_mfma_f32_16x16x32_bf16 v[58:61], v[152:155], v[176:179], v[58:61]
	v_mfma_f32_16x16x32_bf16 v[54:57], v[144:147], v[184:187], v[54:57]
	v_mfma_f32_16x16x32_bf16 v[46:49], v[152:155], v[184:187], v[46:49]
	v_mfma_f32_16x16x32_bf16 v[38:41], v[144:147], v[196:199], v[38:41]
	v_mfma_f32_16x16x32_bf16 v[30:33], v[152:155], v[196:199], v[30:33]
	v_mfma_f32_16x16x32_bf16 v[22:25], v[144:147], v[204:207], v[22:25]
	v_mfma_f32_16x16x32_bf16 v[14:17], v[152:155], v[204:207], v[14:17]
	v_mfma_f32_16x16x32_bf16 v[62:65], v[148:151], v[180:183], v[62:65]
	v_mfma_f32_16x16x32_bf16 v[58:61], v[156:159], v[180:183], v[58:61]
	v_mfma_f32_16x16x32_bf16 v[54:57], v[148:151], v[192:195], v[54:57]
	v_mfma_f32_16x16x32_bf16 v[46:49], v[156:159], v[192:195], v[46:49]
	v_mfma_f32_16x16x32_bf16 v[38:41], v[148:151], v[200:203], v[38:41]
	v_mfma_f32_16x16x32_bf16 v[30:33], v[156:159], v[200:203], v[30:33]
	v_mfma_f32_16x16x32_bf16 v[22:25], v[148:151], v[208:211], v[22:25]
	v_mfma_f32_16x16x32_bf16 v[14:17], v[156:159], v[208:211], v[14:17]
	v_mfma_f32_16x16x32_bf16 v[50:53], v[160:163], v[176:179], v[50:53]
	v_mfma_f32_16x16x32_bf16 v[42:45], v[168:171], v[176:179], v[42:45]
	v_mfma_f32_16x16x32_bf16 v[34:37], v[160:163], v[184:187], v[34:37]
	v_mfma_f32_16x16x32_bf16 v[26:29], v[168:171], v[184:187], v[26:29]
	v_mfma_f32_16x16x32_bf16 v[18:21], v[160:163], v[196:199], v[18:21]
	v_mfma_f32_16x16x32_bf16 v[10:13], v[168:171], v[196:199], v[10:13]
	v_mfma_f32_16x16x32_bf16 v[6:9], v[160:163], v[204:207], v[6:9]
	v_mfma_f32_16x16x32_bf16 v[2:5], v[168:171], v[204:207], v[2:5]
	v_mfma_f32_16x16x32_bf16 v[50:53], v[164:167], v[180:183], v[50:53]
	v_mfma_f32_16x16x32_bf16 v[42:45], v[172:175], v[180:183], v[42:45]
	v_mfma_f32_16x16x32_bf16 v[34:37], v[164:167], v[192:195], v[34:37]
	v_mfma_f32_16x16x32_bf16 v[26:29], v[172:175], v[192:195], v[26:29]
	v_mfma_f32_16x16x32_bf16 v[18:21], v[164:167], v[200:203], v[18:21]
	v_mfma_f32_16x16x32_bf16 v[10:13], v[172:175], v[200:203], v[10:13]
	v_mfma_f32_16x16x32_bf16 v[6:9], v[164:167], v[208:211], v[6:9]
	v_mfma_f32_16x16x32_bf16 v[2:5], v[172:175], v[208:211], v[2:5]
	s_barrier
	s_add_i32 s77, s77, 2
	s_add_u32 s2, s2, 0x100
	s_addc_u32 s3, s3, 0
	s_cmp_gt_u32 s77, 13
	s_cbranch_scc0 .LBB0_216
	s_cmp_lt_u32 s46, 4
	s_cbranch_scc0 .LBB0_219
	s_barrier
.LBB0_219:
	v_readlane_b32 s2, v245, 7
	v_readlane_b32 s4, v245, 9
	v_ashrrev_i32_e32 v0, 1, v140
	s_add_u32 s2, s6, s2
	v_add_u32_e32 v132, s4, v141
	v_readlane_b32 s4, v245, 8
	v_and_b32_e32 v0, -8, v0
	s_addc_u32 s3, s7, 0
	s_add_i32 s12, s12, s4
	v_add_u32_e32 v130, s12, v0
	v_ashrrev_i32_e32 v131, 31, v130
	v_lshl_add_u64 v[130:131], v[130:131], 1, s[2:3]
	s_mov_b64 s[2:3], 0x19200000
	v_ashrrev_i32_e32 v133, 31, v132
	v_lshl_add_u64 v[134:135], v[130:131], 0, s[2:3]
	v_lshlrev_b64 v[130:131], 13, v[132:133]
	v_lshl_add_u64 v[130:131], v[134:135], 0, v[130:131]
	v_cvt_pk_bf16_f32 v126, v126, v127
	v_cvt_pk_bf16_f32 v127, v128, v129
	v_cvt_pk_bf16_f32 v128, v122, v123
	v_cvt_pk_bf16_f32 v129, v124, v125
	global_store_dwordx4 v[130:131], v[126:129], off
	v_cvt_pk_bf16_f32 v114, v114, v115
	v_cvt_pk_bf16_f32 v115, v116, v117
	v_cvt_pk_bf16_f32 v116, v106, v107
	v_or_b32_e32 v106, 16, v132
	v_ashrrev_i32_e32 v107, 31, v106
	v_lshlrev_b64 v[106:107], 13, v[106:107]
	v_cvt_pk_bf16_f32 v117, v108, v109
	global_store_dwordx4 v[130:131], v[114:117], off offset:256
	s_mov_b64 s[2:3], 0x100000
	s_mov_b64 s[6:7], 0
	v_lshl_add_u64 v[114:115], v[134:135], 0, v[106:107]
	v_cvt_pk_bf16_f32 v106, v118, v119
	v_cvt_pk_bf16_f32 v107, v120, v121
	v_cvt_pk_bf16_f32 v108, v110, v111
	v_cvt_pk_bf16_f32 v109, v112, v113
	global_store_dwordx4 v[114:115], v[106:109], off
	v_cvt_pk_bf16_f32 v98, v98, v99
	v_cvt_pk_bf16_f32 v99, v100, v101
	v_cvt_pk_bf16_f32 v100, v90, v91
	v_or_b32_e32 v90, 32, v132
	v_ashrrev_i32_e32 v91, 31, v90
	v_lshlrev_b64 v[90:91], 13, v[90:91]
	v_cvt_pk_bf16_f32 v101, v92, v93
	global_store_dwordx4 v[114:115], v[98:101], off offset:256
	s_nop 1
	v_lshl_add_u64 v[98:99], v[134:135], 0, v[90:91]
	v_cvt_pk_bf16_f32 v90, v102, v103
	v_cvt_pk_bf16_f32 v91, v104, v105
	v_cvt_pk_bf16_f32 v92, v94, v95
	v_cvt_pk_bf16_f32 v93, v96, v97
	global_store_dwordx4 v[98:99], v[90:93], off
	v_cvt_pk_bf16_f32 v82, v82, v83
	v_cvt_pk_bf16_f32 v83, v84, v85
	v_cvt_pk_bf16_f32 v84, v74, v75
	v_or_b32_e32 v74, 48, v132
	v_ashrrev_i32_e32 v75, 31, v74
	v_lshlrev_b64 v[74:75], 13, v[74:75]
	v_cvt_pk_bf16_f32 v85, v76, v77
	global_store_dwordx4 v[98:99], v[82:85], off offset:256
	s_nop 1
	v_lshl_add_u64 v[82:83], v[134:135], 0, v[74:75]
	v_cvt_pk_bf16_f32 v74, v86, v87
	v_cvt_pk_bf16_f32 v75, v88, v89
	v_cvt_pk_bf16_f32 v76, v78, v79
	v_cvt_pk_bf16_f32 v77, v80, v81
	global_store_dwordx4 v[82:83], v[74:77], off
	v_cvt_pk_bf16_f32 v70, v70, v71
	v_cvt_pk_bf16_f32 v71, v72, v73
	v_cvt_pk_bf16_f32 v72, v66, v67
	v_lshl_add_u64 v[66:67], v[130:131], 0, s[2:3]
	s_mov_b32 s2, 0x100000
	v_cvt_pk_bf16_f32 v73, v68, v69
	global_store_dwordx4 v[82:83], v[70:73], off offset:256
	v_cvt_pk_bf16_f32 v62, v62, v63
	v_cvt_pk_bf16_f32 v63, v64, v65
	v_cvt_pk_bf16_f32 v64, v58, v59
	v_add_co_u32_e32 v58, vcc, s2, v130
	v_cvt_pk_bf16_f32 v65, v60, v61
	s_mov_b64 s[2:3], 0x120000
	s_nop 0
	v_addc_co_u32_e32 v59, vcc, 0, v131, vcc
	global_store_dwordx4 v[58:59], v[62:65], off
	v_cvt_pk_bf16_f32 v50, v50, v51
	v_cvt_pk_bf16_f32 v51, v52, v53
	v_cvt_pk_bf16_f32 v52, v42, v43
	v_cvt_pk_bf16_f32 v53, v44, v45
	global_store_dwordx4 v[66:67], v[50:53], off offset:256
	v_cvt_pk_bf16_f32 v42, v54, v55
	v_cvt_pk_bf16_f32 v43, v56, v57
	v_cvt_pk_bf16_f32 v44, v46, v47
	v_cvt_pk_bf16_f32 v45, v48, v49
	s_nop 1
	v_lshl_add_u64 v[50:51], v[130:131], 0, s[2:3]
	s_mov_b32 s2, 0x120000
	v_add_co_u32_e32 v46, vcc, s2, v130
	s_mov_b64 s[2:3], 0x140000
	s_nop 0
	v_addc_co_u32_e32 v47, vcc, 0, v131, vcc
	global_store_dwordx4 v[46:47], v[42:45], off
	v_cvt_pk_bf16_f32 v34, v34, v35
	v_cvt_pk_bf16_f32 v35, v36, v37
	v_cvt_pk_bf16_f32 v36, v26, v27
	v_cvt_pk_bf16_f32 v37, v28, v29
	global_store_dwordx4 v[50:51], v[34:37], off offset:256
	v_cvt_pk_bf16_f32 v26, v38, v39
	v_cvt_pk_bf16_f32 v27, v40, v41
	v_cvt_pk_bf16_f32 v28, v30, v31
	v_cvt_pk_bf16_f32 v29, v32, v33
	s_nop 1
	v_lshl_add_u64 v[34:35], v[130:131], 0, s[2:3]
	s_mov_b32 s2, 0x140000
	v_add_co_u32_e32 v30, vcc, s2, v130
	s_mov_b64 s[2:3], 0x160000
	s_nop 0
	v_addc_co_u32_e32 v31, vcc, 0, v131, vcc
	global_store_dwordx4 v[30:31], v[26:29], off
	v_cvt_pk_bf16_f32 v18, v18, v19
	v_cvt_pk_bf16_f32 v19, v20, v21
	v_cvt_pk_bf16_f32 v20, v10, v11
	v_cvt_pk_bf16_f32 v21, v12, v13
	global_store_dwordx4 v[34:35], v[18:21], off offset:256
	v_cvt_pk_bf16_f32 v10, v22, v23
	v_cvt_pk_bf16_f32 v11, v24, v25
	v_cvt_pk_bf16_f32 v12, v14, v15
	v_cvt_pk_bf16_f32 v13, v16, v17
	s_nop 1
	v_lshl_add_u64 v[18:19], v[130:131], 0, s[2:3]
	s_mov_b32 s2, 0x160000
	v_add_co_u32_e32 v14, vcc, s2, v130
	s_mov_b64 s[2:3], s[0:1]
	s_nop 0
	v_addc_co_u32_e32 v15, vcc, 0, v131, vcc
	global_store_dwordx4 v[14:15], v[10:13], off
	v_cvt_pk_bf16_f32 v6, v6, v7
	v_cvt_pk_bf16_f32 v7, v8, v9
	v_cvt_pk_bf16_f32 v8, v2, v3
	v_cvt_pk_bf16_f32 v9, v4, v5
	global_store_dwordx4 v[18:19], v[6:9], off offset:256
	s_waitcnt vmcnt(0)
	s_barrier
	s_load_dwordx2 s[4:5], s[2:3], 0x80
	s_and_b64 vcc, exec, s[92:93]
	s_setprio 0
	s_getreg_b32 s12, hwreg(HW_REG_XCC_ID, 0, 4)
	s_cbranch_vccnz .LBB0_221
	v_mov_b32_e32 v0, v220
	s_nop 0
	v_cmp_eq_u32_e32 vcc, 0, v0
	s_and_b64 s[6:7], vcc, exec

.LBB0_719:
	s_mov_b64 s[2:3], s[0:1]
	s_load_dwordx2 s[4:5], s[2:3], 0x80
	v_readlane_b32 s2, v245, 0
	v_readlane_b32 s3, v245, 1
	s_mov_b64 s[6:7], 0
	s_setprio 0
	s_getreg_b32 s8, hwreg(HW_REG_XCC_ID, 0, 4)
	s_and_b64 vcc, exec, s[2:3]
	s_cbranch_vccz .LBB0_721
	v_mov_b32_e32 v0, v220
	s_nop 0
	v_cmp_eq_u32_e32 vcc, 0, v0
	s_and_b64 s[6:7], vcc, exec

.LBB0_775:
	s_mov_b64 s[2:3], s[0:1]
	s_load_dwordx2 s[90:91], s[2:3], 0x80
	s_mov_b64 s[2:3], s[0:1]
	s_load_dwordx2 s[4:5], s[2:3], 0x80
	s_mov_b64 s[2:3], s[0:1]
	s_lshl_b32 s6, s46, 25
	s_waitcnt lgkmcnt(0)
	s_add_u32 s55, s90, s6
	s_load_dwordx2 s[6:7], s[2:3], 0x80
	s_mov_b64 s[2:3], s[0:1]
	s_mov_b64 s[8:9], s[0:1]
	s_load_dwordx2 s[2:3], s[2:3], 0x80
	s_mov_b64 s[12:13], s[0:1]
	s_load_dwordx2 s[8:9], s[8:9], 0x80
	s_load_dwordx2 s[86:87], s[12:13], 0x48
	s_mov_b64 s[12:13], s[0:1]
	v_mov_b32_e32 v240, v220
	v_readlane_b32 s58, v245, 2
	s_addc_u32 s56, s91, 0
	s_load_dwordx2 s[84:85], s[12:13], 0x50
	s_lshl_b32 s13, s58, 10
	v_lshlrev_b32_e32 v12, 4, v240
	v_add_u32_e32 v2, s13, v12
	v_ashrrev_i32_e32 v0, 31, v2
	v_lshrrev_b32_e32 v0, 22, v0
	v_add_u32_e32 v0, v2, v0
	v_ashrrev_i32_e32 v6, 10, v0
	v_mul_i32_i24_e32 v0, 0x400, v6
	v_sub_u32_e32 v0, v2, v0
	v_lshrrev_b32_e32 v3, 4, v0
	v_bitop3_b32 v0, v3, v0, 32 bitop3:0x6c
	v_ashrrev_i32_e32 v4, 31, v0
	v_lshrrev_b32_e32 v4, 26, v4
	v_add_u32_e32 v4, v0, v4
	v_lshlrev_b32_e32 v3, 3, v6
	v_ashrrev_i32_e32 v7, 6, v4
	v_and_b32_e32 v4, 0xc0, v4
	v_and_b32_e32 v3, -16, v3
	v_sub_u32_e32 v0, v0, v4
	v_add_u32_e32 v3, v7, v3
	v_lshlrev_b32_e32 v5, 5, v6
	v_ashrrev_i16_sdwa v0, v230, sext(v0) dst_sel:DWORD dst_unused:UNUSED_PAD src0_sel:DWORD src1_sel:BYTE_0
	v_and_b32_e32 v5, 32, v5
	v_bfe_i32 v8, v0, 0, 16
	v_lshlrev_b32_e32 v0, 1, v3
	v_lshrrev_b32_e32 v4, 2, v3
	v_and_b32_e32 v9, 3, v7
	s_mov_b32 s57, 0x1fffe0
	v_and_b32_e32 v0, 24, v0
	v_and_b32_e32 v4, 4, v4
	v_and_or_b32 v9, v3, s57, v9
	v_add_lshl_u32 v5, v5, v8, 1
	v_add_u32_e32 v2, 0x2000, v2
	v_or3_b32 v4, v9, v4, v0
	v_lshl_add_u32 v0, v3, 11, v5
	v_ashrrev_i32_e32 v3, 31, v2
	v_lshrrev_b32_e32 v3, 22, v3
	v_add_u32_e32 v3, v2, v3
	v_ashrrev_i32_e32 v9, 10, v3
	v_mul_i32_i24_e32 v3, 0x400, v9
	v_sub_u32_e32 v2, v2, v3
	v_lshrrev_b32_e32 v3, 4, v2
	v_bitop3_b32 v2, v3, v2, 32 bitop3:0x6c
	v_lshl_add_u32 v82, v4, 11, v5
	v_ashrrev_i32_e32 v4, 31, v2
	v_lshrrev_b32_e32 v4, 26, v4
	v_add_u32_e32 v4, v2, v4
	v_ashrrev_i32_e32 v10, 6, v4
	v_and_b32_e32 v4, 0xffc0, v4
	v_sub_u32_e32 v2, v2, v4
	v_lshrrev_b16_e32 v4, 7, v2
	v_lshlrev_b32_e32 v3, 3, v9
	v_and_b32_e32 v4, 1, v4
	v_and_b32_e32 v3, -16, v3
	v_add_u16_e32 v2, v2, v4
	v_add_u32_e32 v3, v10, v3
	v_ashrrev_i16_sdwa v2, v230, sext(v2) dst_sel:DWORD dst_unused:UNUSED_PAD src0_sel:DWORD src1_sel:BYTE_0
	v_lshlrev_b32_e32 v5, 5, v9
	v_bfe_i32 v11, v2, 0, 16
	v_lshlrev_b32_e32 v2, 1, v3
	v_lshrrev_b32_e32 v4, 2, v3
	v_and_b32_e32 v13, 3, v10
	v_and_b32_e32 v5, 32, v5
	v_and_b32_e32 v2, 24, v2
	v_and_b32_e32 v4, 4, v4
	v_and_or_b32 v13, v3, s57, v13
	s_add_i32 s57, s13, 0
	v_or3_b32 v2, v13, v4, v2
	v_add_lshl_u32 v4, v5, v11, 1
	s_add_i32 m0, s57, 0x10000
	v_lshl_add_u32 v86, v2, 11, v4
	global_load_lds_dwordx4 v82, s[76:77]
	s_add_i32 m0, s57, 0x12000
	s_ashr_i32 s12, s58, 2
	global_load_lds_dwordx4 v86, s[76:77]
	s_add_i32 m0, s57, 0x14000
	v_readlane_b32 s59, v245, 57
	global_load_lds_dwordx4 v82, s[78:79]
	s_add_i32 m0, s57, 0x16000
	s_add_u32 s55, s55, s59
	s_addc_u32 s56, s56, 0
	s_add_u32 s88, s55, 0xb200000
	s_addc_u32 s89, s56, 0
	s_add_i32 s59, s57, 0x2000
	global_load_lds_dwordx4 v86, s[78:79]
	s_mov_b32 m0, s57
	s_add_u32 s68, s55, 0xb240000
	v_lshl_add_u32 v84, v3, 11, v4
	global_load_lds_dwordx4 v0, s[88:89]
	s_mov_b32 m0, s59
	s_addc_u32 s69, s56, 0
	s_add_i32 s60, s57, 0x4000
	global_load_lds_dwordx4 v84, s[88:89]
	s_mov_b32 m0, s60
	s_add_i32 s61, s57, 0x6000
	global_load_lds_dwordx4 v0, s[68:69]
	s_mov_b32 m0, s61
	v_mov_b32_e32 v85, v1
	global_load_lds_dwordx4 v84, s[68:69]
	v_lshl_add_u64 v[4:5], s[88:89], 0, v[0:1]
	s_cmp_lg_u32 s12, 1
	v_lshl_add_u64 v[2:3], s[88:89], 0, v[84:85]
	s_cbranch_scc1 .LBB0_777
	s_setprio 1
	s_barrier
.LBB0_777:
	v_and_b32_e32 v13, 15, v240
	v_and_b32_e32 v18, 48, v240
	v_mov_b32_e32 v83, v1
	s_and_b32 s56, s58, 3
	v_lshl_or_b32 v239, s12, 6, v13
	v_and_b32_e32 v12, 0xfffffc00, v12
	v_lshl_or_b32 v13, v13, 6, v18
	v_lshlrev_b32_e32 v18, 2, v240
	v_lshl_add_u64 v[14:15], s[76:77], 0, v[82:83]
	v_mov_b32_e32 v87, v1
	v_lshl_add_u32 v19, s12, 13, v12
	v_and_b32_e32 v18, 32, v18
	v_lshl_add_u32 v12, s56, 12, v12
	v_lshl_add_u64 v[16:17], s[76:77], 0, v[86:87]
	v_bitop3_b32 v19, v13, v19, v18 bitop3:0xde
	v_bitop3_b32 v108, v13, v12, v18 bitop3:0xde
	s_add_i32 m0, s57, 0x18000
	v_lshl_add_u64 v[12:13], v[14:15], 0, s[50:51]
	s_waitcnt vmcnt(2)
	s_barrier
	global_load_lds_dwordx4 v[12:13], off
	v_lshl_add_u64 v[12:13], v[16:17], 0, s[50:51]
	s_add_i32 m0, s57, 0x1a000
	s_add_i32 s68, s57, 0x8000
	global_load_lds_dwordx4 v[12:13], off
	v_lshl_add_u64 v[4:5], v[4:5], 0, s[50:51]
	s_mov_b32 m0, s68
	s_add_i32 s69, s57, 0xa000
	global_load_lds_dwordx4 v[4:5], off
	v_lshl_add_u64 v[2:3], v[2:3], 0, s[50:51]
	s_mov_b32 m0, s69
	s_xor_b64 s[82:83], s[92:93], -1
	global_load_lds_dwordx4 v[2:3], off
	s_add_i32 m0, s57, 0x1c000
	v_lshl_add_u64 v[2:3], s[80:81], 0, v[82:83]
	global_load_lds_dwordx4 v[2:3], off
	v_lshl_add_u64 v[2:3], s[80:81], 0, v[86:87]
	s_add_i32 m0, s57, 0x1e000
	v_readlane_b32 s55, v244, 7
	global_load_lds_dwordx4 v[2:3], off
	v_lshlrev_b32_e32 v2, 14, v6
	s_add_u32 s55, s90, s55
	v_readlane_b32 s90, v244, 8
	v_and_b32_e32 v2, 0xffff8000, v2
	s_addc_u32 s92, s91, s90
	s_lshl_b64 s[90:91], s[46:47], 25
	v_lshl_add_u32 v2, v7, 11, v2
	v_and_b32_e32 v3, 1, v6
	v_lshl_or_b32 v2, v3, 6, v2
	s_add_u32 s90, s55, s90
	v_lshl_add_u32 v2, v8, 1, v2
	v_mov_b32_e32 v3, v1
	s_addc_u32 s91, s92, s91
	v_lshl_add_u64 v[88:89], s[90:91], 0, v[2:3]
	v_lshlrev_b32_e32 v2, 14, v9
	v_and_b32_e32 v2, 0xffff8000, v2
	v_lshl_add_u32 v2, v10, 11, v2
	v_and_b32_e32 v3, 1, v9
	v_lshl_or_b32 v2, v3, 6, v2
	s_waitcnt vmcnt(6)
	v_lshl_add_u32 v2, v11, 1, v2
	v_mov_b32_e32 v3, v1
	v_lshl_add_u64 v[106:107], s[90:91], 0, v[2:3]
	s_mov_b32 vcc_lo, -2
	s_mov_b64 s[90:91], 0
	v_add_u32_e32 v109, 0, v19
	s_barrier
	v_add_u32_e32 v154, s63, v108
	v_add_u32_e32 v170, s10, v108
	s_add_u32 s92, s90, 0x100
	ds_read_b128 v[110:113], v154
	ds_read_b128 v[146:149], v154 offset:1024
	ds_read_b128 v[150:153], v154 offset:2048
	ds_read_b128 v[154:157], v154 offset:3072
	ds_read_b128 v[158:161], v170
	ds_read_b128 v[162:165], v170 offset:1024
	ds_read_b128 v[166:169], v170 offset:2048
	ds_read_b128 v[170:173], v170 offset:3072
	s_addc_u32 s93, s91, 0
	s_cmp_lg_u32 vcc_lo, 12
	s_cselect_b32 s94, s92, 0
	s_cselect_b32 s55, s93, 0
	s_add_u32 s96, s88, s94
	s_addc_u32 s97, s89, s55
	s_add_u32 s94, s76, s94
	s_addc_u32 s95, s77, s55
	v_lshl_add_u64 v[208:209], v[88:89], 0, s[90:91]
	s_add_i32 m0, s57, 0xc000
	ds_read_b128 v[174:177], v109
	ds_read_b128 v[178:181], v109 offset:1024
	ds_read_b128 v[182:185], v109 offset:2048
	ds_read_b128 v[186:189], v109 offset:3072
	ds_read_b128 v[192:195], v109 offset:4096
	ds_read_b128 v[196:199], v109 offset:5120
	ds_read_b128 v[200:203], v109 offset:6144
	ds_read_b128 v[204:207], v109 offset:7168
	global_load_lds_dwordx4 v[208:209], off
	v_lshl_add_u64 v[208:209], v[106:107], 0, s[90:91]
	s_add_i32 m0, s57, 0xe000
	s_nop 0
	global_load_lds_dwordx4 v[208:209], off
	s_waitcnt vmcnt(8)
	s_waitcnt lgkmcnt(0)
	s_barrier
	s_waitcnt lgkmcnt(0)
	v_mfma_f32_16x16x32_bf16 v[126:129], v[110:113], v[174:177], 0
	v_mfma_f32_16x16x32_bf16 v[118:121], v[150:153], v[174:177], 0
	v_mfma_f32_16x16x32_bf16 v[138:141], v[110:113], v[182:185], 0
	v_mfma_f32_16x16x32_bf16 v[134:137], v[150:153], v[182:185], 0
	v_mfma_f32_16x16x32_bf16 v[102:105], v[110:113], v[192:195], 0
	v_mfma_f32_16x16x32_bf16 v[98:101], v[150:153], v[192:195], 0
	v_mfma_f32_16x16x32_bf16 v[78:81], v[110:113], v[200:203], 0
	v_mfma_f32_16x16x32_bf16 v[74:77], v[150:153], v[200:203], 0
	v_mfma_f32_16x16x32_bf16 v[126:129], v[146:149], v[178:181], v[126:129]
	v_mfma_f32_16x16x32_bf16 v[118:121], v[154:157], v[178:181], v[118:121]
	v_mfma_f32_16x16x32_bf16 v[138:141], v[146:149], v[186:189], v[138:141]
	v_mfma_f32_16x16x32_bf16 v[134:137], v[154:157], v[186:189], v[134:137]
	v_mfma_f32_16x16x32_bf16 v[102:105], v[146:149], v[196:199], v[102:105]
	v_mfma_f32_16x16x32_bf16 v[98:101], v[154:157], v[196:199], v[98:101]
	v_mfma_f32_16x16x32_bf16 v[78:81], v[146:149], v[204:207], v[78:81]
	v_mfma_f32_16x16x32_bf16 v[74:77], v[154:157], v[204:207], v[74:77]
	v_mfma_f32_16x16x32_bf16 v[142:145], v[158:161], v[174:177], 0
	v_mfma_f32_16x16x32_bf16 v[114:117], v[166:169], v[174:177], 0
	v_mfma_f32_16x16x32_bf16 v[130:133], v[158:161], v[182:185], 0
	v_mfma_f32_16x16x32_bf16 v[122:125], v[166:169], v[182:185], 0
	v_mfma_f32_16x16x32_bf16 v[94:97], v[158:161], v[192:195], 0
	v_mfma_f32_16x16x32_bf16 v[90:93], v[166:169], v[192:195], 0
	v_mfma_f32_16x16x32_bf16 v[70:73], v[158:161], v[200:203], 0
	v_mfma_f32_16x16x32_bf16 v[66:69], v[166:169], v[200:203], 0
	v_mfma_f32_16x16x32_bf16 v[142:145], v[162:165], v[178:181], v[142:145]
	v_mfma_f32_16x16x32_bf16 v[114:117], v[170:173], v[178:181], v[114:117]
	v_mfma_f32_16x16x32_bf16 v[130:133], v[162:165], v[186:189], v[130:133]
	v_mfma_f32_16x16x32_bf16 v[122:125], v[170:173], v[186:189], v[122:125]
	v_mfma_f32_16x16x32_bf16 v[94:97], v[162:165], v[196:199], v[94:97]
	v_mfma_f32_16x16x32_bf16 v[90:93], v[170:173], v[196:199], v[90:93]
	v_mfma_f32_16x16x32_bf16 v[70:73], v[162:165], v[204:207], v[70:73]
	v_mfma_f32_16x16x32_bf16 v[66:69], v[170:173], v[204:207], v[66:69]
	s_barrier
	s_add_i32 s55, s63, s13
	v_lshl_add_u64 v[208:209], s[94:95], 0, v[82:83]
	s_mov_b32 m0, s55
	ds_read_b128 v[174:177], v109 offset:16384
	ds_read_b128 v[178:181], v109 offset:17408
	ds_read_b128 v[182:185], v109 offset:18432
	ds_read_b128 v[186:189], v109 offset:19456
	ds_read_b128 v[192:195], v109 offset:20480
	ds_read_b128 v[196:199], v109 offset:21504
	ds_read_b128 v[200:203], v109 offset:22528
	ds_read_b128 v[204:207], v109 offset:23552
	global_load_lds_dwordx4 v[208:209], off
	s_add_i32 m0, s55, 0x2000
	s_add_u32 s90, s94, 0x40000
	v_lshl_add_u64 v[210:211], s[94:95], 0, v[86:87]
	s_addc_u32 s91, s95, 0
	s_add_i32 s55, s10, s13
	global_load_lds_dwordx4 v[210:211], off
	v_lshl_add_u64 v[212:213], s[90:91], 0, v[82:83]
	s_mov_b32 m0, s55
	v_lshl_add_u64 v[214:215], s[96:97], 0, v[84:85]
	global_load_lds_dwordx4 v[212:213], off
	v_lshl_add_u64 v[212:213], s[90:91], 0, v[86:87]
	s_add_i32 m0, s55, 0x2000
	s_nop 0
	global_load_lds_dwordx4 v[212:213], off
	v_lshl_add_u64 v[212:213], s[96:97], 0, v[0:1]
	s_mov_b32 m0, s57
	s_nop 0
	global_load_lds_dwordx4 v[212:213], off
	s_mov_b32 m0, s59
	s_nop 0
	global_load_lds_dwordx4 v[214:215], off
	s_waitcnt vmcnt(8)
	s_waitcnt lgkmcnt(0)
	s_barrier
	s_waitcnt lgkmcnt(0)
	v_mfma_f32_16x16x32_bf16 v[62:65], v[110:113], v[174:177], 0
	v_mfma_f32_16x16x32_bf16 v[58:61], v[150:153], v[174:177], 0
	v_mfma_f32_16x16x32_bf16 v[46:49], v[110:113], v[182:185], 0
	v_mfma_f32_16x16x32_bf16 v[42:45], v[150:153], v[182:185], 0
	v_mfma_f32_16x16x32_bf16 v[30:33], v[110:113], v[192:195], 0
	v_mfma_f32_16x16x32_bf16 v[26:29], v[150:153], v[192:195], 0
	v_mfma_f32_16x16x32_bf16 v[14:17], v[110:113], v[200:203], 0
	v_mfma_f32_16x16x32_bf16 v[10:13], v[150:153], v[200:203], 0
	v_mfma_f32_16x16x32_bf16 v[62:65], v[146:149], v[178:181], v[62:65]
	v_mfma_f32_16x16x32_bf16 v[58:61], v[154:157], v[178:181], v[58:61]
	v_mfma_f32_16x16x32_bf16 v[46:49], v[146:149], v[186:189], v[46:49]
	v_mfma_f32_16x16x32_bf16 v[42:45], v[154:157], v[186:189], v[42:45]
	v_mfma_f32_16x16x32_bf16 v[30:33], v[146:149], v[196:199], v[30:33]
	v_mfma_f32_16x16x32_bf16 v[26:29], v[154:157], v[196:199], v[26:29]
	v_mfma_f32_16x16x32_bf16 v[14:17], v[146:149], v[204:207], v[14:17]
	v_mfma_f32_16x16x32_bf16 v[10:13], v[154:157], v[204:207], v[10:13]
	v_mfma_f32_16x16x32_bf16 v[54:57], v[158:161], v[174:177], 0
	v_mfma_f32_16x16x32_bf16 v[50:53], v[166:169], v[174:177], 0
	v_mfma_f32_16x16x32_bf16 v[38:41], v[158:161], v[182:185], 0
	v_mfma_f32_16x16x32_bf16 v[34:37], v[166:169], v[182:185], 0
	v_mfma_f32_16x16x32_bf16 v[22:25], v[158:161], v[192:195], 0
	v_mfma_f32_16x16x32_bf16 v[18:21], v[166:169], v[192:195], 0
	v_mfma_f32_16x16x32_bf16 v[6:9], v[158:161], v[200:203], 0
	v_mfma_f32_16x16x32_bf16 v[2:5], v[166:169], v[200:203], 0
	v_mfma_f32_16x16x32_bf16 v[54:57], v[162:165], v[178:181], v[54:57]
	v_mfma_f32_16x16x32_bf16 v[50:53], v[170:173], v[178:181], v[50:53]
	v_mfma_f32_16x16x32_bf16 v[38:41], v[162:165], v[186:189], v[38:41]
	v_mfma_f32_16x16x32_bf16 v[34:37], v[170:173], v[186:189], v[34:37]
	v_mfma_f32_16x16x32_bf16 v[22:25], v[162:165], v[196:199], v[22:25]
	v_mfma_f32_16x16x32_bf16 v[18:21], v[170:173], v[196:199], v[18:21]
	v_mfma_f32_16x16x32_bf16 v[6:9], v[162:165], v[204:207], v[6:9]
	v_mfma_f32_16x16x32_bf16 v[2:5], v[170:173], v[204:207], v[2:5]
	s_barrier
	v_add_u32_e32 v154, s11, v108
	v_add_u32_e32 v170, s67, v108
	ds_read_b128 v[110:113], v154
	ds_read_b128 v[146:149], v154 offset:1024
	ds_read_b128 v[150:153], v154 offset:2048
	ds_read_b128 v[154:157], v154 offset:3072
	ds_read_b128 v[158:161], v170
	ds_read_b128 v[162:165], v170 offset:1024
	ds_read_b128 v[166:169], v170 offset:2048
	ds_read_b128 v[170:173], v170 offset:3072
	s_add_u32 s90, s96, 0x40000
	s_addc_u32 s91, s97, 0
	s_mov_b32 m0, s60
	v_lshl_add_u64 v[216:217], s[90:91], 0, v[0:1]
	ds_read_b128 v[174:177], v109 offset:32768
	ds_read_b128 v[178:181], v109 offset:33792
	ds_read_b128 v[182:185], v109 offset:34816
	ds_read_b128 v[186:189], v109 offset:35840
	ds_read_b128 v[192:195], v109 offset:36864
	ds_read_b128 v[196:199], v109 offset:37888
	ds_read_b128 v[200:203], v109 offset:38912
	ds_read_b128 v[204:207], v109 offset:39936
	global_load_lds_dwordx4 v[216:217], off
	v_lshl_add_u64 v[216:217], s[90:91], 0, v[84:85]
	s_mov_b32 m0, s61
	s_nop 0
	global_load_lds_dwordx4 v[216:217], off
	s_waitcnt vmcnt(8)
	s_waitcnt lgkmcnt(0)
	s_barrier
	s_waitcnt lgkmcnt(0)
	v_mfma_f32_16x16x32_bf16 v[126:129], v[110:113], v[174:177], v[126:129]
	v_mfma_f32_16x16x32_bf16 v[118:121], v[150:153], v[174:177], v[118:121]
	v_mfma_f32_16x16x32_bf16 v[138:141], v[110:113], v[182:185], v[138:141]
	v_mfma_f32_16x16x32_bf16 v[134:137], v[150:153], v[182:185], v[134:137]
	v_mfma_f32_16x16x32_bf16 v[102:105], v[110:113], v[192:195], v[102:105]
	v_mfma_f32_16x16x32_bf16 v[98:101], v[150:153], v[192:195], v[98:101]
	v_mfma_f32_16x16x32_bf16 v[78:81], v[110:113], v[200:203], v[78:81]
	v_mfma_f32_16x16x32_bf16 v[74:77], v[150:153], v[200:203], v[74:77]
	v_mfma_f32_16x16x32_bf16 v[126:129], v[146:149], v[178:181], v[126:129]
	v_mfma_f32_16x16x32_bf16 v[118:121], v[154:157], v[178:181], v[118:121]
	v_mfma_f32_16x16x32_bf16 v[138:141], v[146:149], v[186:189], v[138:141]
	v_mfma_f32_16x16x32_bf16 v[134:137], v[154:157], v[186:189], v[134:137]
	v_mfma_f32_16x16x32_bf16 v[102:105], v[146:149], v[196:199], v[102:105]
	v_mfma_f32_16x16x32_bf16 v[98:101], v[154:157], v[196:199], v[98:101]
	v_mfma_f32_16x16x32_bf16 v[78:81], v[146:149], v[204:207], v[78:81]
	v_mfma_f32_16x16x32_bf16 v[74:77], v[154:157], v[204:207], v[74:77]
	v_mfma_f32_16x16x32_bf16 v[142:145], v[158:161], v[174:177], v[142:145]
	v_mfma_f32_16x16x32_bf16 v[114:117], v[166:169], v[174:177], v[114:117]
	v_mfma_f32_16x16x32_bf16 v[130:133], v[158:161], v[182:185], v[130:133]
	v_mfma_f32_16x16x32_bf16 v[122:125], v[166:169], v[182:185], v[122:125]
	v_mfma_f32_16x16x32_bf16 v[94:97], v[158:161], v[192:195], v[94:97]
	v_mfma_f32_16x16x32_bf16 v[90:93], v[166:169], v[192:195], v[90:93]
	v_mfma_f32_16x16x32_bf16 v[70:73], v[158:161], v[200:203], v[70:73]
	v_mfma_f32_16x16x32_bf16 v[66:69], v[166:169], v[200:203], v[66:69]
	v_mfma_f32_16x16x32_bf16 v[142:145], v[162:165], v[178:181], v[142:145]
	v_mfma_f32_16x16x32_bf16 v[114:117], v[170:173], v[178:181], v[114:117]
	v_mfma_f32_16x16x32_bf16 v[130:133], v[162:165], v[186:189], v[130:133]
	v_mfma_f32_16x16x32_bf16 v[122:125], v[170:173], v[186:189], v[122:125]
	v_mfma_f32_16x16x32_bf16 v[94:97], v[162:165], v[196:199], v[94:97]
	v_mfma_f32_16x16x32_bf16 v[90:93], v[170:173], v[196:199], v[90:93]
	v_mfma_f32_16x16x32_bf16 v[70:73], v[162:165], v[204:207], v[70:73]
	v_mfma_f32_16x16x32_bf16 v[66:69], v[170:173], v[204:207], v[66:69]
	s_barrier
	s_add_i32 s55, s11, s13
	v_lshl_add_u64 v[208:209], v[208:209], 0, s[50:51]
	s_mov_b32 m0, s55
	ds_read_b128 v[174:177], v109 offset:49152
	ds_read_b128 v[178:181], v109 offset:50176
	ds_read_b128 v[182:185], v109 offset:51200
	ds_read_b128 v[186:189], v109 offset:52224
	ds_read_b128 v[192:195], v109 offset:53248
	ds_read_b128 v[196:199], v109 offset:54272
	ds_read_b128 v[200:203], v109 offset:55296
	ds_read_b128 v[204:207], v109 offset:56320
	global_load_lds_dwordx4 v[208:209], off
	s_add_i32 m0, s55, 0x2000
	s_add_u32 s90, s94, 0x40080
	v_lshl_add_u64 v[208:209], v[210:211], 0, s[50:51]
	s_addc_u32 s91, s95, 0
	s_add_i32 s55, s67, s13
	global_load_lds_dwordx4 v[208:209], off
	v_lshl_add_u64 v[208:209], s[90:91], 0, v[82:83]
	s_mov_b32 m0, s55
	s_nop 0
	global_load_lds_dwordx4 v[208:209], off
	v_lshl_add_u64 v[208:209], s[90:91], 0, v[86:87]
	s_add_i32 m0, s55, 0x2000
	s_nop 0
	global_load_lds_dwordx4 v[208:209], off
	v_lshl_add_u64 v[208:209], v[212:213], 0, s[50:51]
	s_mov_b32 m0, s68
	s_nop 0
	global_load_lds_dwordx4 v[208:209], off
	v_lshl_add_u64 v[208:209], v[214:215], 0, s[50:51]
	s_mov_b32 m0, s69
	s_nop 0
	global_load_lds_dwordx4 v[208:209], off
	s_waitcnt vmcnt(8)
	s_waitcnt lgkmcnt(0)
	s_barrier
	s_waitcnt lgkmcnt(0)
	v_mfma_f32_16x16x32_bf16 v[62:65], v[110:113], v[174:177], v[62:65]
	v_mfma_f32_16x16x32_bf16 v[58:61], v[150:153], v[174:177], v[58:61]
	v_mfma_f32_16x16x32_bf16 v[46:49], v[110:113], v[182:185], v[46:49]
	v_mfma_f32_16x16x32_bf16 v[42:45], v[150:153], v[182:185], v[42:45]
	v_mfma_f32_16x16x32_bf16 v[30:33], v[110:113], v[192:195], v[30:33]
	v_mfma_f32_16x16x32_bf16 v[26:29], v[150:153], v[192:195], v[26:29]
	v_mfma_f32_16x16x32_bf16 v[14:17], v[110:113], v[200:203], v[14:17]
	v_mfma_f32_16x16x32_bf16 v[10:13], v[150:153], v[200:203], v[10:13]
	v_mfma_f32_16x16x32_bf16 v[62:65], v[146:149], v[178:181], v[62:65]
	v_mfma_f32_16x16x32_bf16 v[58:61], v[154:157], v[178:181], v[58:61]
	v_mfma_f32_16x16x32_bf16 v[46:49], v[146:149], v[186:189], v[46:49]
	v_mfma_f32_16x16x32_bf16 v[42:45], v[154:157], v[186:189], v[42:45]
	v_mfma_f32_16x16x32_bf16 v[30:33], v[146:149], v[196:199], v[30:33]
	v_mfma_f32_16x16x32_bf16 v[26:29], v[154:157], v[196:199], v[26:29]
	v_mfma_f32_16x16x32_bf16 v[14:17], v[146:149], v[204:207], v[14:17]
	v_mfma_f32_16x16x32_bf16 v[10:13], v[154:157], v[204:207], v[10:13]
	v_mfma_f32_16x16x32_bf16 v[54:57], v[158:161], v[174:177], v[54:57]
	v_mfma_f32_16x16x32_bf16 v[50:53], v[166:169], v[174:177], v[50:53]
	v_mfma_f32_16x16x32_bf16 v[38:41], v[158:161], v[182:185], v[38:41]
	v_mfma_f32_16x16x32_bf16 v[34:37], v[166:169], v[182:185], v[34:37]
	v_mfma_f32_16x16x32_bf16 v[22:25], v[158:161], v[192:195], v[22:25]
	v_mfma_f32_16x16x32_bf16 v[18:21], v[166:169], v[192:195], v[18:21]
	v_mfma_f32_16x16x32_bf16 v[6:9], v[158:161], v[200:203], v[6:9]
	v_mfma_f32_16x16x32_bf16 v[2:5], v[166:169], v[200:203], v[2:5]
	v_mfma_f32_16x16x32_bf16 v[54:57], v[162:165], v[178:181], v[54:57]
	v_mfma_f32_16x16x32_bf16 v[50:53], v[170:173], v[178:181], v[50:53]
	v_mfma_f32_16x16x32_bf16 v[38:41], v[162:165], v[186:189], v[38:41]
	v_mfma_f32_16x16x32_bf16 v[34:37], v[170:173], v[186:189], v[34:37]
	v_mfma_f32_16x16x32_bf16 v[22:25], v[162:165], v[196:199], v[22:25]
	v_mfma_f32_16x16x32_bf16 v[18:21], v[170:173], v[196:199], v[18:21]
	v_mfma_f32_16x16x32_bf16 v[6:9], v[162:165], v[204:207], v[6:9]
	v_mfma_f32_16x16x32_bf16 v[2:5], v[170:173], v[204:207], v[2:5]
	s_barrier
	s_add_i32 vcc_lo, vcc_lo, 2
	s_mov_b64 s[90:91], s[92:93]
.LBB0_778:
	v_add_u32_e32 v154, s63, v108
	v_add_u32_e32 v170, s10, v108
	s_add_u32 s92, s90, 0x100
	ds_read_b128 v[110:113], v154
	ds_read_b128 v[146:149], v154 offset:1024
	ds_read_b128 v[150:153], v154 offset:2048
	ds_read_b128 v[154:157], v154 offset:3072
	ds_read_b128 v[158:161], v170
	ds_read_b128 v[162:165], v170 offset:1024
	ds_read_b128 v[166:169], v170 offset:2048
	ds_read_b128 v[170:173], v170 offset:3072
	s_addc_u32 s93, s91, 0
	s_cmp_lg_u32 vcc_lo, 12
	s_cselect_b32 s94, s92, 0
	s_cselect_b32 s55, s93, 0
	s_add_u32 s96, s88, s94
	s_addc_u32 s97, s89, s55
	s_add_u32 s94, s76, s94
	s_addc_u32 s95, s77, s55
	v_lshl_add_u64 v[208:209], v[88:89], 0, s[90:91]
	s_add_i32 m0, s57, 0xc000
	ds_read_b128 v[174:177], v109
	ds_read_b128 v[178:181], v109 offset:1024
	ds_read_b128 v[182:185], v109 offset:2048
	ds_read_b128 v[186:189], v109 offset:3072
	ds_read_b128 v[192:195], v109 offset:4096
	ds_read_b128 v[196:199], v109 offset:5120
	ds_read_b128 v[200:203], v109 offset:6144
	ds_read_b128 v[204:207], v109 offset:7168
	global_load_lds_dwordx4 v[208:209], off
	v_lshl_add_u64 v[208:209], v[106:107], 0, s[90:91]
	s_add_i32 m0, s57, 0xe000
	s_nop 0
	global_load_lds_dwordx4 v[208:209], off
	s_waitcnt vmcnt(8)
	s_waitcnt lgkmcnt(0)
	s_barrier
	s_waitcnt lgkmcnt(0)
	v_mfma_f32_16x16x32_bf16 v[126:129], v[110:113], v[174:177], v[126:129]
	v_mfma_f32_16x16x32_bf16 v[118:121], v[150:153], v[174:177], v[118:121]
	v_mfma_f32_16x16x32_bf16 v[138:141], v[110:113], v[182:185], v[138:141]
	v_mfma_f32_16x16x32_bf16 v[134:137], v[150:153], v[182:185], v[134:137]
	v_mfma_f32_16x16x32_bf16 v[102:105], v[110:113], v[192:195], v[102:105]
	v_mfma_f32_16x16x32_bf16 v[98:101], v[150:153], v[192:195], v[98:101]
	v_mfma_f32_16x16x32_bf16 v[78:81], v[110:113], v[200:203], v[78:81]
	v_mfma_f32_16x16x32_bf16 v[74:77], v[150:153], v[200:203], v[74:77]
	v_mfma_f32_16x16x32_bf16 v[126:129], v[146:149], v[178:181], v[126:129]
	v_mfma_f32_16x16x32_bf16 v[118:121], v[154:157], v[178:181], v[118:121]
	v_mfma_f32_16x16x32_bf16 v[138:141], v[146:149], v[186:189], v[138:141]
	v_mfma_f32_16x16x32_bf16 v[134:137], v[154:157], v[186:189], v[134:137]
	v_mfma_f32_16x16x32_bf16 v[102:105], v[146:149], v[196:199], v[102:105]
	v_mfma_f32_16x16x32_bf16 v[98:101], v[154:157], v[196:199], v[98:101]
	v_mfma_f32_16x16x32_bf16 v[78:81], v[146:149], v[204:207], v[78:81]
	v_mfma_f32_16x16x32_bf16 v[74:77], v[154:157], v[204:207], v[74:77]
	v_mfma_f32_16x16x32_bf16 v[142:145], v[158:161], v[174:177], v[142:145]
	v_mfma_f32_16x16x32_bf16 v[114:117], v[166:169], v[174:177], v[114:117]
	v_mfma_f32_16x16x32_bf16 v[130:133], v[158:161], v[182:185], v[130:133]
	v_mfma_f32_16x16x32_bf16 v[122:125], v[166:169], v[182:185], v[122:125]
	v_mfma_f32_16x16x32_bf16 v[94:97], v[158:161], v[192:195], v[94:97]
	v_mfma_f32_16x16x32_bf16 v[90:93], v[166:169], v[192:195], v[90:93]
	v_mfma_f32_16x16x32_bf16 v[70:73], v[158:161], v[200:203], v[70:73]
	v_mfma_f32_16x16x32_bf16 v[66:69], v[166:169], v[200:203], v[66:69]
	v_mfma_f32_16x16x32_bf16 v[142:145], v[162:165], v[178:181], v[142:145]
	v_mfma_f32_16x16x32_bf16 v[114:117], v[170:173], v[178:181], v[114:117]
	v_mfma_f32_16x16x32_bf16 v[130:133], v[162:165], v[186:189], v[130:133]
	v_mfma_f32_16x16x32_bf16 v[122:125], v[170:173], v[186:189], v[122:125]
	v_mfma_f32_16x16x32_bf16 v[94:97], v[162:165], v[196:199], v[94:97]
	v_mfma_f32_16x16x32_bf16 v[90:93], v[170:173], v[196:199], v[90:93]
	v_mfma_f32_16x16x32_bf16 v[70:73], v[162:165], v[204:207], v[70:73]
	v_mfma_f32_16x16x32_bf16 v[66:69], v[170:173], v[204:207], v[66:69]
	s_barrier
	s_add_i32 s55, s63, s13
	v_lshl_add_u64 v[208:209], s[94:95], 0, v[82:83]
	s_mov_b32 m0, s55
	ds_read_b128 v[174:177], v109 offset:16384
	ds_read_b128 v[178:181], v109 offset:17408
	ds_read_b128 v[182:185], v109 offset:18432
	ds_read_b128 v[186:189], v109 offset:19456
	ds_read_b128 v[192:195], v109 offset:20480
	ds_read_b128 v[196:199], v109 offset:21504
	ds_read_b128 v[200:203], v109 offset:22528
	ds_read_b128 v[204:207], v109 offset:23552
	global_load_lds_dwordx4 v[208:209], off
	s_add_i32 m0, s55, 0x2000
	s_add_u32 s90, s94, 0x40000
	v_lshl_add_u64 v[210:211], s[94:95], 0, v[86:87]
	s_addc_u32 s91, s95, 0
	s_add_i32 s55, s10, s13
	global_load_lds_dwordx4 v[210:211], off
	v_lshl_add_u64 v[212:213], s[90:91], 0, v[82:83]
	s_mov_b32 m0, s55
	v_lshl_add_u64 v[214:215], s[96:97], 0, v[84:85]
	global_load_lds_dwordx4 v[212:213], off
	v_lshl_add_u64 v[212:213], s[90:91], 0, v[86:87]
	s_add_i32 m0, s55, 0x2000
	s_nop 0
	global_load_lds_dwordx4 v[212:213], off
	v_lshl_add_u64 v[212:213], s[96:97], 0, v[0:1]
	s_mov_b32 m0, s57
	s_nop 0
	global_load_lds_dwordx4 v[212:213], off
	s_mov_b32 m0, s59
	s_nop 0
	global_load_lds_dwordx4 v[214:215], off
	s_waitcnt vmcnt(8)
	s_waitcnt lgkmcnt(0)
	s_barrier
	s_waitcnt lgkmcnt(0)
	v_mfma_f32_16x16x32_bf16 v[62:65], v[110:113], v[174:177], v[62:65]
	v_mfma_f32_16x16x32_bf16 v[58:61], v[150:153], v[174:177], v[58:61]
	v_mfma_f32_16x16x32_bf16 v[46:49], v[110:113], v[182:185], v[46:49]
	v_mfma_f32_16x16x32_bf16 v[42:45], v[150:153], v[182:185], v[42:45]
	v_mfma_f32_16x16x32_bf16 v[30:33], v[110:113], v[192:195], v[30:33]
	v_mfma_f32_16x16x32_bf16 v[26:29], v[150:153], v[192:195], v[26:29]
	v_mfma_f32_16x16x32_bf16 v[14:17], v[110:113], v[200:203], v[14:17]
	v_mfma_f32_16x16x32_bf16 v[10:13], v[150:153], v[200:203], v[10:13]
	v_mfma_f32_16x16x32_bf16 v[62:65], v[146:149], v[178:181], v[62:65]
	v_mfma_f32_16x16x32_bf16 v[58:61], v[154:157], v[178:181], v[58:61]
	v_mfma_f32_16x16x32_bf16 v[46:49], v[146:149], v[186:189], v[46:49]
	v_mfma_f32_16x16x32_bf16 v[42:45], v[154:157], v[186:189], v[42:45]
	v_mfma_f32_16x16x32_bf16 v[30:33], v[146:149], v[196:199], v[30:33]
	v_mfma_f32_16x16x32_bf16 v[26:29], v[154:157], v[196:199], v[26:29]
	v_mfma_f32_16x16x32_bf16 v[14:17], v[146:149], v[204:207], v[14:17]
	v_mfma_f32_16x16x32_bf16 v[10:13], v[154:157], v[204:207], v[10:13]
	v_mfma_f32_16x16x32_bf16 v[54:57], v[158:161], v[174:177], v[54:57]
	v_mfma_f32_16x16x32_bf16 v[50:53], v[166:169], v[174:177], v[50:53]
	v_mfma_f32_16x16x32_bf16 v[38:41], v[158:161], v[182:185], v[38:41]
	v_mfma_f32_16x16x32_bf16 v[34:37], v[166:169], v[182:185], v[34:37]
	v_mfma_f32_16x16x32_bf16 v[22:25], v[158:161], v[192:195], v[22:25]
	v_mfma_f32_16x16x32_bf16 v[18:21], v[166:169], v[192:195], v[18:21]
	v_mfma_f32_16x16x32_bf16 v[6:9], v[158:161], v[200:203], v[6:9]
	v_mfma_f32_16x16x32_bf16 v[2:5], v[166:169], v[200:203], v[2:5]
	v_mfma_f32_16x16x32_bf16 v[54:57], v[162:165], v[178:181], v[54:57]
	v_mfma_f32_16x16x32_bf16 v[50:53], v[170:173], v[178:181], v[50:53]
	v_mfma_f32_16x16x32_bf16 v[38:41], v[162:165], v[186:189], v[38:41]
	v_mfma_f32_16x16x32_bf16 v[34:37], v[170:173], v[186:189], v[34:37]
	v_mfma_f32_16x16x32_bf16 v[22:25], v[162:165], v[196:199], v[22:25]
	v_mfma_f32_16x16x32_bf16 v[18:21], v[170:173], v[196:199], v[18:21]
	v_mfma_f32_16x16x32_bf16 v[6:9], v[162:165], v[204:207], v[6:9]
	v_mfma_f32_16x16x32_bf16 v[2:5], v[170:173], v[204:207], v[2:5]
	s_barrier
	v_add_u32_e32 v154, s11, v108
	v_add_u32_e32 v170, s67, v108
	ds_read_b128 v[110:113], v154
	ds_read_b128 v[146:149], v154 offset:1024
	ds_read_b128 v[150:153], v154 offset:2048
	ds_read_b128 v[154:157], v154 offset:3072
	ds_read_b128 v[158:161], v170
	ds_read_b128 v[162:165], v170 offset:1024
	ds_read_b128 v[166:169], v170 offset:2048
	ds_read_b128 v[170:173], v170 offset:3072
	s_add_u32 s90, s96, 0x40000
	s_addc_u32 s91, s97, 0
	s_mov_b32 m0, s60
	v_lshl_add_u64 v[216:217], s[90:91], 0, v[0:1]
	ds_read_b128 v[174:177], v109 offset:32768
	ds_read_b128 v[178:181], v109 offset:33792
	ds_read_b128 v[182:185], v109 offset:34816
	ds_read_b128 v[186:189], v109 offset:35840
	ds_read_b128 v[192:195], v109 offset:36864
	ds_read_b128 v[196:199], v109 offset:37888
	ds_read_b128 v[200:203], v109 offset:38912
	ds_read_b128 v[204:207], v109 offset:39936
	global_load_lds_dwordx4 v[216:217], off
	v_lshl_add_u64 v[216:217], s[90:91], 0, v[84:85]
	s_mov_b32 m0, s61
	s_nop 0
	global_load_lds_dwordx4 v[216:217], off
	s_waitcnt vmcnt(8)
	s_waitcnt lgkmcnt(0)
	s_barrier
	s_waitcnt lgkmcnt(0)
	v_mfma_f32_16x16x32_bf16 v[126:129], v[110:113], v[174:177], v[126:129]
	v_mfma_f32_16x16x32_bf16 v[118:121], v[150:153], v[174:177], v[118:121]
	v_mfma_f32_16x16x32_bf16 v[138:141], v[110:113], v[182:185], v[138:141]
	v_mfma_f32_16x16x32_bf16 v[134:137], v[150:153], v[182:185], v[134:137]
	v_mfma_f32_16x16x32_bf16 v[102:105], v[110:113], v[192:195], v[102:105]
	v_mfma_f32_16x16x32_bf16 v[98:101], v[150:153], v[192:195], v[98:101]
	v_mfma_f32_16x16x32_bf16 v[78:81], v[110:113], v[200:203], v[78:81]
	v_mfma_f32_16x16x32_bf16 v[74:77], v[150:153], v[200:203], v[74:77]
	v_mfma_f32_16x16x32_bf16 v[126:129], v[146:149], v[178:181], v[126:129]
	v_mfma_f32_16x16x32_bf16 v[118:121], v[154:157], v[178:181], v[118:121]
	v_mfma_f32_16x16x32_bf16 v[138:141], v[146:149], v[186:189], v[138:141]
	v_mfma_f32_16x16x32_bf16 v[134:137], v[154:157], v[186:189], v[134:137]
	v_mfma_f32_16x16x32_bf16 v[102:105], v[146:149], v[196:199], v[102:105]
	v_mfma_f32_16x16x32_bf16 v[98:101], v[154:157], v[196:199], v[98:101]
	v_mfma_f32_16x16x32_bf16 v[78:81], v[146:149], v[204:207], v[78:81]
	v_mfma_f32_16x16x32_bf16 v[74:77], v[154:157], v[204:207], v[74:77]
	v_mfma_f32_16x16x32_bf16 v[142:145], v[158:161], v[174:177], v[142:145]
	v_mfma_f32_16x16x32_bf16 v[114:117], v[166:169], v[174:177], v[114:117]
	v_mfma_f32_16x16x32_bf16 v[130:133], v[158:161], v[182:185], v[130:133]
	v_mfma_f32_16x16x32_bf16 v[122:125], v[166:169], v[182:185], v[122:125]
	v_mfma_f32_16x16x32_bf16 v[94:97], v[158:161], v[192:195], v[94:97]
	v_mfma_f32_16x16x32_bf16 v[90:93], v[166:169], v[192:195], v[90:93]
	v_mfma_f32_16x16x32_bf16 v[70:73], v[158:161], v[200:203], v[70:73]
	v_mfma_f32_16x16x32_bf16 v[66:69], v[166:169], v[200:203], v[66:69]
	v_mfma_f32_16x16x32_bf16 v[142:145], v[162:165], v[178:181], v[142:145]
	v_mfma_f32_16x16x32_bf16 v[114:117], v[170:173], v[178:181], v[114:117]
	v_mfma_f32_16x16x32_bf16 v[130:133], v[162:165], v[186:189], v[130:133]
	v_mfma_f32_16x16x32_bf16 v[122:125], v[170:173], v[186:189], v[122:125]
	v_mfma_f32_16x16x32_bf16 v[94:97], v[162:165], v[196:199], v[94:97]
	v_mfma_f32_16x16x32_bf16 v[90:93], v[170:173], v[196:199], v[90:93]
	v_mfma_f32_16x16x32_bf16 v[70:73], v[162:165], v[204:207], v[70:73]
	v_mfma_f32_16x16x32_bf16 v[66:69], v[170:173], v[204:207], v[66:69]
	s_barrier
	s_add_i32 s55, s11, s13
	v_lshl_add_u64 v[208:209], v[208:209], 0, s[50:51]
	s_mov_b32 m0, s55
	ds_read_b128 v[174:177], v109 offset:49152
	ds_read_b128 v[178:181], v109 offset:50176
	ds_read_b128 v[182:185], v109 offset:51200
	ds_read_b128 v[186:189], v109 offset:52224
	ds_read_b128 v[192:195], v109 offset:53248
	ds_read_b128 v[196:199], v109 offset:54272
	ds_read_b128 v[200:203], v109 offset:55296
	ds_read_b128 v[204:207], v109 offset:56320
	global_load_lds_dwordx4 v[208:209], off
	s_add_i32 m0, s55, 0x2000
	s_add_u32 s90, s94, 0x40080
	v_lshl_add_u64 v[208:209], v[210:211], 0, s[50:51]
	s_addc_u32 s91, s95, 0
	s_add_i32 s55, s67, s13
	global_load_lds_dwordx4 v[208:209], off
	v_lshl_add_u64 v[208:209], s[90:91], 0, v[82:83]
	s_mov_b32 m0, s55
	s_nop 0
	global_load_lds_dwordx4 v[208:209], off
	v_lshl_add_u64 v[208:209], s[90:91], 0, v[86:87]
	s_add_i32 m0, s55, 0x2000
	s_nop 0
	global_load_lds_dwordx4 v[208:209], off
	v_lshl_add_u64 v[208:209], v[212:213], 0, s[50:51]
	s_mov_b32 m0, s68
	s_nop 0
	global_load_lds_dwordx4 v[208:209], off
	v_lshl_add_u64 v[208:209], v[214:215], 0, s[50:51]
	s_mov_b32 m0, s69
	s_nop 0
	global_load_lds_dwordx4 v[208:209], off
	s_waitcnt vmcnt(8)
	s_waitcnt lgkmcnt(0)
	s_barrier
	s_waitcnt lgkmcnt(0)
	v_mfma_f32_16x16x32_bf16 v[62:65], v[110:113], v[174:177], v[62:65]
	v_mfma_f32_16x16x32_bf16 v[58:61], v[150:153], v[174:177], v[58:61]
	v_mfma_f32_16x16x32_bf16 v[46:49], v[110:113], v[182:185], v[46:49]
	v_mfma_f32_16x16x32_bf16 v[42:45], v[150:153], v[182:185], v[42:45]
	v_mfma_f32_16x16x32_bf16 v[30:33], v[110:113], v[192:195], v[30:33]
	v_mfma_f32_16x16x32_bf16 v[26:29], v[150:153], v[192:195], v[26:29]
	v_mfma_f32_16x16x32_bf16 v[14:17], v[110:113], v[200:203], v[14:17]
	v_mfma_f32_16x16x32_bf16 v[10:13], v[150:153], v[200:203], v[10:13]
	v_mfma_f32_16x16x32_bf16 v[62:65], v[146:149], v[178:181], v[62:65]
	v_mfma_f32_16x16x32_bf16 v[58:61], v[154:157], v[178:181], v[58:61]
	v_mfma_f32_16x16x32_bf16 v[46:49], v[146:149], v[186:189], v[46:49]
	v_mfma_f32_16x16x32_bf16 v[42:45], v[154:157], v[186:189], v[42:45]
	v_mfma_f32_16x16x32_bf16 v[30:33], v[146:149], v[196:199], v[30:33]
	v_mfma_f32_16x16x32_bf16 v[26:29], v[154:157], v[196:199], v[26:29]
	v_mfma_f32_16x16x32_bf16 v[14:17], v[146:149], v[204:207], v[14:17]
	v_mfma_f32_16x16x32_bf16 v[10:13], v[154:157], v[204:207], v[10:13]
	v_mfma_f32_16x16x32_bf16 v[54:57], v[158:161], v[174:177], v[54:57]
	v_mfma_f32_16x16x32_bf16 v[50:53], v[166:169], v[174:177], v[50:53]
	v_mfma_f32_16x16x32_bf16 v[38:41], v[158:161], v[182:185], v[38:41]
	v_mfma_f32_16x16x32_bf16 v[34:37], v[166:169], v[182:185], v[34:37]
	v_mfma_f32_16x16x32_bf16 v[22:25], v[158:161], v[192:195], v[22:25]
	v_mfma_f32_16x16x32_bf16 v[18:21], v[166:169], v[192:195], v[18:21]
	v_mfma_f32_16x16x32_bf16 v[6:9], v[158:161], v[200:203], v[6:9]
	v_mfma_f32_16x16x32_bf16 v[2:5], v[166:169], v[200:203], v[2:5]
	v_mfma_f32_16x16x32_bf16 v[54:57], v[162:165], v[178:181], v[54:57]
	v_mfma_f32_16x16x32_bf16 v[50:53], v[170:173], v[178:181], v[50:53]
	v_mfma_f32_16x16x32_bf16 v[38:41], v[162:165], v[186:189], v[38:41]
	v_mfma_f32_16x16x32_bf16 v[34:37], v[170:173], v[186:189], v[34:37]
	v_mfma_f32_16x16x32_bf16 v[22:25], v[162:165], v[196:199], v[22:25]
	v_mfma_f32_16x16x32_bf16 v[18:21], v[170:173], v[196:199], v[18:21]
	v_mfma_f32_16x16x32_bf16 v[6:9], v[162:165], v[204:207], v[6:9]
	v_mfma_f32_16x16x32_bf16 v[2:5], v[170:173], v[204:207], v[2:5]
	s_barrier
	s_add_i32 vcc_lo, vcc_lo, 2
	s_cmp_lt_u32 vcc_lo, 14
	s_mov_b64 s[90:91], s[92:93]
	s_cbranch_scc1 .LBB0_778
	s_waitcnt vmcnt(0)
	s_cmp_gt_u32 s58, 3
	s_cbranch_scc1 .LBB0_781
	s_barrier

.LBB0_875:
	s_or_b64 exec, exec, s[2:3]
	s_mov_b64 s[2:3], s[0:1]
	s_waitcnt lgkmcnt(0)
	s_barrier
	s_load_dwordx2 s[2:3], s[2:3], 0x80
	v_readlane_b32 s4, v244, 29
	s_add_u32 s46, s4, 0x700000
	v_readlane_b32 s4, v244, 30
	s_addc_u32 s56, s4, 0
	s_waitcnt lgkmcnt(0)
	s_add_u32 s57, s2, 0x7200000
	s_addc_u32 s58, s3, 0
	s_mov_b64 s[2:3], s[0:1]
	v_mov_b32_e32 v16, v220
	v_readlane_b32 s6, v245, 2
	s_load_dwordx2 s[4:5], s[2:3], 0x80
	s_lshl_b32 s59, s6, 10
	v_lshl_add_u32 v2, v16, 4, s59
	v_ashrrev_i32_e32 v0, 31, v2
	v_lshrrev_b32_e32 v0, 22, v0
	v_add_u32_e32 v0, v2, v0
	v_ashrrev_i32_e32 v10, 10, v0
	v_mul_i32_i24_e32 v0, 0x400, v10
	v_sub_u32_e32 v0, v2, v0
	v_lshrrev_b32_e32 v3, 4, v0
	v_bitop3_b32 v0, v3, v0, 32 bitop3:0x6c
	v_ashrrev_i32_e32 v4, 31, v0
	v_lshrrev_b32_e32 v4, 26, v4
	v_add_u32_e32 v4, v0, v4
	v_lshlrev_b32_e32 v3, 3, v10
	v_ashrrev_i32_e32 v11, 6, v4
	v_and_b32_e32 v4, 0xc0, v4
	v_and_b32_e32 v3, -16, v3
	v_sub_u32_e32 v0, v0, v4
	v_add_u32_e32 v3, v11, v3
	v_ashrrev_i16_sdwa v0, v230, sext(v0) dst_sel:DWORD dst_unused:UNUSED_PAD src0_sel:DWORD src1_sel:BYTE_0
	v_lshlrev_b32_e32 v5, 5, v10
	v_bfe_i32 v12, v0, 0, 16
	v_lshlrev_b32_e32 v0, 1, v3
	v_lshrrev_b32_e32 v4, 2, v3
	v_and_b32_e32 v6, 3, v11
	s_mov_b32 s2, 0x1fffe0
	v_and_b32_e32 v5, 32, v5
	v_and_b32_e32 v0, 24, v0
	v_and_b32_e32 v4, 4, v4
	v_and_or_b32 v6, v3, s2, v6
	v_or3_b32 v0, v6, v4, v0
	v_add_lshl_u32 v4, v5, v12, 1
	v_add_u32_e32 v2, 0x2000, v2
	v_lshl_add_u32 v130, v3, 11, v4
	v_ashrrev_i32_e32 v3, 31, v2
	v_lshrrev_b32_e32 v3, 22, v3
	v_add_u32_e32 v3, v2, v3
	v_ashrrev_i32_e32 v13, 10, v3
	v_mul_i32_i24_e32 v3, 0x400, v13
	v_sub_u32_e32 v2, v2, v3
	v_lshrrev_b32_e32 v3, 4, v2
	v_bitop3_b32 v2, v3, v2, 32 bitop3:0x6c
	v_lshl_add_u32 v0, v0, 11, v4
	v_ashrrev_i32_e32 v4, 31, v2
	v_lshrrev_b32_e32 v4, 26, v4
	v_add_u32_e32 v4, v2, v4
	v_ashrrev_i32_e32 v14, 6, v4
	v_and_b32_e32 v4, 0xffc0, v4
	v_lshlrev_b32_e32 v3, 3, v13
	v_sub_u32_e32 v2, v2, v4
	v_and_b32_e32 v3, -16, v3
	v_lshrrev_b16_e32 v4, 7, v2
	v_add_u32_e32 v3, v14, v3
	v_and_b32_e32 v4, 1, v4
	v_and_b32_e32 v6, 3, v14
	s_ashr_i32 s7, s6, 2
	v_add_u16_e32 v2, v2, v4
	v_and_or_b32 v6, v3, s2, v6
	v_readlane_b32 s2, v244, 0
	v_ashrrev_i16_sdwa v2, v230, sext(v2) dst_sel:DWORD dst_unused:UNUSED_PAD src0_sel:DWORD src1_sel:BYTE_0
	s_add_u32 s82, s46, s2
	v_lshlrev_b32_e32 v5, 5, v13
	v_bfe_i32 v15, v2, 0, 16
	v_lshlrev_b32_e32 v2, 1, v3
	v_lshrrev_b32_e32 v4, 2, v3
	s_addc_u32 s83, s56, 0
	s_add_i32 s60, s59, 0
	v_and_b32_e32 v5, 32, v5
	v_and_b32_e32 v2, 24, v2
	v_and_b32_e32 v4, 4, v4
	s_add_i32 m0, s60, 0x10000
	v_or3_b32 v2, v6, v4, v2
	v_add_lshl_u32 v4, v5, v15, 1
	global_load_lds_dwordx4 v0, s[82:83]
	s_add_i32 m0, s60, 0x12000
	v_lshl_add_u32 v134, v2, 11, v4
	s_add_u32 s2, s82, 0x40000
	global_load_lds_dwordx4 v134, s[82:83]
	s_addc_u32 s3, s83, 0
	s_add_i32 m0, s60, 0x14000
	v_lshl_add_u32 v132, v3, 11, v4
	global_load_lds_dwordx4 v0, s[2:3]
	s_add_i32 m0, s60, 0x16000
	v_mov_b32_e32 v135, v1
	global_load_lds_dwordx4 v134, s[2:3]
	v_readlane_b32 s2, v245, 62
	s_add_u32 s80, s57, s2
	s_addc_u32 s81, s58, 0
	s_add_i32 s61, s60, 0x2000
	s_mov_b32 m0, s60
	s_add_u32 s2, s80, 0x40000
	global_load_lds_dwordx4 v130, s[80:81]
	s_mov_b32 m0, s61
	s_addc_u32 s3, s81, 0
	s_add_i32 s68, s60, 0x4000
	global_load_lds_dwordx4 v132, s[80:81]
	s_mov_b32 m0, s68
	s_add_i32 s69, s60, 0x6000
	global_load_lds_dwordx4 v130, s[2:3]
	s_mov_b32 m0, s69
	v_mov_b32_e32 v131, v1
	global_load_lds_dwordx4 v132, s[2:3]
	v_mov_b32_e32 v133, v1
	s_cmp_eq_u32 s7, 1
	v_lshl_add_u64 v[8:9], s[82:83], 0, v[0:1]
	v_lshl_add_u64 v[6:7], s[82:83], 0, v[134:135]
	v_lshl_add_u64 v[2:3], s[80:81], 0, v[130:131]
	s_cselect_b64 s[2:3], -1, 0
	s_cmp_lg_u32 s7, 1
	v_lshl_add_u64 v[4:5], s[80:81], 0, v[132:133]
	s_cbranch_scc1 .LBB0_877
	s_setprio 1
	s_barrier

.LBB0_889:
	s_mov_b64 s[2:3], s[0:1]
	s_waitcnt vmcnt(0)
	s_barrier
	s_load_dwordx2 s[4:5], s[2:3], 0x80
	s_mov_b64 s[6:7], 0
	s_and_b64 vcc, exec, s[84:85]
	s_setprio 0
	s_getreg_b32 s8, hwreg(HW_REG_XCC_ID, 0, 4)
	s_cbranch_vccnz .LBB0_891
	v_mov_b32_e32 v0, v220
	s_nop 0
	v_cmp_eq_u32_e32 vcc, 0, v0
	s_and_b64 s[6:7], vcc, exec

.LBB0_947:
	s_mul_i32 s46, s56, 0x2c00000
	s_lshl_b64 s[12:13], s[46:47], 1
	s_waitcnt lgkmcnt(0)
	s_add_u32 s55, s90, s12
	s_addc_u32 s59, s91, s13
	s_mov_b64 s[12:13], s[0:1]
	s_load_dwordx2 s[86:87], s[12:13], 0x68
	s_mov_b64 s[12:13], s[0:1]
	v_mov_b32_e32 v209, v220
	v_readlane_b32 s58, v245, 2
	s_load_dwordx2 s[84:85], s[12:13], 0x70
	s_lshl_b32 s46, s58, 10
	v_lshlrev_b32_e32 v14, 4, v209
	v_add_u32_e32 v2, s46, v14
	v_ashrrev_i32_e32 v0, 31, v2
	v_lshrrev_b32_e32 v0, 22, v0
	v_add_u32_e32 v0, v2, v0
	v_ashrrev_i32_e32 v6, 10, v0
	v_mul_i32_i24_e32 v0, 0x400, v6
	v_sub_u32_e32 v0, v2, v0
	v_lshrrev_b32_e32 v3, 4, v0
	v_bitop3_b32 v0, v3, v0, 32 bitop3:0x6c
	v_ashrrev_i32_e32 v4, 31, v0
	v_lshrrev_b32_e32 v4, 26, v4
	v_add_u32_e32 v4, v0, v4
	v_lshlrev_b32_e32 v3, 3, v6
	v_ashrrev_i32_e32 v8, 6, v4
	v_and_b32_e32 v4, 0xc0, v4
	v_and_b32_e32 v3, -16, v3
	v_sub_u32_e32 v0, v0, v4
	v_add_u32_e32 v3, v8, v3
	v_lshlrev_b32_e32 v5, 5, v6
	v_ashrrev_i16_sdwa v0, v230, sext(v0) dst_sel:DWORD dst_unused:UNUSED_PAD src0_sel:DWORD src1_sel:BYTE_0
	v_and_b32_e32 v7, 32, v5
	v_bfe_i32 v9, v0, 0, 16
	v_lshlrev_b32_e32 v0, 1, v3
	v_lshrrev_b32_e32 v5, 2, v3
	v_and_b32_e32 v10, 3, v8
	s_mov_b32 s13, 0xffffe0
	v_and_b32_e32 v0, 24, v0
	v_and_b32_e32 v5, 4, v5
	v_and_or_b32 v10, v3, s13, v10
	v_or3_b32 v5, v10, v5, v0
	s_movk_i32 s57, 0xb00
	v_add_u32_e32 v4, v7, v9
	v_mul_lo_u32 v0, v3, s57
	v_mul_u32_u24_e32 v3, 0xb00, v5
	v_add_u32_e32 v2, 0x2000, v2
	v_add_lshl_u32 v82, v3, v4, 1
	v_ashrrev_i32_e32 v3, 31, v2
	v_lshrrev_b32_e32 v3, 22, v3
	v_add_u32_e32 v3, v2, v3
	v_ashrrev_i32_e32 v10, 10, v3
	v_mul_i32_i24_e32 v3, 0x400, v10
	v_sub_u32_e32 v2, v2, v3
	v_lshrrev_b32_e32 v3, 4, v2
	v_bitop3_b32 v2, v3, v2, 32 bitop3:0x6c
	v_add_lshl_u32 v0, v4, v0, 1
	v_ashrrev_i32_e32 v4, 31, v2
	v_lshrrev_b32_e32 v4, 26, v4
	v_add_u32_e32 v4, v2, v4
	v_ashrrev_i32_e32 v12, 6, v4
	v_and_b32_e32 v4, 0xffc0, v4
	v_sub_u32_e32 v2, v2, v4
	v_lshlrev_b32_e32 v3, 3, v10
	v_lshrrev_b16_e32 v4, 7, v2
	v_and_b32_e32 v3, -16, v3
	v_and_b32_e32 v4, 1, v4
	v_add_u32_e32 v3, v12, v3
	v_lshlrev_b32_e32 v5, 5, v10
	v_add_u16_e32 v2, v2, v4
	v_and_b32_e32 v11, 32, v5
	v_ashrrev_i16_sdwa v2, v230, sext(v2) dst_sel:DWORD dst_unused:UNUSED_PAD src0_sel:DWORD src1_sel:BYTE_0
	v_lshlrev_b32_e32 v4, 1, v3
	v_lshrrev_b32_e32 v5, 2, v3
	v_and_b32_e32 v15, 3, v12
	v_bfe_i32 v13, v2, 0, 16
	v_and_b32_e32 v4, 24, v4
	v_and_b32_e32 v5, 4, v5
	v_and_or_b32 v15, v3, s13, v15
	v_add_u32_e32 v2, v11, v13
	v_or3_b32 v4, v15, v5, v4
	v_mul_lo_u32 v3, v3, s57
	s_add_i32 s57, s46, 0
	v_add_lshl_u32 v84, v2, v3, 1
	v_mul_u32_u24_e32 v3, 0xb00, v4
	s_add_i32 m0, s57, 0x10000
	v_add_lshl_u32 v90, v3, v2, 1
	global_load_lds_dwordx4 v82, s[74:75]
	s_add_i32 m0, s57, 0x12000
	v_readlane_b32 s13, v245, 56
	global_load_lds_dwordx4 v90, s[74:75]
	s_add_i32 m0, s57, 0x14000
	s_ashr_i32 s12, s58, 2
	global_load_lds_dwordx4 v82, s[76:77]
	s_add_i32 m0, s57, 0x16000
	s_mul_i32 s13, s13, 0x160000
	s_add_u32 s13, s55, s13
	s_addc_u32 s55, s59, 0
	s_add_u32 s88, s13, 0x13200000
	s_addc_u32 s89, s55, 0
	s_add_i32 s59, s57, 0x2000
	global_load_lds_dwordx4 v90, s[76:77]
	s_mov_b32 m0, s57
	s_add_u32 s68, s13, 0x132b0000
	global_load_lds_dwordx4 v0, s[88:89]
	s_mov_b32 m0, s59
	s_addc_u32 s69, s55, 0
	s_add_i32 s60, s57, 0x4000
	global_load_lds_dwordx4 v84, s[88:89]
	s_mov_b32 m0, s60
	s_add_i32 s61, s57, 0x6000
	global_load_lds_dwordx4 v0, s[68:69]
	s_mov_b32 m0, s61
	v_mov_b32_e32 v85, v1
	global_load_lds_dwordx4 v84, s[68:69]
	v_lshl_add_u64 v[4:5], s[88:89], 0, v[0:1]
	s_cmp_lg_u32 s12, 1
	v_lshl_add_u64 v[2:3], s[88:89], 0, v[84:85]
	s_cbranch_scc1 .LBB0_949
	s_setprio 1
	s_barrier

.LBB0_950:
	v_add_u32_e32 v138, s63, v108
	v_add_u32_e32 v154, s10, v108
	s_add_u32 s92, s90, 0x100
	ds_read_b128 v[110:113], v138
	ds_read_b128 v[130:133], v138 offset:1024
	ds_read_b128 v[134:137], v138 offset:2048
	ds_read_b128 v[138:141], v138 offset:3072
	ds_read_b128 v[142:145], v154
	ds_read_b128 v[146:149], v154 offset:1024
	ds_read_b128 v[150:153], v154 offset:2048
	ds_read_b128 v[154:157], v154 offset:3072
	s_addc_u32 s93, s91, 0
	s_cmp_lg_u32 vcc_lo, 40
	s_cselect_b32 s94, s92, 0
	s_cselect_b32 s55, s93, 0
	s_add_u32 s96, s88, s94
	s_addc_u32 s97, s89, s55
	s_add_u32 s94, s74, s94
	s_addc_u32 s95, s75, s55
	v_lshl_add_u64 v[210:211], v[92:93], 0, s[90:91]
	s_add_i32 m0, s57, 0xc000
	ds_read_b128 v[158:161], v109
	ds_read_b128 v[170:173], v109 offset:1024
	ds_read_b128 v[174:177], v109 offset:2048
	ds_read_b128 v[186:189], v109 offset:3072
	ds_read_b128 v[192:195], v109 offset:4096
	ds_read_b128 v[196:199], v109 offset:5120
	ds_read_b128 v[200:203], v109 offset:6144
	ds_read_b128 v[204:207], v109 offset:7168
	global_load_lds_dwordx4 v[210:211], off
	v_lshl_add_u64 v[210:211], v[106:107], 0, s[90:91]
	s_add_i32 m0, s57, 0xe000
	s_nop 0
	global_load_lds_dwordx4 v[210:211], off
	s_waitcnt vmcnt(8)
	s_waitcnt lgkmcnt(0)
	s_barrier
	s_waitcnt lgkmcnt(0)
	v_mfma_f32_16x16x32_bf16 v[182:185], v[110:113], v[158:161], v[182:185]
	v_mfma_f32_16x16x32_bf16 v[178:181], v[134:137], v[158:161], v[178:181]
	v_mfma_f32_16x16x32_bf16 v[126:129], v[110:113], v[174:177], v[126:129]
	v_mfma_f32_16x16x32_bf16 v[122:125], v[134:137], v[174:177], v[122:125]
	v_mfma_f32_16x16x32_bf16 v[102:105], v[110:113], v[192:195], v[102:105]
	v_mfma_f32_16x16x32_bf16 v[98:101], v[134:137], v[192:195], v[98:101]
	v_mfma_f32_16x16x32_bf16 v[78:81], v[110:113], v[200:203], v[78:81]
	v_mfma_f32_16x16x32_bf16 v[74:77], v[134:137], v[200:203], v[74:77]
	v_mfma_f32_16x16x32_bf16 v[182:185], v[130:133], v[170:173], v[182:185]
	v_mfma_f32_16x16x32_bf16 v[178:181], v[138:141], v[170:173], v[178:181]
	v_mfma_f32_16x16x32_bf16 v[126:129], v[130:133], v[186:189], v[126:129]
	v_mfma_f32_16x16x32_bf16 v[122:125], v[138:141], v[186:189], v[122:125]
	v_mfma_f32_16x16x32_bf16 v[102:105], v[130:133], v[196:199], v[102:105]
	v_mfma_f32_16x16x32_bf16 v[98:101], v[138:141], v[196:199], v[98:101]
	v_mfma_f32_16x16x32_bf16 v[78:81], v[130:133], v[204:207], v[78:81]
	v_mfma_f32_16x16x32_bf16 v[74:77], v[138:141], v[204:207], v[74:77]
	v_mfma_f32_16x16x32_bf16 v[166:169], v[142:145], v[158:161], v[166:169]
	v_mfma_f32_16x16x32_bf16 v[118:121], v[142:145], v[174:177], v[118:121]
	v_mfma_f32_16x16x32_bf16 v[114:117], v[150:153], v[174:177], v[114:117]
	v_mfma_f32_16x16x32_bf16 v[94:97], v[142:145], v[192:195], v[94:97]
	v_mfma_f32_16x16x32_bf16 v[86:89], v[150:153], v[192:195], v[86:89]
	v_mfma_f32_16x16x32_bf16 v[70:73], v[142:145], v[200:203], v[70:73]
	v_mfma_f32_16x16x32_bf16 v[66:69], v[150:153], v[200:203], v[66:69]
	v_mfma_f32_16x16x32_bf16 v[166:169], v[146:149], v[170:173], v[166:169]
	v_mfma_f32_16x16x32_bf16 v[158:161], v[150:153], v[158:161], v[162:165]
	v_mfma_f32_16x16x32_bf16 v[118:121], v[146:149], v[186:189], v[118:121]
	v_mfma_f32_16x16x32_bf16 v[114:117], v[154:157], v[186:189], v[114:117]
	v_mfma_f32_16x16x32_bf16 v[94:97], v[146:149], v[196:199], v[94:97]
	v_mfma_f32_16x16x32_bf16 v[86:89], v[154:157], v[196:199], v[86:89]
	v_mfma_f32_16x16x32_bf16 v[70:73], v[146:149], v[204:207], v[70:73]
	v_mfma_f32_16x16x32_bf16 v[66:69], v[154:157], v[204:207], v[66:69]
	v_mfma_f32_16x16x32_bf16 v[158:161], v[154:157], v[170:173], v[158:161]
	s_barrier
	s_add_i32 s55, s63, s46
	v_lshl_add_u64 v[210:211], s[94:95], 0, v[82:83]
	s_mov_b32 m0, s55
	ds_read_b128 v[162:165], v109 offset:16384
	ds_read_b128 v[170:173], v109 offset:17408
	ds_read_b128 v[174:177], v109 offset:18432
	ds_read_b128 v[186:189], v109 offset:19456
	ds_read_b128 v[192:195], v109 offset:20480
	ds_read_b128 v[196:199], v109 offset:21504
	ds_read_b128 v[200:203], v109 offset:22528
	ds_read_b128 v[204:207], v109 offset:23552
	global_load_lds_dwordx4 v[210:211], off
	s_add_i32 m0, s55, 0x2000
	s_add_u32 s90, s94, 0xb0000
	v_lshl_add_u64 v[212:213], s[94:95], 0, v[90:91]
	s_addc_u32 s91, s95, 0
	s_add_i32 s55, s10, s46
	global_load_lds_dwordx4 v[212:213], off
	v_lshl_add_u64 v[214:215], s[90:91], 0, v[82:83]
	s_mov_b32 m0, s55
	v_lshl_add_u64 v[216:217], s[96:97], 0, v[84:85]
	global_load_lds_dwordx4 v[214:215], off
	v_lshl_add_u64 v[214:215], s[90:91], 0, v[90:91]
	s_add_i32 m0, s55, 0x2000
	s_nop 0
	global_load_lds_dwordx4 v[214:215], off
	v_lshl_add_u64 v[214:215], s[96:97], 0, v[0:1]
	s_mov_b32 m0, s57
	s_nop 0
	global_load_lds_dwordx4 v[214:215], off
	s_mov_b32 m0, s59
	s_nop 0
	global_load_lds_dwordx4 v[216:217], off
	s_waitcnt vmcnt(8)
	s_waitcnt lgkmcnt(0)
	s_barrier
	s_waitcnt lgkmcnt(0)
	v_mfma_f32_16x16x32_bf16 v[62:65], v[110:113], v[162:165], v[62:65]
	v_mfma_f32_16x16x32_bf16 v[58:61], v[134:137], v[162:165], v[58:61]
	v_mfma_f32_16x16x32_bf16 v[46:49], v[110:113], v[174:177], v[46:49]
	v_mfma_f32_16x16x32_bf16 v[42:45], v[134:137], v[174:177], v[42:45]
	v_mfma_f32_16x16x32_bf16 v[30:33], v[110:113], v[192:195], v[30:33]
	v_mfma_f32_16x16x32_bf16 v[26:29], v[134:137], v[192:195], v[26:29]
	v_mfma_f32_16x16x32_bf16 v[14:17], v[110:113], v[200:203], v[14:17]
	v_mfma_f32_16x16x32_bf16 v[10:13], v[134:137], v[200:203], v[10:13]
	v_mfma_f32_16x16x32_bf16 v[62:65], v[130:133], v[170:173], v[62:65]
	v_mfma_f32_16x16x32_bf16 v[58:61], v[138:141], v[170:173], v[58:61]
	v_mfma_f32_16x16x32_bf16 v[46:49], v[130:133], v[186:189], v[46:49]
	v_mfma_f32_16x16x32_bf16 v[42:45], v[138:141], v[186:189], v[42:45]
	v_mfma_f32_16x16x32_bf16 v[30:33], v[130:133], v[196:199], v[30:33]
	v_mfma_f32_16x16x32_bf16 v[26:29], v[138:141], v[196:199], v[26:29]
	v_mfma_f32_16x16x32_bf16 v[14:17], v[130:133], v[204:207], v[14:17]
	v_mfma_f32_16x16x32_bf16 v[10:13], v[138:141], v[204:207], v[10:13]
	v_mfma_f32_16x16x32_bf16 v[54:57], v[142:145], v[162:165], v[54:57]
	v_mfma_f32_16x16x32_bf16 v[50:53], v[150:153], v[162:165], v[50:53]
	v_mfma_f32_16x16x32_bf16 v[38:41], v[142:145], v[174:177], v[38:41]
	v_mfma_f32_16x16x32_bf16 v[34:37], v[150:153], v[174:177], v[34:37]
	v_mfma_f32_16x16x32_bf16 v[22:25], v[142:145], v[192:195], v[22:25]
	v_mfma_f32_16x16x32_bf16 v[18:21], v[150:153], v[192:195], v[18:21]
	v_mfma_f32_16x16x32_bf16 v[6:9], v[142:145], v[200:203], v[6:9]
	v_mfma_f32_16x16x32_bf16 v[2:5], v[150:153], v[200:203], v[2:5]
	v_mfma_f32_16x16x32_bf16 v[54:57], v[146:149], v[170:173], v[54:57]
	v_mfma_f32_16x16x32_bf16 v[50:53], v[154:157], v[170:173], v[50:53]
	v_mfma_f32_16x16x32_bf16 v[38:41], v[146:149], v[186:189], v[38:41]
	v_mfma_f32_16x16x32_bf16 v[34:37], v[154:157], v[186:189], v[34:37]
	v_mfma_f32_16x16x32_bf16 v[22:25], v[146:149], v[196:199], v[22:25]
	v_mfma_f32_16x16x32_bf16 v[18:21], v[154:157], v[196:199], v[18:21]
	v_mfma_f32_16x16x32_bf16 v[6:9], v[146:149], v[204:207], v[6:9]
	v_mfma_f32_16x16x32_bf16 v[2:5], v[154:157], v[204:207], v[2:5]
	s_barrier
	v_add_u32_e32 v138, s11, v108
	v_add_u32_e32 v154, s67, v108
	ds_read_b128 v[110:113], v138
	ds_read_b128 v[130:133], v138 offset:1024
	ds_read_b128 v[134:137], v138 offset:2048
	ds_read_b128 v[138:141], v138 offset:3072
	ds_read_b128 v[142:145], v154
	ds_read_b128 v[146:149], v154 offset:1024
	ds_read_b128 v[150:153], v154 offset:2048
	ds_read_b128 v[154:157], v154 offset:3072
	s_add_u32 s90, s96, 0xb0000
	s_addc_u32 s91, s97, 0
	s_mov_b32 m0, s60
	v_lshl_add_u64 v[218:219], s[90:91], 0, v[0:1]
	ds_read_b128 v[162:165], v109 offset:32768
	ds_read_b128 v[170:173], v109 offset:33792
	ds_read_b128 v[174:177], v109 offset:34816
	ds_read_b128 v[186:189], v109 offset:35840
	ds_read_b128 v[192:195], v109 offset:36864
	ds_read_b128 v[196:199], v109 offset:37888
	ds_read_b128 v[200:203], v109 offset:38912
	ds_read_b128 v[204:207], v109 offset:39936
	global_load_lds_dwordx4 v[218:219], off
	v_lshl_add_u64 v[218:219], s[90:91], 0, v[84:85]
	s_mov_b32 m0, s61
	s_nop 0
	global_load_lds_dwordx4 v[218:219], off
	s_waitcnt vmcnt(8)
	s_waitcnt lgkmcnt(0)
	s_barrier
	s_waitcnt lgkmcnt(0)
	v_mfma_f32_16x16x32_bf16 v[182:185], v[110:113], v[162:165], v[182:185]
	v_mfma_f32_16x16x32_bf16 v[178:181], v[134:137], v[162:165], v[178:181]
	v_mfma_f32_16x16x32_bf16 v[126:129], v[110:113], v[174:177], v[126:129]
	v_mfma_f32_16x16x32_bf16 v[122:125], v[134:137], v[174:177], v[122:125]
	v_mfma_f32_16x16x32_bf16 v[102:105], v[110:113], v[192:195], v[102:105]
	v_mfma_f32_16x16x32_bf16 v[98:101], v[134:137], v[192:195], v[98:101]
	v_mfma_f32_16x16x32_bf16 v[78:81], v[110:113], v[200:203], v[78:81]
	v_mfma_f32_16x16x32_bf16 v[74:77], v[134:137], v[200:203], v[74:77]
	v_mfma_f32_16x16x32_bf16 v[182:185], v[130:133], v[170:173], v[182:185]
	v_mfma_f32_16x16x32_bf16 v[178:181], v[138:141], v[170:173], v[178:181]
	v_mfma_f32_16x16x32_bf16 v[126:129], v[130:133], v[186:189], v[126:129]
	v_mfma_f32_16x16x32_bf16 v[122:125], v[138:141], v[186:189], v[122:125]
	v_mfma_f32_16x16x32_bf16 v[102:105], v[130:133], v[196:199], v[102:105]
	v_mfma_f32_16x16x32_bf16 v[98:101], v[138:141], v[196:199], v[98:101]
	v_mfma_f32_16x16x32_bf16 v[78:81], v[130:133], v[204:207], v[78:81]
	v_mfma_f32_16x16x32_bf16 v[74:77], v[138:141], v[204:207], v[74:77]
	v_mfma_f32_16x16x32_bf16 v[166:169], v[142:145], v[162:165], v[166:169]
	v_mfma_f32_16x16x32_bf16 v[158:161], v[150:153], v[162:165], v[158:161]
	v_mfma_f32_16x16x32_bf16 v[118:121], v[142:145], v[174:177], v[118:121]
	v_mfma_f32_16x16x32_bf16 v[114:117], v[150:153], v[174:177], v[114:117]
	v_mfma_f32_16x16x32_bf16 v[94:97], v[142:145], v[192:195], v[94:97]
	v_mfma_f32_16x16x32_bf16 v[86:89], v[150:153], v[192:195], v[86:89]
	v_mfma_f32_16x16x32_bf16 v[70:73], v[142:145], v[200:203], v[70:73]
	v_mfma_f32_16x16x32_bf16 v[66:69], v[150:153], v[200:203], v[66:69]
	v_mfma_f32_16x16x32_bf16 v[166:169], v[146:149], v[170:173], v[166:169]
	v_mfma_f32_16x16x32_bf16 v[162:165], v[154:157], v[170:173], v[158:161]
	v_mfma_f32_16x16x32_bf16 v[118:121], v[146:149], v[186:189], v[118:121]
	v_mfma_f32_16x16x32_bf16 v[114:117], v[154:157], v[186:189], v[114:117]
	v_mfma_f32_16x16x32_bf16 v[94:97], v[146:149], v[196:199], v[94:97]
	v_mfma_f32_16x16x32_bf16 v[86:89], v[154:157], v[196:199], v[86:89]
	v_mfma_f32_16x16x32_bf16 v[70:73], v[146:149], v[204:207], v[70:73]
	v_mfma_f32_16x16x32_bf16 v[66:69], v[154:157], v[204:207], v[66:69]
	s_barrier
	s_add_i32 s55, s11, s46
	v_lshl_add_u64 v[210:211], v[210:211], 0, s[50:51]
	s_mov_b32 m0, s55
	ds_read_b128 v[158:161], v109 offset:49152
	ds_read_b128 v[170:173], v109 offset:50176
	ds_read_b128 v[174:177], v109 offset:51200
	ds_read_b128 v[186:189], v109 offset:52224
	ds_read_b128 v[192:195], v109 offset:53248
	ds_read_b128 v[196:199], v109 offset:54272
	ds_read_b128 v[200:203], v109 offset:55296
	ds_read_b128 v[204:207], v109 offset:56320
	global_load_lds_dwordx4 v[210:211], off
	s_add_i32 m0, s55, 0x2000
	s_add_u32 s90, s94, 0xb0080
	v_lshl_add_u64 v[210:211], v[212:213], 0, s[50:51]
	s_addc_u32 s91, s95, 0
	s_add_i32 s55, s67, s46
	global_load_lds_dwordx4 v[210:211], off
	v_lshl_add_u64 v[210:211], s[90:91], 0, v[82:83]
	s_mov_b32 m0, s55
	s_nop 0
	global_load_lds_dwordx4 v[210:211], off
	v_lshl_add_u64 v[210:211], s[90:91], 0, v[90:91]
	s_add_i32 m0, s55, 0x2000
	s_nop 0
	global_load_lds_dwordx4 v[210:211], off
	v_lshl_add_u64 v[210:211], v[214:215], 0, s[50:51]
	s_mov_b32 m0, s68
	s_nop 0
	global_load_lds_dwordx4 v[210:211], off
	v_lshl_add_u64 v[210:211], v[216:217], 0, s[50:51]
	s_mov_b32 m0, s69
	s_nop 0
	global_load_lds_dwordx4 v[210:211], off
	s_waitcnt vmcnt(8)
	s_waitcnt lgkmcnt(0)
	s_barrier
	s_waitcnt lgkmcnt(0)
	v_mfma_f32_16x16x32_bf16 v[62:65], v[110:113], v[158:161], v[62:65]
	v_mfma_f32_16x16x32_bf16 v[58:61], v[134:137], v[158:161], v[58:61]
	v_mfma_f32_16x16x32_bf16 v[46:49], v[110:113], v[174:177], v[46:49]
	v_mfma_f32_16x16x32_bf16 v[42:45], v[134:137], v[174:177], v[42:45]
	v_mfma_f32_16x16x32_bf16 v[30:33], v[110:113], v[192:195], v[30:33]
	v_mfma_f32_16x16x32_bf16 v[26:29], v[134:137], v[192:195], v[26:29]
	v_mfma_f32_16x16x32_bf16 v[14:17], v[110:113], v[200:203], v[14:17]
	v_mfma_f32_16x16x32_bf16 v[10:13], v[134:137], v[200:203], v[10:13]
	v_mfma_f32_16x16x32_bf16 v[62:65], v[130:133], v[170:173], v[62:65]
	v_mfma_f32_16x16x32_bf16 v[58:61], v[138:141], v[170:173], v[58:61]
	v_mfma_f32_16x16x32_bf16 v[46:49], v[130:133], v[186:189], v[46:49]
	v_mfma_f32_16x16x32_bf16 v[42:45], v[138:141], v[186:189], v[42:45]
	v_mfma_f32_16x16x32_bf16 v[30:33], v[130:133], v[196:199], v[30:33]
	v_mfma_f32_16x16x32_bf16 v[26:29], v[138:141], v[196:199], v[26:29]
	v_mfma_f32_16x16x32_bf16 v[14:17], v[130:133], v[204:207], v[14:17]
	v_mfma_f32_16x16x32_bf16 v[10:13], v[138:141], v[204:207], v[10:13]
	v_mfma_f32_16x16x32_bf16 v[54:57], v[142:145], v[158:161], v[54:57]
	v_mfma_f32_16x16x32_bf16 v[50:53], v[150:153], v[158:161], v[50:53]
	v_mfma_f32_16x16x32_bf16 v[38:41], v[142:145], v[174:177], v[38:41]
	v_mfma_f32_16x16x32_bf16 v[34:37], v[150:153], v[174:177], v[34:37]
	v_mfma_f32_16x16x32_bf16 v[22:25], v[142:145], v[192:195], v[22:25]
	v_mfma_f32_16x16x32_bf16 v[18:21], v[150:153], v[192:195], v[18:21]
	v_mfma_f32_16x16x32_bf16 v[6:9], v[142:145], v[200:203], v[6:9]
	v_mfma_f32_16x16x32_bf16 v[2:5], v[150:153], v[200:203], v[2:5]
	v_mfma_f32_16x16x32_bf16 v[54:57], v[146:149], v[170:173], v[54:57]
	v_mfma_f32_16x16x32_bf16 v[50:53], v[154:157], v[170:173], v[50:53]
	v_mfma_f32_16x16x32_bf16 v[38:41], v[146:149], v[186:189], v[38:41]
	v_mfma_f32_16x16x32_bf16 v[34:37], v[154:157], v[186:189], v[34:37]
	v_mfma_f32_16x16x32_bf16 v[22:25], v[146:149], v[196:199], v[22:25]
	v_mfma_f32_16x16x32_bf16 v[18:21], v[154:157], v[196:199], v[18:21]
	v_mfma_f32_16x16x32_bf16 v[6:9], v[146:149], v[204:207], v[6:9]
	v_mfma_f32_16x16x32_bf16 v[2:5], v[154:157], v[204:207], v[2:5]
	s_barrier
	s_add_i32 vcc_lo, vcc_lo, 2
	s_cmp_lt_u32 vcc_lo, 42
	s_mov_b64 s[90:91], s[92:93]
	s_cbranch_scc1 .LBB0_950
	s_waitcnt vmcnt(0)
	s_cmp_gt_u32 s58, 3
	s_cbranch_scc1 .LBB0_953
	s_barrier

.LBB0_1057:
	s_mov_b64 s[2:3], -1
	v_writelane_b32 v244, s2, 22
	s_nop 1
	v_writelane_b32 v244, s3, 23
	s_nop 0
	v_readlane_b32 s2, v244, 27
	v_readlane_b32 s3, v244, 28
	v_readlane_b32 s76, v244, 24
	s_and_b64 vcc, exec, s[2:3]
	s_mov_b64 s[2:3], -1
	v_readlane_b32 s77, v244, 25
	s_cbranch_vccz .LBB0_156
	s_mov_b64 s[2:3], s[0:1]
	s_load_dwordx2 s[4:5], s[2:3], 0x80
	s_mov_b64 s[6:7], 0
	s_and_b64 vcc, exec, s[76:77]
	s_setprio 0
	s_getreg_b32 s8, hwreg(HW_REG_XCC_ID, 0, 4)
	s_cbranch_vccnz .LBB0_1060
	v_mov_b32_e32 v0, v220
	s_nop 0
	v_cmp_eq_u32_e32 vcc, 0, v0
	s_and_b64 s[6:7], vcc, exec
